# routing sort keys formed with one instruction each ((bits | 127) ^ c or (bits & ~127) | (127 - c)) instead of OR + subtract
# speedup vs baseline: 1.0101x; 1.0011x over previous
; #define LAS __attribute__((address_space(3)))
; #define MFMA32(a, b, c) __builtin_amdgcn_mfma_f32_32x32x16_bf16((a), (b), (c), 0, 0, 0)
; #define CE_(a, b) ce_desc(v[a], v[b])
; __device__ __forceinline__ void sort16_desc(int (&v)[16]) {
;     ...
;     CE_(0,13); CE_(1,12); CE_(2,15); CE_(3,14); CE_(4,8); CE_(5,6); CE_(7,11); CE_(9,10);
;     CE_(0,5); CE_(1,7); CE_(2,9); CE_(3,4); CE_(6,13); CE_(8,14); CE_(10,15); CE_(11,12);
;     CE_(0,1); CE_(2,3); CE_(4,5); CE_(6,8); CE_(7,9); CE_(10,11); CE_(12,13); CE_(14,15);
;     CE_(0,2); CE_(1,3); CE_(4,10); CE_(5,11); CE_(6,7); CE_(8,9); CE_(12,14); CE_(13,15);
;     CE_(1,2); CE_(3,12); CE_(4,6); CE_(5,7); CE_(8,10); CE_(9,11); CE_(13,14);
;     CE_(1,4); CE_(2,6); CE_(5,8); CE_(7,10); CE_(9,13); CE_(11,14);
;     CE_(2,4); CE_(3,6); CE_(9,12); CE_(11,13);
;     CE_(3,5); CE_(6,8); CE_(7,9); CE_(10,12);
;     CE_(3,4); CE_(5,6); CE_(7,8); CE_(9,10); CE_(11,12);
;     CE_(6,7); CE_(8,9);
;     ...
; }
; __device__ __forceinline__ void route_task(int task, int tl0, const bf16* QP  , const LAS bf16* KHL, LAS unsigned short* EL, LAS float* GL, int lane) {
;     ...
;         for (int kt = 0; kt < 4; ++kt) {
;             f32x16 X;
; #pragma unroll
;             for (int i = 0; i < 16; ++i) X[i] = 8.f;
;             const LAS bf16* khp = KHL + (half * 128 + 32 * kt + r) * 72 + 8 * hi;
; #pragma unroll
;             for (int ks = 0; ks < 4; ++ks) {
;                 const bf16x8 kh = lds8(khp + 16 * ks);
;                 X = MFMA32(kh, qa[half][ks], X);
;             }
;             int grp[16];
; #pragma unroll
;             for (int i = 0; i < 16; ++i) grp[i] = (int)((__float_as_uint(X[i]) | 127u) - (unsigned)(32 * kt + (i & 3) + 8 * (i >> 2)));
;             sort16_desc(grp);
;             if (kt == 0) {
; #pragma unroll
;                 for (int i = 0; i < 16; ++i) cur[i] = grp[i];
;             } else merge16_desc(cur, grp);
.LBB0_666:
	s_or_b64 exec, exec, s[10:11]
	s_lshl_b32 s10, s2, 4
	s_add_i32 s10, s10, s95
	s_lshl_b32 s10, s10, 12
	v_or_b32_e32 v82, s10, v88
	s_waitcnt lgkmcnt(0)
	s_barrier
	s_add_i32 s11, 0, 0x12000
	v_lshl_add_u64 v[70:71], v[82:83], 1, s[80:81]
	global_load_dwordx4 v[62:65], v[70:71], off
	global_load_dwordx4 v[54:57], v[70:71], off offset:32
	global_load_dwordx4 v[58:61], v[70:71], off offset:64
	global_load_dwordx4 v[50:53], v[70:71], off offset:96
	ds_read_b128 v[34:37], v94
	ds_read_b128 v[38:41], v94 offset:32
	s_add_i32 s10, s10, 0x8000
	s_mov_b32 s41, 0
	s_waitcnt vmcnt(3) lgkmcnt(1)
	v_mfma_f32_32x32x16_bf16 v[18:33], v[34:37], v[62:65], v[2:17]
	ds_read_b128 v[34:37], v94 offset:64
	ds_read_b128 v[66:69], v94 offset:96
	s_waitcnt vmcnt(2) lgkmcnt(2)
	v_mfma_f32_32x32x16_bf16 v[18:33], v[38:41], v[54:57], v[18:33]
	v_and_b32_e32 v38, 64, v112
	v_add_u32_e32 v122, 64, v38
	v_cmp_lt_i32_e32 vcc, v113, v122
	s_waitcnt vmcnt(1) lgkmcnt(1)
	v_mfma_f32_32x32x16_bf16 v[18:33], v[34:37], v[58:61], v[18:33]
	v_cndmask_b32_e32 v34, v112, v113, vcc
	v_lshlrev_b32_e32 v123, 2, v34
	global_load_dwordx4 v[46:49], v[70:71], off offset:128
	global_load_dwordx4 v[42:45], v[70:71], off offset:160
	global_load_dwordx4 v[38:41], v[70:71], off offset:192
	global_load_dwordx4 v[34:37], v[70:71], off offset:224
	s_waitcnt vmcnt(4) lgkmcnt(0)
	v_mfma_f32_32x32x16_bf16 v[18:33], v[66:69], v[50:53], v[18:33]
	s_nop 11
	s_movk_i32 s42, 0x7f
	s_movk_i32 s43, 0xff80
	v_bitop3_b32 v21, v21, s42, 3 bitop3:0x56
	v_bitop3_b32 v32, v32, s42, 26 bitop3:0x56
	v_bitop3_b32 v22, v22, s42, 8 bitop3:0x56
	v_bitop3_b32 v26, v26, s42, 16 bitop3:0x56
	v_bitop3_b32 v31, v31, s42, 25 bitop3:0x56
	v_bitop3_b32 v23, v23, s42, 9 bitop3:0x56
	v_bitop3_b32 v24, v24, s42, 10 bitop3:0x56
	v_bitop3_b32 v27, v27, s42, 17 bitop3:0x56
	v_bitop3_b32 v28, v28, s42, 18 bitop3:0x56
	v_bitop3_b32 v20, v20, s42, 2 bitop3:0x56
	v_bitop3_b32 v33, v33, s42, 27 bitop3:0x56
	v_bitop3_b32 v25, v25, s42, 11 bitop3:0x56
	v_bitop3_b32 v29, v29, s42, 19 bitop3:0x56
	v_bitop3_b32 v19, v19, s42, 1 bitop3:0x56
	v_bitop3_b32 v30, v30, s42, 24 bitop3:0x56
	v_or_b32_e32 v18, 0x7f, v18
	v_max_i32_e32 v66, v21, v32
	v_max_i32_e32 v67, v22, v26
	v_max_i32_e32 v68, v18, v31
	v_max_i32_e32 v69, v23, v24
	v_min_i32_e32 v70, v27, v28
	v_min_i32_e32 v71, v20, v33
	v_min_i32_e32 v72, v25, v29
	v_min_i32_e32 v73, v19, v30
	v_min_i32_e32 v23, v23, v24
	v_min_i32_e32 v18, v18, v31
	v_min_i32_e32 v22, v22, v26
	v_min_i32_e32 v21, v21, v32
	v_max_i32_e32 v19, v19, v30
	v_max_i32_e32 v24, v25, v29
	v_max_i32_e32 v20, v20, v33
	v_max_i32_e32 v25, v27, v28
	v_min_i32_e32 v26, v66, v67
	v_min_i32_e32 v27, v68, v69
	v_max_i32_e32 v28, v70, v71
	v_max_i32_e32 v29, v72, v73
	v_max_i32_e32 v30, v23, v18
	v_max_i32_e32 v31, v22, v21
	v_min_i32_e32 v32, v19, v24
	v_min_i32_e32 v33, v20, v25
	v_min_i32_e32 v18, v23, v18
	v_min_i32_e32 v21, v22, v21
	v_min_i32_e32 v22, v70, v71
	v_max_i32_e32 v23, v68, v69
	v_max_i32_e32 v19, v19, v24
	v_max_i32_e32 v20, v20, v25
	v_max_i32_e32 v24, v66, v67
	v_min_i32_e32 v25, v26, v27
	v_max_i32_e32 v67, v30, v31
	v_min_i32_e32 v30, v30, v31
	v_min_i32_e32 v31, v32, v33
	v_max_i32_e32 v26, v26, v27
	v_max_i32_e32 v27, v28, v29
	v_min_i32_e32 v66, v28, v29
	v_max_i32_e32 v68, v32, v33
	v_min_i32_e32 v75, v21, v22
	v_max_i32_e32 v21, v21, v22
	v_min_i32_e32 v22, v23, v19
	v_min_i32_e32 v28, v20, v24
	v_max_i32_e32 v33, v30, v31
	v_min_i32_e32 v69, v26, v27
	v_max_i32_e32 v29, v25, v66
	v_min_i32_e32 v32, v67, v68
	v_min_i32_e32 v77, v25, v66
	v_min_i32_e32 v25, v22, v28
	v_max_i32_e32 v80, v22, v28
	v_min_i32_e32 v22, v33, v69
	v_max_i32_e32 v125, v20, v24
	v_max_i32_e32 v129, v67, v68
	v_max_i32_e32 v24, v33, v69
	ds_read_b128 v[66:69], v95
	v_min_i32_e32 v72, v72, v73
	v_min_i32_e32 v74, v72, v18
	v_max_i32_e32 v18, v72, v18
	v_max_i32_e32 v124, v23, v19
	v_min_i32_e32 v76, v30, v31
	v_max_i32_e32 v78, v74, v75
	v_min_i32_e32 v79, v18, v21
	v_min_i32_e32 v126, v124, v125
	v_max_i32_e32 v128, v26, v27
	v_max_i32_e32 v18, v18, v21
	v_max_i32_e32 v81, v76, v77
	v_max_i32_e32 v82, v78, v79
	v_min_i32_e32 v127, v80, v126
	v_min_i32_e32 v130, v128, v129
	v_min_i32_e32 v21, v29, v32
	v_min_i32_e32 v28, v25, v18
	v_max_i32_e32 v18, v25, v18
	v_max_i32_e32 v30, v81, v82
	v_min_i32_e32 v19, v127, v130
	v_max_i32_e32 v23, v29, v32
	v_max_i32_e32 v25, v21, v22
	v_max_i32_e32 v31, v30, v28
	v_min_i32_e32 v20, v18, v19
	v_min_i32_e32 v26, v23, v24
	v_max_i32_e32 v70, v25, v31
	v_min_i32_e32 v27, v20, v26
	v_min_i32_e32 v131, v70, v27
	v_max_i32_e32 v143, v70, v27
	ds_read_b128 v[70:73], v95 offset:32
	v_min_i32_e32 v132, v25, v31
	v_min_i32_e32 v133, v21, v22
	v_min_i32_e32 v134, v30, v28
	v_max_i32_e32 v138, v18, v19
	v_max_i32_e32 v139, v23, v24
	v_max_i32_e32 v141, v20, v26
	s_waitcnt lgkmcnt(1)
	v_mfma_f32_32x32x16_bf16 v[18:33], v[66:69], v[62:65], v[2:17]
	ds_read_b128 v[66:69], v95 offset:64
	v_max_i32_e32 v135, v133, v134
	v_max_i32_e32 v136, v132, v135
	v_min_i32_e32 v76, v76, v77
	v_min_i32_e32 v77, v78, v79
	v_min_i32_e32 v132, v132, v135
	v_max_i32_e32 v127, v127, v130
	s_waitcnt lgkmcnt(1)
	v_mfma_f32_32x32x16_bf16 v[18:33], v[70:73], v[54:57], v[18:33]
	ds_read_b128 v[70:73], v95 offset:96
	v_max_i32_e32 v80, v80, v126
	v_min_i32_e32 v74, v74, v75
	v_min_i32_e32 v140, v138, v139
	v_max_i32_e32 v78, v76, v77
	v_min_i32_e32 v79, v81, v82
	v_min_i32_e32 v82, v133, v134
	s_waitcnt lgkmcnt(1)
	v_mfma_f32_32x32x16_bf16 v[18:33], v[66:69], v[58:61], v[18:33]
	v_max_i32_e32 v66, v128, v129
	v_max_i32_e32 v134, v138, v139
	v_min_i32_e32 v76, v76, v77
	v_max_i32_e32 v81, v78, v79
	v_min_i32_e32 v78, v78, v79
	v_min_i32_e32 v67, v80, v66
	v_min_i32_e32 v142, v140, v141
	s_waitcnt lgkmcnt(0)
; #define LAS __attribute__((address_space(3)))
; #define MFMA32(a, b, c) __builtin_amdgcn_mfma_f32_32x32x16_bf16((a), (b), (c), 0, 0, 0)
; #define CE_(a, b) ce_desc(v[a], v[b])
; __device__ __forceinline__ void sort16_desc(int (&v)[16]) {
;     ...
;     CE_(0,13); CE_(1,12); CE_(2,15); CE_(3,14); CE_(4,8); CE_(5,6); CE_(7,11); CE_(9,10);
;     CE_(0,5); CE_(1,7); CE_(2,9); CE_(3,4); CE_(6,13); CE_(8,14); CE_(10,15); CE_(11,12);
;     CE_(0,1); CE_(2,3); CE_(4,5); CE_(6,8); CE_(7,9); CE_(10,11); CE_(12,13); CE_(14,15);
;     CE_(0,2); CE_(1,3); CE_(4,10); CE_(5,11); CE_(6,7); CE_(8,9); CE_(12,14); CE_(13,15);
;     CE_(1,2); CE_(3,12); CE_(4,6); CE_(5,7); CE_(8,10); CE_(9,11); CE_(13,14);
;     CE_(1,4); CE_(2,6); CE_(5,8); CE_(7,10); CE_(9,13); CE_(11,14);
;     CE_(2,4); CE_(3,6); CE_(9,12); CE_(11,13);
;     CE_(3,5); CE_(6,8); CE_(7,9); CE_(10,12);
;     CE_(3,4); CE_(5,6); CE_(7,8); CE_(9,10); CE_(11,12);
;     CE_(6,7); CE_(8,9);
;     ...
; }
; __device__ __forceinline__ void merge16_desc(int (&a)[16], const int (&b)[16]) {
; #pragma unroll
;     for (int i = 0; i < 16; ++i) a[i] = a[i] > b[15 - i] ? a[i] : b[15 - i];
; #pragma unroll
;     for (int j = 8; j > 0; j >>= 1)
; #pragma unroll
;         for (int i = 0; i < 16; ++i) { const int l = i ^ j; if (l > i) ce_desc(a[i], a[l]); }
; }
; __device__ __forceinline__ void route_task(int task, int tl0, const bf16* QP  , const LAS bf16* KHL, LAS unsigned short* EL, LAS float* GL, int lane) {
;     ...
;         for (int kt = 0; kt < 4; ++kt) {
;             f32x16 X;
; #pragma unroll
;             for (int i = 0; i < 16; ++i) X[i] = 8.f;
;             const LAS bf16* khp = KHL + (half * 128 + 32 * kt + r) * 72 + 8 * hi;
; #pragma unroll
;             for (int ks = 0; ks < 4; ++ks) {
;                 const bf16x8 kh = lds8(khp + 16 * ks);
;                 X = MFMA32(kh, qa[half][ks], X);
;             }
;             int grp[16];
; #pragma unroll
;             for (int i = 0; i < 16; ++i) grp[i] = (int)((__float_as_uint(X[i]) | 127u) - (unsigned)(32 * kt + (i & 3) + 8 * (i >> 2)));
;             sort16_desc(grp);
;             if (kt == 0) {
; #pragma unroll
;                 for (int i = 0; i < 16; ++i) cur[i] = grp[i];
;             } else merge16_desc(cur, grp);
	v_mfma_f32_32x32x16_bf16 v[18:33], v[70:73], v[50:53], v[18:33]
	v_min_i32_e32 v68, v127, v67
	v_min_i32_e32 v137, v131, v136
	v_min_i32_e32 v144, v142, v143
	v_min_i32_e32 v133, v81, v82
	v_min_i32_e32 v69, v134, v68
	s_nop 6
	v_bitop3_b32 v21, v21, s42, 35 bitop3:0x56
	v_bitop3_b32 v32, v32, s42, 58 bitop3:0x56
	v_bitop3_b32 v22, v22, s42, 40 bitop3:0x56
	v_bitop3_b32 v26, v26, s42, 48 bitop3:0x56
	v_bitop3_b32 v18, v18, s42, 32 bitop3:0x56
	v_bitop3_b32 v31, v31, s42, 57 bitop3:0x56
	v_bitop3_b32 v23, v23, s42, 41 bitop3:0x56
	v_bitop3_b32 v24, v24, s42, 42 bitop3:0x56
	v_bitop3_b32 v27, v27, s42, 49 bitop3:0x56
	v_bitop3_b32 v28, v28, s42, 50 bitop3:0x56
	v_bitop3_b32 v20, v20, s42, 34 bitop3:0x56
	v_bitop3_b32 v33, v33, s42, 59 bitop3:0x56
	v_bitop3_b32 v25, v25, s42, 43 bitop3:0x56
	v_bitop3_b32 v29, v29, s42, 51 bitop3:0x56
	v_bitop3_b32 v19, v19, s42, 33 bitop3:0x56
	v_bitop3_b32 v30, v30, s42, 56 bitop3:0x56
	v_max_i32_e32 v70, v21, v32
	v_max_i32_e32 v71, v22, v26
	v_max_i32_e32 v73, v18, v31
	v_max_i32_e32 v75, v23, v24
	v_min_i32_e32 v126, v27, v28
	v_min_i32_e32 v128, v20, v33
	v_min_i32_e32 v130, v25, v29
	v_min_i32_e32 v135, v19, v30
	v_min_i32_e32 v23, v23, v24
	v_min_i32_e32 v18, v18, v31
	v_min_i32_e32 v22, v22, v26
	v_min_i32_e32 v21, v21, v32
	v_max_i32_e32 v19, v19, v30
	v_max_i32_e32 v25, v25, v29
	v_max_i32_e32 v20, v20, v33
	v_max_i32_e32 v27, v27, v28
	v_min_i32_e32 v72, v70, v71
	v_min_i32_e32 v77, v73, v75
	v_max_i32_e32 v129, v126, v128
	v_max_i32_e32 v138, v130, v135
	v_max_i32_e32 v24, v23, v18
	v_max_i32_e32 v26, v22, v21
	v_min_i32_e32 v29, v19, v25
	v_min_i32_e32 v28, v20, v27
	v_min_i32_e32 v130, v130, v135
	v_min_i32_e32 v18, v23, v18
	v_min_i32_e32 v21, v22, v21
	v_min_i32_e32 v22, v126, v128
	v_max_i32_e32 v73, v73, v75
	v_max_i32_e32 v19, v19, v25
	v_max_i32_e32 v20, v20, v27
	v_max_i32_e32 v27, v70, v71
	v_min_i32_e32 v79, v72, v77
	v_min_i32_e32 v139, v129, v138
	v_max_i32_e32 v31, v24, v26
	v_max_i32_e32 v30, v29, v28
	v_min_i32_e32 v24, v24, v26
	v_min_i32_e32 v26, v29, v28
	v_max_i32_e32 v29, v72, v77
	v_max_i32_e32 v72, v129, v138
	v_min_i32_e32 v23, v130, v18
	v_min_i32_e32 v126, v21, v22
	v_max_i32_e32 v18, v130, v18
	v_max_i32_e32 v21, v21, v22
	v_min_i32_e32 v25, v73, v19
	v_min_i32_e32 v70, v20, v27
	v_max_i32_e32 v19, v73, v19
	v_max_i32_e32 v20, v20, v27
	v_min_i32_e32 v32, v31, v30
	v_max_i32_e32 v28, v24, v26
	v_min_i32_e32 v77, v29, v72
	v_min_i32_e32 v24, v24, v26
	v_min_i32_e32 v26, v79, v139
	v_max_i32_e32 v128, v23, v126
	v_min_i32_e32 v22, v18, v21
	v_min_i32_e32 v71, v25, v70
	v_max_i32_e32 v25, v25, v70
	v_min_i32_e32 v27, v19, v20
	v_max_i32_e32 v29, v29, v72
	v_max_i32_e32 v30, v31, v30
	v_max_i32_e32 v145, v79, v139
	v_max_i32_e32 v79, v24, v26
	v_max_i32_e32 v130, v128, v22
	v_max_i32_e32 v18, v18, v21
	v_min_i32_e32 v70, v25, v27
	v_min_i32_e32 v31, v29, v30
	v_min_i32_e32 v33, v145, v32
	v_min_i32_e32 v129, v28, v77
	v_max_i32_e32 v135, v79, v130
	v_min_i32_e32 v21, v71, v18
	v_max_i32_e32 v18, v71, v18
	v_min_i32_e32 v71, v70, v31
	v_max_i32_e32 v32, v145, v32
	v_max_i32_e32 v28, v28, v77
	v_max_i32_e32 v138, v33, v129
	v_max_i32_e32 v75, v135, v21
	v_min_i32_e32 v72, v18, v71
	v_min_i32_e32 v73, v32, v28
	v_min_i32_e32 v33, v33, v129
	v_min_i32_e32 v21, v135, v21
	v_max_i32_e32 v18, v18, v71
	v_max_i32_e32 v28, v32, v28
	v_min_i32_e32 v24, v24, v26
	v_min_i32_e32 v22, v128, v22
	v_max_i32_e32 v25, v25, v27
	v_max_i32_e32 v27, v29, v30
	v_max_i32_e32 v139, v138, v75
	v_min_i32_e32 v77, v72, v73
	v_min_i32_e32 v75, v138, v75
	v_max_i32_e32 v129, v33, v21
	v_min_i32_e32 v32, v18, v28
	v_max_i32_e32 v71, v72, v73
	v_max_i32_e32 v26, v24, v22
	v_min_i32_e32 v79, v79, v130
	v_max_i32_e32 v18, v18, v28
	v_max_i32_e32 v28, v70, v31
	v_min_i32_e32 v29, v25, v27
	v_min_i32_e32 v145, v139, v77
	v_max_i32_e32 v135, v75, v129
	v_min_i32_e32 v72, v32, v71
	v_max_i32_e32 v73, v139, v77
	v_max_i32_e32 v128, v26, v79
	v_min_i32_e32 v21, v33, v21
	v_min_i32_e32 v30, v28, v29
	v_min_i32_e32 v138, v145, v135
	v_min_i32_e32 v77, v72, v73
	v_min_i32_e32 v33, v128, v21
	v_min_i32_e32 v75, v75, v129
	v_min_i32_e32 v31, v18, v30
	v_min_i32_e32 v26, v26, v79
	v_min_i32_e32 v22, v24, v22
	v_min_i32_e32 v23, v23, v126
	v_max3_i32 v23, v124, v125, v23
	v_max3_i32 v22, v80, v66, v22
	v_max3_i32 v24, v127, v67, v26
	v_max3_i32 v26, v134, v68, v33
	v_max3_i32 v21, v69, v128, v21
	v_max3_i32 v33, v140, v141, v75
	v_max3_i32 v66, v142, v143, v138
	v_max3_i32 v67, v144, v145, v135
	v_max3_i32 v68, v131, v136, v77
	v_max3_i32 v69, v137, v72, v73
	v_max3_i32 v32, v132, v32, v71
	v_max3_i32 v31, v81, v82, v31
	v_max3_i32 v18, v133, v18, v30
	v_max3_i32 v28, v78, v28, v29
	v_max3_i32 v25, v76, v25, v27
	v_max3_i32 v19, v74, v19, v20
	v_max_i32_e32 v20, v23, v68
	v_min_i32_e32 v23, v23, v68
	v_max_i32_e32 v27, v22, v69
	v_min_i32_e32 v22, v22, v69
	v_max_i32_e32 v29, v24, v32
	v_min_i32_e32 v24, v24, v32
	v_max_i32_e32 v30, v26, v31
	v_min_i32_e32 v26, v26, v31
	v_max_i32_e32 v31, v21, v18
	v_min_i32_e32 v18, v21, v18
	v_max_i32_e32 v21, v33, v28
	v_min_i32_e32 v28, v33, v28
	v_max_i32_e32 v32, v66, v25
	v_min_i32_e32 v25, v66, v25
	v_max_i32_e32 v33, v67, v19
	v_min_i32_e32 v19, v67, v19
	ds_read_b128 v[66:69], v94 offset:9216
	v_max_i32_e32 v70, v20, v31
	v_min_i32_e32 v74, v20, v31
	v_max_i32_e32 v20, v27, v21
	v_min_i32_e32 v75, v27, v21
	v_max_i32_e32 v21, v29, v32
	v_max_i32_e32 v27, v30, v33
	v_max_i32_e32 v127, v70, v21
	v_min_i32_e32 v128, v70, v21
	ds_read_b128 v[70:73], v94 offset:9248
	v_min_i32_e32 v76, v29, v32
	v_min_i32_e32 v77, v30, v33
	v_max_i32_e32 v78, v23, v18
	v_min_i32_e32 v79, v23, v18
	v_max_i32_e32 v80, v22, v28
	v_min_i32_e32 v81, v22, v28
	v_max_i32_e32 v82, v24, v25
	v_min_i32_e32 v124, v24, v25
	v_max_i32_e32 v125, v26, v19
	v_min_i32_e32 v126, v26, v19
	v_max_i32_e32 v129, v20, v27
	v_min_i32_e32 v130, v20, v27
	s_waitcnt lgkmcnt(1)
; #define LAS __attribute__((address_space(3)))
; #define MFMA32(a, b, c) __builtin_amdgcn_mfma_f32_32x32x16_bf16((a), (b), (c), 0, 0, 0)
; #define CE_(a, b) ce_desc(v[a], v[b])
; __device__ __forceinline__ void sort16_desc(int (&v)[16]) {
;     ...
;     CE_(0,13); CE_(1,12); CE_(2,15); CE_(3,14); CE_(4,8); CE_(5,6); CE_(7,11); CE_(9,10);
;     CE_(0,5); CE_(1,7); CE_(2,9); CE_(3,4); CE_(6,13); CE_(8,14); CE_(10,15); CE_(11,12);
;     CE_(0,1); CE_(2,3); CE_(4,5); CE_(6,8); CE_(7,9); CE_(10,11); CE_(12,13); CE_(14,15);
;     CE_(0,2); CE_(1,3); CE_(4,10); CE_(5,11); CE_(6,7); CE_(8,9); CE_(12,14); CE_(13,15);
;     CE_(1,2); CE_(3,12); CE_(4,6); CE_(5,7); CE_(8,10); CE_(9,11); CE_(13,14);
;     CE_(1,4); CE_(2,6); CE_(5,8); CE_(7,10); CE_(9,13); CE_(11,14);
;     CE_(2,4); CE_(3,6); CE_(9,12); CE_(11,13);
;     CE_(3,5); CE_(6,8); CE_(7,9); CE_(10,12);
;     CE_(3,4); CE_(5,6); CE_(7,8); CE_(9,10); CE_(11,12);
;     CE_(6,7); CE_(8,9);
;     ...
; }
; __device__ __forceinline__ void merge16_desc(int (&a)[16], const int (&b)[16]) {
; #pragma unroll
;     for (int i = 0; i < 16; ++i) a[i] = a[i] > b[15 - i] ? a[i] : b[15 - i];
; #pragma unroll
;     for (int j = 8; j > 0; j >>= 1)
; #pragma unroll
;         for (int i = 0; i < 16; ++i) { const int l = i ^ j; if (l > i) ce_desc(a[i], a[l]); }
; }
; __device__ __forceinline__ void route_task(int task, int tl0, const bf16* QP  , const LAS bf16* KHL, LAS unsigned short* EL, LAS float* GL, int lane) {
;     ...
;         for (int kt = 0; kt < 4; ++kt) {
;             f32x16 X;
; #pragma unroll
;             for (int i = 0; i < 16; ++i) X[i] = 8.f;
;             const LAS bf16* khp = KHL + (half * 128 + 32 * kt + r) * 72 + 8 * hi;
; #pragma unroll
;             for (int ks = 0; ks < 4; ++ks) {
;                 const bf16x8 kh = lds8(khp + 16 * ks);
;                 X = MFMA32(kh, qa[half][ks], X);
;             }
;             int grp[16];
; #pragma unroll
;             for (int i = 0; i < 16; ++i) grp[i] = (int)((__float_as_uint(X[i]) | 127u) - (unsigned)(32 * kt + (i & 3) + 8 * (i >> 2)));
;             sort16_desc(grp);
;             if (kt == 0) {
; #pragma unroll
;                 for (int i = 0; i < 16; ++i) cur[i] = grp[i];
;             } else merge16_desc(cur, grp);
	v_mfma_f32_32x32x16_bf16 v[18:33], v[66:69], v[62:65], v[2:17]
	ds_read_b128 v[66:69], v94 offset:9280
	v_max_i32_e32 v131, v74, v76
	v_min_i32_e32 v74, v74, v76
	v_max_i32_e32 v76, v75, v77
	v_min_i32_e32 v75, v75, v77
	v_max_i32_e32 v77, v78, v82
	v_min_i32_e32 v78, v78, v82
	s_waitcnt lgkmcnt(1)
	v_mfma_f32_32x32x16_bf16 v[18:33], v[70:73], v[54:57], v[18:33]
	ds_read_b128 v[70:73], v94 offset:9312
	v_max_i32_e32 v82, v80, v125
	v_min_i32_e32 v80, v80, v125
	v_max_i32_e32 v125, v79, v124
	v_min_i32_e32 v79, v79, v124
	v_max_i32_e32 v124, v81, v126
	v_min_i32_e32 v81, v81, v126
	s_waitcnt lgkmcnt(1)
	v_mfma_f32_32x32x16_bf16 v[18:33], v[66:69], v[58:61], v[18:33]
	v_min_i32_e32 v126, v127, v129
	v_min_i32_e32 v66, v128, v130
	v_min_i32_e32 v67, v131, v76
	v_min_i32_e32 v69, v77, v82
	v_min_i32_e32 v132, v78, v80
	v_min_i32_e32 v133, v125, v124
	v_min_i32_e32 v68, v74, v75
	s_waitcnt lgkmcnt(0)
	v_mfma_f32_32x32x16_bf16 v[18:33], v[70:73], v[50:53], v[18:33]
	v_min_i32_e32 v134, v79, v81
	s_nop 10
	v_and_or_b32 v21, v21, s43, 60
	v_and_or_b32 v32, v32, s43, 37
	v_and_or_b32 v22, v22, s43, 55
	v_and_or_b32 v26, v26, s43, 47
	v_bitop3_b32 v18, v18, s42, 64 bitop3:0x56
	v_and_or_b32 v31, v31, s43, 38
	v_and_or_b32 v23, v23, s43, 54
	v_and_or_b32 v24, v24, s43, 53
	v_and_or_b32 v27, v27, s43, 46
	v_and_or_b32 v28, v28, s43, 45
	v_and_or_b32 v20, v20, s43, 61
	v_and_or_b32 v33, v33, s43, 36
	v_and_or_b32 v25, v25, s43, 52
	v_and_or_b32 v29, v29, s43, 44
	v_and_or_b32 v19, v19, s43, 62
	v_and_or_b32 v30, v30, s43, 39
	v_max_i32_e32 v70, v21, v32
	v_max_i32_e32 v71, v22, v26
	v_max_i32_e32 v73, v18, v31
	v_max_i32_e32 v135, v23, v24
	v_min_i32_e32 v138, v27, v28
	v_min_i32_e32 v139, v20, v33
	v_min_i32_e32 v141, v25, v29
	v_min_i32_e32 v142, v19, v30
	v_min_i32_e32 v23, v23, v24
	v_min_i32_e32 v18, v18, v31
	v_min_i32_e32 v22, v22, v26
	v_min_i32_e32 v21, v21, v32
	v_max_i32_e32 v19, v19, v30
	v_max_i32_e32 v25, v25, v29
	v_max_i32_e32 v20, v20, v33
	v_max_i32_e32 v27, v27, v28
	v_min_i32_e32 v72, v70, v71
	v_min_i32_e32 v136, v73, v135
	v_max_i32_e32 v140, v138, v139
	v_max_i32_e32 v143, v141, v142
	v_max_i32_e32 v24, v23, v18
	v_max_i32_e32 v26, v22, v21
	v_min_i32_e32 v29, v19, v25
	v_min_i32_e32 v28, v20, v27
	v_min_i32_e32 v141, v141, v142
	v_min_i32_e32 v18, v23, v18
	v_min_i32_e32 v21, v22, v21
	v_min_i32_e32 v22, v138, v139
	v_max_i32_e32 v73, v73, v135
	v_max_i32_e32 v19, v19, v25
	v_max_i32_e32 v20, v20, v27
	v_max_i32_e32 v27, v70, v71
	v_min_i32_e32 v137, v72, v136
	v_min_i32_e32 v144, v140, v143
	v_max_i32_e32 v31, v24, v26
	v_max_i32_e32 v30, v29, v28
	v_min_i32_e32 v24, v24, v26
	v_min_i32_e32 v26, v29, v28
	v_max_i32_e32 v29, v72, v136
	v_max_i32_e32 v72, v140, v143
	v_min_i32_e32 v23, v141, v18
	v_min_i32_e32 v138, v21, v22
	v_max_i32_e32 v18, v141, v18
	v_max_i32_e32 v21, v21, v22
	v_min_i32_e32 v25, v73, v19
	v_min_i32_e32 v70, v20, v27
	v_max_i32_e32 v19, v73, v19
	v_max_i32_e32 v20, v20, v27
	v_min_i32_e32 v32, v31, v30
	v_max_i32_e32 v28, v24, v26
	v_min_i32_e32 v136, v29, v72
	v_min_i32_e32 v24, v24, v26
	v_min_i32_e32 v26, v137, v144
	v_max_i32_e32 v139, v23, v138
	v_min_i32_e32 v22, v18, v21
	v_min_i32_e32 v71, v25, v70
	v_max_i32_e32 v25, v25, v70
	v_min_i32_e32 v27, v19, v20
	v_max_i32_e32 v29, v29, v72
	v_max_i32_e32 v30, v31, v30
	v_max_i32_e32 v145, v137, v144
	v_max_i32_e32 v137, v24, v26
	v_max_i32_e32 v141, v139, v22
	v_max_i32_e32 v18, v18, v21
	v_min_i32_e32 v70, v25, v27
	v_min_i32_e32 v31, v29, v30
	v_min_i32_e32 v33, v145, v32
	v_min_i32_e32 v140, v28, v136
	v_max_i32_e32 v142, v137, v141
	v_min_i32_e32 v21, v71, v18
	v_max_i32_e32 v18, v71, v18
	v_min_i32_e32 v71, v70, v31
	v_max_i32_e32 v32, v145, v32
	v_max_i32_e32 v28, v28, v136
	v_max_i32_e32 v143, v33, v140
	v_max_i32_e32 v135, v142, v21
	v_min_i32_e32 v72, v18, v71
	v_min_i32_e32 v73, v32, v28
	v_min_i32_e32 v33, v33, v140
	v_min_i32_e32 v21, v142, v21
	v_max_i32_e32 v18, v18, v71
	v_max_i32_e32 v28, v32, v28
	v_min_i32_e32 v24, v24, v26
	v_min_i32_e32 v22, v139, v22
	v_max_i32_e32 v25, v25, v27
	v_max_i32_e32 v27, v29, v30
	v_max_i32_e32 v144, v143, v135
	v_min_i32_e32 v136, v72, v73
	v_min_i32_e32 v135, v143, v135
	v_max_i32_e32 v140, v33, v21
	v_min_i32_e32 v32, v18, v28
	v_max_i32_e32 v71, v72, v73
	v_max_i32_e32 v26, v24, v22
	v_min_i32_e32 v137, v137, v141
	v_max_i32_e32 v18, v18, v28
	v_max_i32_e32 v28, v70, v31
	v_min_i32_e32 v29, v25, v27
	v_min_i32_e32 v145, v144, v136
	v_max_i32_e32 v142, v135, v140
	v_min_i32_e32 v72, v32, v71
	v_max_i32_e32 v73, v144, v136
	v_max_i32_e32 v139, v26, v137
	v_min_i32_e32 v21, v33, v21
	v_min_i32_e32 v30, v28, v29
	v_min_i32_e32 v143, v145, v142
	v_min_i32_e32 v136, v72, v73
	v_min_i32_e32 v33, v139, v21
	v_max_i32_e32 v21, v139, v21
	v_min_i32_e32 v135, v135, v140
	v_max_i32_e32 v32, v32, v71
	v_min_i32_e32 v31, v18, v30
	v_max_i32_e32 v18, v18, v30
	v_min_i32_e32 v26, v26, v137
	v_min_i32_e32 v22, v24, v22
	v_max_i32_e32 v24, v25, v27
	v_min_i32_e32 v23, v23, v138
	v_max3_i32 v23, v127, v129, v23
	v_max_i32_e32 v22, v126, v22
	v_max3_i32 v25, v128, v130, v26
	v_max_i32_e32 v26, v66, v33
	v_max3_i32 v21, v131, v76, v21
	v_max_i32_e32 v27, v67, v135
	v_max3_i32 v30, v74, v75, v143
	v_max3_i32 v66, v77, v82, v136
	v_max3_i32 v67, v69, v72, v73
	v_max3_i32 v32, v78, v80, v32
	v_max_i32_e32 v31, v132, v31
	v_max3_i32 v18, v125, v124, v18
	v_max3_i32 v28, v133, v28, v29
	v_max3_i32 v24, v79, v81, v24
	v_max3_i32 v33, v68, v145, v142
	v_max3_i32 v19, v134, v19, v20
	v_max_i32_e32 v20, v23, v66
	v_min_i32_e32 v23, v23, v66
	v_max_i32_e32 v29, v22, v67
	v_max_i32_e32 v66, v25, v32
	v_min_i32_e32 v25, v25, v32
	v_max_i32_e32 v32, v26, v31
	v_min_i32_e32 v26, v26, v31
	v_max_i32_e32 v31, v21, v18
	v_min_i32_e32 v18, v21, v18
	v_max_i32_e32 v21, v27, v28
	v_min_i32_e32 v27, v27, v28
	v_max_i32_e32 v28, v30, v24
	v_min_i32_e32 v22, v22, v67
	v_min_i32_e32 v24, v30, v24
	v_max_i32_e32 v30, v33, v19
	v_min_i32_e32 v19, v33, v19
	v_max_i32_e32 v33, v20, v31
	v_min_i32_e32 v74, v20, v31
	v_max_i32_e32 v20, v29, v21
	v_min_i32_e32 v75, v29, v21
	v_max_i32_e32 v21, v66, v28
	v_min_i32_e32 v76, v66, v28
	ds_read_b128 v[66:69], v96
	ds_read_b128 v[70:73], v96 offset:32
	v_max_i32_e32 v28, v32, v30
	v_min_i32_e32 v77, v32, v30
	v_max_i32_e32 v78, v23, v18
	v_min_i32_e32 v79, v23, v18
	v_max_i32_e32 v80, v22, v27
	v_min_i32_e32 v81, v22, v27
	v_max_i32_e32 v82, v25, v24
	v_min_i32_e32 v124, v25, v24
	v_max_i32_e32 v125, v26, v19
	v_min_i32_e32 v126, v26, v19
	v_max_i32_e32 v127, v33, v21
	v_min_i32_e32 v128, v33, v21
	v_max_i32_e32 v129, v20, v28
	v_min_i32_e32 v130, v20, v28
	s_waitcnt lgkmcnt(1)
; #define LAS __attribute__((address_space(3)))
; #define MFMA32(a, b, c) __builtin_amdgcn_mfma_f32_32x32x16_bf16((a), (b), (c), 0, 0, 0)
; #define CE_(a, b) ce_desc(v[a], v[b])
; __device__ __forceinline__ void sort16_desc(int (&v)[16]) {
;     ...
;     CE_(0,13); CE_(1,12); CE_(2,15); CE_(3,14); CE_(4,8); CE_(5,6); CE_(7,11); CE_(9,10);
;     CE_(0,5); CE_(1,7); CE_(2,9); CE_(3,4); CE_(6,13); CE_(8,14); CE_(10,15); CE_(11,12);
;     CE_(0,1); CE_(2,3); CE_(4,5); CE_(6,8); CE_(7,9); CE_(10,11); CE_(12,13); CE_(14,15);
;     CE_(0,2); CE_(1,3); CE_(4,10); CE_(5,11); CE_(6,7); CE_(8,9); CE_(12,14); CE_(13,15);
;     CE_(1,2); CE_(3,12); CE_(4,6); CE_(5,7); CE_(8,10); CE_(9,11); CE_(13,14);
;     CE_(1,4); CE_(2,6); CE_(5,8); CE_(7,10); CE_(9,13); CE_(11,14);
;     CE_(2,4); CE_(3,6); CE_(9,12); CE_(11,13);
;     CE_(3,5); CE_(6,8); CE_(7,9); CE_(10,12);
;     CE_(3,4); CE_(5,6); CE_(7,8); CE_(9,10); CE_(11,12);
;     CE_(6,7); CE_(8,9);
;     ...
; }
; __device__ __forceinline__ void merge16_desc(int (&a)[16], const int (&b)[16]) {
; #pragma unroll
;     for (int i = 0; i < 16; ++i) a[i] = a[i] > b[15 - i] ? a[i] : b[15 - i];
; #pragma unroll
;     for (int j = 8; j > 0; j >>= 1)
; #pragma unroll
;         for (int i = 0; i < 16; ++i) { const int l = i ^ j; if (l > i) ce_desc(a[i], a[l]); }
; }
; __device__ __forceinline__ void route_task(int task, int tl0, const bf16* QP  , const LAS bf16* KHL, LAS unsigned short* EL, LAS float* GL, int lane) {
;     ...
;         for (int kt = 0; kt < 4; ++kt) {
;             f32x16 X;
; #pragma unroll
;             for (int i = 0; i < 16; ++i) X[i] = 8.f;
;             const LAS bf16* khp = KHL + (half * 128 + 32 * kt + r) * 72 + 8 * hi;
; #pragma unroll
;             for (int ks = 0; ks < 4; ++ks) {
;                 const bf16x8 kh = lds8(khp + 16 * ks);
;                 X = MFMA32(kh, qa[half][ks], X);
;             }
;             int grp[16];
; #pragma unroll
;             for (int i = 0; i < 16; ++i) grp[i] = (int)((__float_as_uint(X[i]) | 127u) - (unsigned)(32 * kt + (i & 3) + 8 * (i >> 2)));
;             sort16_desc(grp);
;             if (kt == 0) {
; #pragma unroll
;                 for (int i = 0; i < 16; ++i) cur[i] = grp[i];
;             } else merge16_desc(cur, grp);
	v_mfma_f32_32x32x16_bf16 v[18:33], v[66:69], v[62:65], v[2:17]
	ds_read_b128 v[62:65], v96 offset:64
	v_max_i32_e32 v67, v75, v77
	v_min_i32_e32 v68, v75, v77
	v_max_i32_e32 v75, v80, v125
	v_max_i32_e32 v131, v74, v76
	v_min_i32_e32 v66, v74, v76
	v_max_i32_e32 v69, v78, v82
	s_waitcnt lgkmcnt(1)
	v_mfma_f32_32x32x16_bf16 v[18:33], v[70:73], v[54:57], v[18:33]
	ds_read_b128 v[54:57], v96 offset:96
	v_min_i32_e32 v70, v80, v125
	v_max_i32_e32 v71, v79, v124
	v_min_i32_e32 v72, v79, v124
	v_min_i32_e32 v74, v78, v82
	v_max_i32_e32 v73, v81, v126
	v_min_i32_e32 v76, v81, v126
	s_waitcnt lgkmcnt(1)
	v_mfma_f32_32x32x16_bf16 v[18:33], v[62:65], v[58:61], v[18:33]
	v_min_i32_e32 v77, v127, v129
	v_min_i32_e32 v58, v128, v130
	v_min_i32_e32 v59, v131, v67
	v_min_i32_e32 v60, v66, v68
	v_min_i32_e32 v61, v69, v75
	v_min_i32_e32 v62, v74, v70
	v_min_i32_e32 v63, v71, v73
	s_waitcnt lgkmcnt(0)
	v_mfma_f32_32x32x16_bf16 v[18:33], v[54:57], v[50:53], v[18:33]
	v_min_i32_e32 v64, v72, v76
	s_nop 10
	v_and_or_b32 v25, v25, s43, 20
	v_and_or_b32 v29, v29, s43, 12
	v_and_or_b32 v19, v19, s43, 30
	v_and_or_b32 v30, v30, s43, 7
	v_and_or_b32 v23, v23, s43, 22
	v_and_or_b32 v24, v24, s43, 21
	v_and_or_b32 v18, v18, s43, 31
	v_and_or_b32 v31, v31, s43, 6
	v_and_or_b32 v22, v22, s43, 23
	v_and_or_b32 v26, v26, s43, 15
	v_and_or_b32 v21, v21, s43, 28
	v_and_or_b32 v32, v32, s43, 5
	v_and_or_b32 v27, v27, s43, 14
	v_and_or_b32 v28, v28, s43, 13
	v_and_or_b32 v20, v20, s43, 29
	v_and_or_b32 v33, v33, s43, 4
	v_min_i32_e32 v50, v25, v29
	v_min_i32_e32 v51, v19, v30
	v_min_i32_e32 v53, v23, v24
	v_min_i32_e32 v54, v18, v31
	v_min_i32_e32 v57, v22, v26
	v_min_i32_e32 v65, v21, v32
	v_min_i32_e32 v79, v27, v28
	v_min_i32_e32 v80, v20, v33
	v_max_i32_e32 v18, v18, v31
	v_max_i32_e32 v23, v23, v24
	v_max_i32_e32 v19, v19, v30
	v_max_i32_e32 v25, v25, v29
	v_max_i32_e32 v20, v20, v33
	v_max_i32_e32 v27, v27, v28
	v_max_i32_e32 v21, v21, v32
	v_max_i32_e32 v22, v22, v26
	v_max_i32_e32 v24, v18, v23
	v_max_i32_e32 v29, v19, v25
	v_max_i32_e32 v28, v20, v27
	v_max_i32_e32 v26, v21, v22
	v_min_i32_e32 v30, v24, v29
	v_min_i32_e32 v31, v28, v26
	v_min_i32_e32 v55, v53, v54
	v_min_i32_e32 v32, v30, v31
	v_max_i32_e32 v30, v30, v31
	v_min_i32_e32 v21, v21, v22
	v_min_i32_e32 v18, v18, v23
	v_max_i32_e32 v23, v79, v80
	v_max_i32_e32 v31, v50, v51
	v_max_i32_e32 v53, v53, v54
	v_max_i32_e32 v54, v57, v65
	v_min_i32_e32 v19, v19, v25
	v_min_i32_e32 v20, v20, v27
	v_min_i32_e32 v52, v50, v51
	v_min_i32_e32 v78, v57, v65
	v_min_i32_e32 v81, v79, v80
	v_max_i32_e32 v22, v21, v18
	v_max_i32_e32 v57, v53, v54
	v_max_i32_e32 v25, v19, v20
	v_min_i32_e32 v18, v21, v18
	v_min_i32_e32 v21, v23, v31
	v_min_i32_e32 v56, v52, v55
	v_min_i32_e32 v82, v78, v81
	v_max_i32_e32 v33, v52, v55
	v_max_i32_e32 v52, v78, v81
	v_max_i32_e32 v24, v24, v29
	v_max_i32_e32 v26, v28, v26
	v_max_i32_e32 v50, v23, v31
	v_max_i32_e32 v27, v57, v25
	v_max_i32_e32 v23, v18, v21
	v_min_i32_e32 v25, v57, v25
	v_min_i32_e32 v53, v53, v54
	v_min_i32_e32 v19, v19, v20
	v_max_i32_e32 v55, v33, v52
	v_min_i32_e32 v28, v24, v26
	v_max_i32_e32 v51, v22, v50
	v_max_i32_e32 v31, v23, v25
	v_max_i32_e32 v20, v53, v19
	v_min_i32_e32 v23, v23, v25
	v_min_i32_e32 v19, v53, v19
	v_min_i32_e32 v18, v18, v21
	v_max_i32_e32 v25, v56, v82
	v_min_i32_e32 v33, v33, v52
	v_min_i32_e32 v29, v30, v28
	v_min_i32_e32 v65, v51, v27
	v_min_i32_e32 v22, v22, v50
	v_max_i32_e32 v21, v19, v18
	v_max_i32_e32 v52, v25, v33
	v_max_i32_e32 v78, v32, v55
	v_min_i32_e32 v79, v29, v65
	v_max_i32_e32 v50, v20, v22
	v_min_i32_e32 v20, v20, v22
	v_max_i32_e32 v53, v21, v52
	v_min_i32_e32 v32, v32, v55
	v_max_i32_e32 v80, v78, v79
	v_max_i32_e32 v54, v31, v50
	v_min_i32_e32 v78, v78, v79
	v_min_i32_e32 v31, v31, v50
	v_max_i32_e32 v22, v23, v20
	v_max_i32_e32 v55, v53, v32
	v_min_i32_e32 v18, v19, v18
	v_min_i32_e32 v19, v25, v33
	v_min_i32_e32 v20, v23, v20
	v_min_i32_e32 v23, v53, v32
	v_max_i32_e32 v28, v30, v28
	v_max_i32_e32 v27, v51, v27
	v_min_i32_e32 v124, v56, v82
	v_min_i32_e32 v57, v80, v54
	v_max_i32_e32 v50, v78, v31
	v_max_i32_e32 v56, v22, v55
	v_min_i32_e32 v31, v78, v31
	v_max_i32_e32 v25, v18, v19
	v_min_i32_e32 v21, v21, v52
	v_min_i32_e32 v32, v20, v23
	v_max_i32_e32 v29, v29, v65
	v_min_i32_e32 v30, v28, v27
	v_min_i32_e32 v22, v22, v55
	v_max_i32_e32 v20, v20, v23
	v_min_i32_e32 v79, v57, v50
	v_max_i32_e32 v78, v56, v31
	v_max_i32_e32 v33, v25, v21
	v_max_i32_e32 v53, v80, v54
	v_min_i32_e32 v51, v29, v30
	v_min_i32_e32 v31, v56, v31
	v_max_i32_e32 v23, v22, v20
	v_min_i32_e32 v81, v79, v78
	v_max_i32_e32 v52, v33, v32
	v_max_i32_e32 v54, v53, v51
	v_min_i32_e32 v21, v25, v21
	v_max_i32_e32 v25, v57, v50
	v_min_i32_e32 v55, v31, v23
	v_max_i32_e32 v27, v28, v27
	v_min_i32_e32 v18, v18, v19
	v_min_i32_e32 v20, v22, v20
	v_min_i32_e32 v32, v33, v32
	v_min_i32_e32 v33, v53, v51
	v_max3_i32 v124, v127, v129, v124
	v_max3_i32 v69, v69, v75, v81
	v_max3_i32 v52, v131, v67, v52
	v_max3_i32 v54, v71, v73, v54
	v_max3_i32 v21, v128, v130, v21
	v_max3_i32 v25, v74, v70, v25
	v_max3_i32 v55, v66, v68, v55
	v_max3_i32 v27, v72, v76, v27
	v_max_i32_e32 v18, v77, v18
	v_max3_i32 v19, v61, v79, v78
	v_max_i32_e32 v20, v59, v20
	v_max3_i32 v22, v63, v29, v30
	v_max_i32_e32 v32, v58, v32
	v_max_i32_e32 v33, v62, v33
	v_max3_i32 v23, v60, v31, v23
	v_max3_i32 v24, v64, v24, v26
	v_min_i32_e32 v65, v52, v54
	v_min_i32_e32 v50, v21, v25
	v_min_i32_e32 v61, v18, v19
	v_min_i32_e32 v29, v20, v22
	v_min_i32_e32 v26, v23, v24
	v_max_i32_e32 v59, v124, v69
	v_max_i32_e32 v52, v52, v54
	v_max_i32_e32 v21, v21, v25
	v_max_i32_e32 v25, v55, v27
; #define LAS __attribute__((address_space(3)))
; #define MFMA32(a, b, c) __builtin_amdgcn_mfma_f32_32x32x16_bf16((a), (b), (c), 0, 0, 0)
; __device__ __forceinline__ void route_task(int task, int tl0, const bf16* QP  , const LAS bf16* KHL, LAS unsigned short* EL, LAS float* GL, int lane) {
;     ...
;         for (int kt = 0; kt < 4; ++kt) {
;             f32x16 X;
; #pragma unroll
;             for (int i = 0; i < 16; ++i) X[i] = 8.f;
;             const LAS bf16* khp = KHL + (half * 128 + 32 * kt + r) * 72 + 8 * hi;
; #pragma unroll
;             for (int ks = 0; ks < 4; ++ks) {
;                 const bf16x8 kh = lds8(khp + 16 * ks);
;                 X = MFMA32(kh, qa[half][ks], X);
;             }
;             int grp[16];
; #pragma unroll
;             for (int i = 0; i < 16; ++i) grp[i] = (int)((__float_as_uint(X[i]) | 127u) - (unsigned)(32 * kt + (i & 3) + 8 * (i >> 2)));
;             sort16_desc(grp);
;             if (kt == 0) {
; #pragma unroll
;                 for (int i = 0; i < 16; ++i) cur[i] = grp[i];
;             } else merge16_desc(cur, grp);
;         }
;         { const unsigned h4 = 4u * (unsigned)hi;
; #pragma unroll
;           for (int i = 0; i < 16; ++i) cur[i] -= (int)h4; }
;         int oth[16];
; #pragma unroll
;         for (int i = 0; i < 16; ++i) oth[i] = __shfl_xor(cur[i], 32);
;         merge16_desc(cur, oth);
; #pragma unroll
;         for (int i = 0; i < 16; ++i) top[half][i] = cur[i];
	v_max_i32_e32 v18, v18, v19
	v_max_i32_e32 v19, v20, v22
	v_max_i32_e32 v22, v32, v33
	v_max_i32_e32 v23, v23, v24
	v_min_i32_e32 v28, v55, v27
	v_max_i32_e32 v54, v59, v52
	v_max_i32_e32 v27, v21, v25
	v_max_i32_e32 v20, v18, v19
	v_max_i32_e32 v24, v22, v23
	v_min_i32_e32 v51, v32, v33
	v_max_i32_e32 v55, v54, v27
	v_max_i32_e32 v32, v20, v24
	v_min_i32_e32 v27, v54, v27
	v_min_i32_e32 v20, v20, v24
	v_max_i32_e32 v24, v27, v20
	v_min_i32_e32 v20, v27, v20
	v_min_i32_e32 v27, v59, v52
	v_min_i32_e32 v21, v21, v25
	v_min_i32_e32 v18, v18, v19
	v_min_i32_e32 v19, v22, v23
	v_min_i32_e32 v75, v124, v69
	v_max_i32_e32 v25, v27, v21
	v_max_i32_e32 v22, v18, v19
	v_min_i32_e32 v21, v27, v21
	v_min_i32_e32 v18, v18, v19
	v_min_i32_e32 v56, v50, v28
	v_min_i32_e32 v31, v51, v26
	v_max_i32_e32 v23, v25, v22
	v_min_i32_e32 v22, v25, v22
	v_max_i32_e32 v19, v21, v18
	v_min_i32_e32 v18, v21, v18
	v_max_i32_e32 v21, v75, v65
	v_max_i32_e32 v25, v50, v28
	v_max_i32_e32 v28, v61, v29
	v_max_i32_e32 v26, v51, v26
	v_min_i32_e32 v67, v75, v65
	v_min_i32_e32 v30, v61, v29
	v_max_i32_e32 v27, v21, v25
	v_min_i32_e32 v21, v21, v25
	v_min_i32_e32 v25, v28, v26
	v_min_i32_e32 v57, v67, v56
	v_min_i32_e32 v53, v30, v31
	v_max_i32_e32 v29, v28, v26
	v_max_i32_e32 v26, v21, v25
	v_min_i32_e32 v21, v21, v25
	v_max_i32_e32 v25, v67, v56
	v_max_i32_e32 v28, v30, v31
	v_min_i32_e32 v58, v57, v53
	v_max_i32_e32 v33, v55, v32
	v_min_i32_e32 v32, v55, v32
	v_max_i32_e32 v50, v27, v29
	v_min_i32_e32 v27, v27, v29
	v_max_i32_e32 v29, v25, v28
	v_min_i32_e32 v25, v25, v28
	v_max_i32_e32 v28, v57, v53
	v_sub_u32_e32 v30, v33, v87
	v_sub_u32_e32 v31, v32, v87
	v_sub_u32_e32 v24, v24, v87
	v_sub_u32_e32 v20, v20, v87
	v_sub_u32_e32 v23, v23, v87
	v_sub_u32_e32 v22, v22, v87
	v_sub_u32_e32 v19, v19, v87
	v_sub_u32_e32 v18, v18, v87
	v_sub_u32_e32 v32, v50, v87
	v_sub_u32_e32 v27, v27, v87
	v_sub_u32_e32 v26, v26, v87
	v_sub_u32_e32 v21, v21, v87
	v_sub_u32_e32 v29, v29, v87
	v_sub_u32_e32 v25, v25, v87
	v_sub_u32_e32 v28, v28, v87
	v_sub_u32_e32 v33, v58, v87
	ds_bpermute_b32 v50, v123, v30
	ds_bpermute_b32 v51, v123, v31
	ds_bpermute_b32 v52, v123, v24
	ds_bpermute_b32 v53, v123, v20
	ds_bpermute_b32 v54, v123, v23
	ds_bpermute_b32 v55, v123, v22
	ds_bpermute_b32 v56, v123, v19
	ds_bpermute_b32 v57, v123, v18
	ds_bpermute_b32 v58, v123, v32
	ds_bpermute_b32 v59, v123, v27
	ds_bpermute_b32 v60, v123, v26
	ds_bpermute_b32 v61, v123, v33
	ds_bpermute_b32 v62, v123, v28
	ds_bpermute_b32 v63, v123, v25
	ds_bpermute_b32 v64, v123, v29
	ds_bpermute_b32 v65, v123, v21
	s_waitcnt lgkmcnt(4)
	v_max_i32_e32 v30, v30, v61
	s_waitcnt lgkmcnt(3)
	v_max_i32_e32 v31, v31, v62
	s_waitcnt lgkmcnt(2)
	v_max_i32_e32 v24, v24, v63
	s_waitcnt lgkmcnt(1)
	v_max_i32_e32 v20, v20, v64
	s_waitcnt lgkmcnt(0)
	v_max_i32_e32 v23, v23, v65
	v_max_i32_e32 v22, v22, v60
	v_max_i32_e32 v19, v19, v59
	v_max_i32_e32 v18, v18, v58
	v_max_i32_e32 v32, v32, v57
	v_max_i32_e32 v27, v27, v56
	v_max_i32_e32 v26, v26, v55
	v_max_i32_e32 v21, v21, v54
	v_max_i32_e32 v29, v29, v53
	v_max_i32_e32 v25, v25, v52
	v_max_i32_e32 v28, v28, v51
	v_max_i32_e32 v33, v33, v50
	v_max_i32_e32 v50, v30, v32
	v_min_i32_e32 v30, v30, v32
	v_max_i32_e32 v32, v31, v27
	v_min_i32_e32 v27, v31, v27
	v_max_i32_e32 v31, v24, v26
	v_min_i32_e32 v24, v24, v26
	v_max_i32_e32 v26, v20, v21
	v_min_i32_e32 v20, v20, v21
	v_max_i32_e32 v21, v23, v29
	v_min_i32_e32 v23, v23, v29
	v_max_i32_e32 v29, v22, v25
	v_min_i32_e32 v22, v22, v25
	v_max_i32_e32 v25, v19, v28
	v_min_i32_e32 v19, v19, v28
	v_max_i32_e32 v28, v18, v33
	v_min_i32_e32 v18, v18, v33
	v_max_i32_e32 v33, v50, v21
	v_min_i32_e32 v21, v50, v21
	v_max_i32_e32 v50, v32, v29
	v_min_i32_e32 v29, v32, v29
	v_max_i32_e32 v32, v31, v25
	v_min_i32_e32 v25, v31, v25
	v_max_i32_e32 v31, v26, v28
	v_max_i32_e32 v64, v50, v31
	v_min_i32_e32 v67, v50, v31
	ds_read_b128 v[50:53], v94 offset:18432
	ds_read_b128 v[54:57], v94 offset:18464
	v_min_i32_e32 v26, v26, v28
	v_max_i32_e32 v28, v30, v23
	v_min_i32_e32 v58, v30, v23
	v_max_i32_e32 v23, v27, v22
	v_min_i32_e32 v59, v27, v22
	v_max_i32_e32 v22, v24, v19
	v_min_i32_e32 v60, v24, v19
	v_max_i32_e32 v19, v20, v18
	v_min_i32_e32 v61, v20, v18
	v_max_i32_e32 v62, v33, v32
	v_min_i32_e32 v66, v33, v32
	v_max_i32_e32 v68, v21, v25
	v_min_i32_e32 v69, v21, v25
	v_max_i32_e32 v70, v29, v26
	v_min_i32_e32 v71, v29, v26
	v_max_i32_e32 v72, v28, v22
	v_min_i32_e32 v73, v28, v22
	v_max_i32_e32 v74, v23, v19
	v_min_i32_e32 v75, v23, v19
	s_waitcnt vmcnt(3) lgkmcnt(1)
	v_mfma_f32_32x32x16_bf16 v[18:33], v[50:53], v[46:49], v[2:17]
	ds_read_b128 v[50:53], v94 offset:18496
	v_max_i32_e32 v76, v58, v60
	v_min_i32_e32 v77, v58, v60
	v_max_i32_e32 v78, v59, v61
	v_min_i32_e32 v79, v59, v61
	v_max_i32_e32 v63, v62, v64
	v_min_i32_e32 v65, v62, v64
	s_waitcnt vmcnt(2) lgkmcnt(1)
	v_mfma_f32_32x32x16_bf16 v[18:33], v[54:57], v[42:45], v[18:33]
	v_max_i32_e32 v64, v66, v67
	v_min_i32_e32 v62, v66, v67
	v_max_i32_e32 v61, v68, v70
	v_min_i32_e32 v60, v68, v70
	v_max_i32_e32 v59, v69, v71
	v_min_i32_e32 v57, v69, v71
	ds_read_b128 v[66:69], v94 offset:18528
	s_waitcnt vmcnt(1) lgkmcnt(1)
	v_mfma_f32_32x32x16_bf16 v[18:33], v[50:53], v[38:41], v[18:33]
	v_max_i32_e32 v55, v72, v74
	v_min_i32_e32 v58, v72, v74
	v_max_i32_e32 v56, v73, v75
	v_min_i32_e32 v54, v73, v75
	v_max_i32_e32 v53, v76, v78
	v_min_i32_e32 v52, v76, v78
	v_max_i32_e32 v51, v77, v79
	s_waitcnt vmcnt(0) lgkmcnt(0)
; #define LAS __attribute__((address_space(3)))
; #define MFMA32(a, b, c) __builtin_amdgcn_mfma_f32_32x32x16_bf16((a), (b), (c), 0, 0, 0)
; __device__ __forceinline__ void route_task(int task, int tl0, const bf16* QP  , const LAS bf16* KHL, LAS unsigned short* EL, LAS float* GL, int lane) {
;     ...
; #pragma unroll
;             for (int i = 0; i < 16; ++i) X[i] = 8.f;
;             const LAS bf16* khp = KHL + (half * 128 + 32 * kt + r) * 72 + 8 * hi;
; #pragma unroll
;             for (int ks = 0; ks < 4; ++ks) {
;                 const bf16x8 kh = lds8(khp + 16 * ks);
;                 X = MFMA32(kh, qa[half][ks], X);
;             }
;             int grp[16];
; #pragma unroll
;             for (int i = 0; i < 16; ++i) grp[i] = (int)((__float_as_uint(X[i]) | 127u) - (unsigned)(32 * kt + (i & 3) + 8 * (i >> 2)));
;             sort16_desc(grp);
;             if (kt == 0) {
; #pragma unroll
;                 for (int i = 0; i < 16; ++i) cur[i] = grp[i];
;             } else merge16_desc(cur, grp);
	v_mfma_f32_32x32x16_bf16 v[18:33], v[66:69], v[34:37], v[18:33]
	v_min_i32_e32 v50, v77, v79
	s_nop 10
	v_bitop3_b32 v21, v21, s42, 3 bitop3:0x56
	v_bitop3_b32 v32, v32, s42, 26 bitop3:0x56
	v_bitop3_b32 v22, v22, s42, 8 bitop3:0x56
	v_bitop3_b32 v26, v26, s42, 16 bitop3:0x56
	v_bitop3_b32 v31, v31, s42, 25 bitop3:0x56
	v_bitop3_b32 v23, v23, s42, 9 bitop3:0x56
	v_bitop3_b32 v24, v24, s42, 10 bitop3:0x56
	v_bitop3_b32 v27, v27, s42, 17 bitop3:0x56
	v_bitop3_b32 v28, v28, s42, 18 bitop3:0x56
	v_bitop3_b32 v20, v20, s42, 2 bitop3:0x56
	v_bitop3_b32 v33, v33, s42, 27 bitop3:0x56
	v_bitop3_b32 v25, v25, s42, 11 bitop3:0x56
	v_bitop3_b32 v29, v29, s42, 19 bitop3:0x56
	v_bitop3_b32 v19, v19, s42, 1 bitop3:0x56
	v_bitop3_b32 v30, v30, s42, 24 bitop3:0x56
	v_or_b32_e32 v18, 0x7f, v18
	v_max_i32_e32 v66, v21, v32
	v_max_i32_e32 v67, v22, v26
	v_max_i32_e32 v69, v18, v31
	v_max_i32_e32 v70, v23, v24
	v_min_i32_e32 v73, v27, v28
	v_min_i32_e32 v74, v20, v33
	v_min_i32_e32 v76, v25, v29
	v_min_i32_e32 v77, v19, v30
	v_min_i32_e32 v23, v23, v24
	v_min_i32_e32 v18, v18, v31
	v_min_i32_e32 v22, v22, v26
	v_min_i32_e32 v21, v21, v32
	v_max_i32_e32 v19, v19, v30
	v_max_i32_e32 v25, v25, v29
	v_max_i32_e32 v20, v20, v33
	v_max_i32_e32 v27, v27, v28
	v_max_i32_e32 v24, v23, v18
	v_max_i32_e32 v26, v22, v21
	v_min_i32_e32 v29, v19, v25
	v_min_i32_e32 v28, v20, v27
	v_max_i32_e32 v31, v24, v26
	v_min_i32_e32 v24, v24, v26
	v_min_i32_e32 v26, v29, v28
	v_min_i32_e32 v68, v66, v67
	v_min_i32_e32 v71, v69, v70
	v_max_i32_e32 v75, v73, v74
	v_max_i32_e32 v78, v76, v77
	v_max_i32_e32 v30, v29, v28
	v_max_i32_e32 v28, v24, v26
	v_min_i32_e32 v81, v24, v26
	v_min_i32_e32 v24, v76, v77
	v_min_i32_e32 v18, v23, v18
	v_min_i32_e32 v21, v22, v21
	v_min_i32_e32 v22, v73, v74
	v_min_i32_e32 v72, v68, v71
	v_min_i32_e32 v79, v75, v78
	v_min_i32_e32 v76, v24, v18
	v_min_i32_e32 v74, v21, v22
	v_max_i32_e32 v18, v24, v18
	v_max_i32_e32 v21, v21, v22
	v_max_i32_e32 v23, v69, v70
	v_max_i32_e32 v19, v19, v25
	v_max_i32_e32 v20, v20, v27
	v_max_i32_e32 v25, v66, v67
	v_max_i32_e32 v80, v72, v79
	v_max_i32_e32 v29, v68, v71
	v_max_i32_e32 v68, v75, v78
	v_min_i32_e32 v79, v72, v79
	v_max_i32_e32 v77, v76, v74
	v_min_i32_e32 v124, v18, v21
	v_min_i32_e32 v24, v23, v19
	v_min_i32_e32 v26, v20, v25
	v_min_i32_e32 v32, v31, v30
	v_min_i32_e32 v71, v29, v68
	v_max_i32_e32 v82, v81, v79
	v_max_i32_e32 v125, v77, v124
	v_min_i32_e32 v27, v24, v26
	v_max_i32_e32 v18, v18, v21
	v_min_i32_e32 v33, v80, v32
	v_min_i32_e32 v75, v28, v71
	v_max_i32_e32 v22, v82, v125
	v_min_i32_e32 v21, v27, v18
	v_max_i32_e32 v78, v33, v75
	v_max_i32_e32 v66, v22, v21
	v_max_i32_e32 v70, v78, v66
	v_max_i32_e32 v131, v29, v68
	v_min_i32_e32 v78, v78, v66
	ds_read_b128 v[66:69], v97
	v_max_i32_e32 v127, v23, v19
	v_max_i32_e32 v128, v20, v25
	v_max_i32_e32 v126, v24, v26
	v_min_i32_e32 v129, v127, v128
	v_max_i32_e32 v132, v31, v30
	v_min_i32_e32 v130, v126, v129
	v_min_i32_e32 v133, v131, v132
	v_max_i32_e32 v18, v27, v18
	v_min_i32_e32 v19, v130, v133
	v_max_i32_e32 v23, v80, v32
	v_max_i32_e32 v24, v28, v71
	v_min_i32_e32 v20, v18, v19
	v_min_i32_e32 v25, v23, v24
	v_min_i32_e32 v26, v20, v25
	v_min_i32_e32 v80, v70, v26
	v_max_i32_e32 v143, v70, v26
	ds_read_b128 v[70:73], v97 offset:32
	v_min_i32_e32 v75, v33, v75
	v_min_i32_e32 v134, v22, v21
	v_max_i32_e32 v138, v18, v19
	v_max_i32_e32 v139, v23, v24
	v_max_i32_e32 v141, v20, v25
	s_waitcnt lgkmcnt(1)
	v_mfma_f32_32x32x16_bf16 v[18:33], v[66:69], v[46:49], v[2:17]
	ds_read_b128 v[66:69], v97 offset:64
	v_max_i32_e32 v135, v75, v134
	v_max_i32_e32 v136, v78, v135
	v_min_i32_e32 v79, v81, v79
	v_min_i32_e32 v77, v77, v124
	v_min_i32_e32 v78, v78, v135
	v_max_i32_e32 v130, v130, v133
	s_waitcnt lgkmcnt(1)
	v_mfma_f32_32x32x16_bf16 v[18:33], v[70:73], v[42:45], v[18:33]
	ds_read_b128 v[70:73], v97 offset:96
	v_max_i32_e32 v126, v126, v129
	v_min_i32_e32 v74, v76, v74
	v_min_i32_e32 v140, v138, v139
	v_max_i32_e32 v81, v79, v77
	v_min_i32_e32 v82, v82, v125
	v_min_i32_e32 v75, v75, v134
	s_waitcnt lgkmcnt(1)
	v_mfma_f32_32x32x16_bf16 v[18:33], v[66:69], v[38:41], v[18:33]
	v_max_i32_e32 v66, v131, v132
	v_max_i32_e32 v134, v138, v139
	v_min_i32_e32 v77, v79, v77
	v_max_i32_e32 v124, v81, v82
	v_min_i32_e32 v81, v81, v82
	v_min_i32_e32 v67, v126, v66
	v_min_i32_e32 v142, v140, v141
	s_waitcnt lgkmcnt(0)
; #define LAS __attribute__((address_space(3)))
; #define MFMA32(a, b, c) __builtin_amdgcn_mfma_f32_32x32x16_bf16((a), (b), (c), 0, 0, 0)
; __device__ __forceinline__ void route_task(int task, int tl0, const bf16* QP  , const LAS bf16* KHL, LAS unsigned short* EL, LAS float* GL, int lane) {
;     ...
; #pragma unroll
;             for (int i = 0; i < 16; ++i) X[i] = 8.f;
;             const LAS bf16* khp = KHL + (half * 128 + 32 * kt + r) * 72 + 8 * hi;
; #pragma unroll
;             for (int ks = 0; ks < 4; ++ks) {
;                 const bf16x8 kh = lds8(khp + 16 * ks);
;                 X = MFMA32(kh, qa[half][ks], X);
;             }
;             int grp[16];
; #pragma unroll
;             for (int i = 0; i < 16; ++i) grp[i] = (int)((__float_as_uint(X[i]) | 127u) - (unsigned)(32 * kt + (i & 3) + 8 * (i >> 2)));
;             sort16_desc(grp);
;             if (kt == 0) {
; #pragma unroll
;                 for (int i = 0; i < 16; ++i) cur[i] = grp[i];
;             } else merge16_desc(cur, grp);
	v_mfma_f32_32x32x16_bf16 v[18:33], v[70:73], v[34:37], v[18:33]
	v_min_i32_e32 v68, v130, v67
	v_min_i32_e32 v137, v80, v136
	v_min_i32_e32 v144, v142, v143
	v_min_i32_e32 v125, v124, v75
	v_min_i32_e32 v69, v134, v68
	s_nop 6
	v_bitop3_b32 v21, v21, s42, 35 bitop3:0x56
	v_bitop3_b32 v32, v32, s42, 58 bitop3:0x56
	v_bitop3_b32 v22, v22, s42, 40 bitop3:0x56
	v_bitop3_b32 v26, v26, s42, 48 bitop3:0x56
	v_bitop3_b32 v18, v18, s42, 32 bitop3:0x56
	v_bitop3_b32 v31, v31, s42, 57 bitop3:0x56
	v_bitop3_b32 v23, v23, s42, 41 bitop3:0x56
	v_bitop3_b32 v24, v24, s42, 42 bitop3:0x56
	v_bitop3_b32 v27, v27, s42, 49 bitop3:0x56
	v_bitop3_b32 v28, v28, s42, 50 bitop3:0x56
	v_bitop3_b32 v20, v20, s42, 34 bitop3:0x56
	v_bitop3_b32 v33, v33, s42, 59 bitop3:0x56
	v_bitop3_b32 v25, v25, s42, 43 bitop3:0x56
	v_bitop3_b32 v29, v29, s42, 51 bitop3:0x56
	v_bitop3_b32 v19, v19, s42, 33 bitop3:0x56
	v_bitop3_b32 v30, v30, s42, 56 bitop3:0x56
	v_max_i32_e32 v70, v21, v32
	v_max_i32_e32 v71, v22, v26
	v_max_i32_e32 v73, v18, v31
	v_max_i32_e32 v76, v23, v24
	v_min_i32_e32 v129, v27, v28
	v_min_i32_e32 v131, v20, v33
	v_min_i32_e32 v133, v25, v29
	v_min_i32_e32 v135, v19, v30
	v_min_i32_e32 v23, v23, v24
	v_min_i32_e32 v18, v18, v31
	v_min_i32_e32 v22, v22, v26
	v_min_i32_e32 v21, v21, v32
	v_max_i32_e32 v19, v19, v30
	v_max_i32_e32 v25, v25, v29
	v_max_i32_e32 v20, v20, v33
	v_max_i32_e32 v27, v27, v28
	v_min_i32_e32 v72, v70, v71
	v_min_i32_e32 v79, v73, v76
	v_max_i32_e32 v132, v129, v131
	v_max_i32_e32 v138, v133, v135
	v_max_i32_e32 v24, v23, v18
	v_max_i32_e32 v26, v22, v21
	v_min_i32_e32 v29, v19, v25
	v_min_i32_e32 v28, v20, v27
	v_min_i32_e32 v133, v133, v135
	v_min_i32_e32 v18, v23, v18
	v_min_i32_e32 v21, v22, v21
	v_min_i32_e32 v22, v129, v131
	v_max_i32_e32 v73, v73, v76
	v_max_i32_e32 v19, v19, v25
	v_max_i32_e32 v20, v20, v27
	v_max_i32_e32 v27, v70, v71
	v_min_i32_e32 v82, v72, v79
	v_min_i32_e32 v139, v132, v138
	v_max_i32_e32 v31, v24, v26
	v_max_i32_e32 v30, v29, v28
	v_min_i32_e32 v24, v24, v26
	v_min_i32_e32 v26, v29, v28
	v_max_i32_e32 v29, v72, v79
	v_max_i32_e32 v72, v132, v138
	v_min_i32_e32 v23, v133, v18
	v_min_i32_e32 v129, v21, v22
	v_max_i32_e32 v18, v133, v18
	v_max_i32_e32 v21, v21, v22
	v_min_i32_e32 v25, v73, v19
	v_min_i32_e32 v70, v20, v27
	v_max_i32_e32 v19, v73, v19
	v_max_i32_e32 v20, v20, v27
	v_min_i32_e32 v32, v31, v30
	v_max_i32_e32 v28, v24, v26
	v_min_i32_e32 v79, v29, v72
	v_min_i32_e32 v24, v24, v26
	v_min_i32_e32 v26, v82, v139
	v_max_i32_e32 v131, v23, v129
	v_min_i32_e32 v22, v18, v21
	v_min_i32_e32 v71, v25, v70
	v_max_i32_e32 v25, v25, v70
	v_min_i32_e32 v27, v19, v20
	v_max_i32_e32 v29, v29, v72
	v_max_i32_e32 v30, v31, v30
	v_max_i32_e32 v145, v82, v139
	v_max_i32_e32 v82, v24, v26
	v_max_i32_e32 v133, v131, v22
	v_max_i32_e32 v18, v18, v21
	v_min_i32_e32 v70, v25, v27
	v_min_i32_e32 v31, v29, v30
	v_min_i32_e32 v33, v145, v32
	v_min_i32_e32 v132, v28, v79
	v_max_i32_e32 v135, v82, v133
	v_min_i32_e32 v21, v71, v18
	v_max_i32_e32 v18, v71, v18
	v_min_i32_e32 v71, v70, v31
	v_max_i32_e32 v32, v145, v32
	v_max_i32_e32 v28, v28, v79
	v_max_i32_e32 v138, v33, v132
	v_max_i32_e32 v76, v135, v21
	v_min_i32_e32 v72, v18, v71
	v_min_i32_e32 v73, v32, v28
	v_min_i32_e32 v33, v33, v132
	v_min_i32_e32 v21, v135, v21
	v_max_i32_e32 v18, v18, v71
	v_max_i32_e32 v28, v32, v28
	v_min_i32_e32 v24, v24, v26
	v_min_i32_e32 v22, v131, v22
	v_max_i32_e32 v25, v25, v27
	v_max_i32_e32 v27, v29, v30
	v_max_i32_e32 v139, v138, v76
	v_min_i32_e32 v79, v72, v73
	v_min_i32_e32 v76, v138, v76
	v_max_i32_e32 v132, v33, v21
	v_min_i32_e32 v32, v18, v28
	v_max_i32_e32 v71, v72, v73
	v_max_i32_e32 v26, v24, v22
	v_min_i32_e32 v82, v82, v133
	v_max_i32_e32 v18, v18, v28
	v_max_i32_e32 v28, v70, v31
	v_min_i32_e32 v29, v25, v27
	v_min_i32_e32 v145, v139, v79
	v_max_i32_e32 v135, v76, v132
	v_min_i32_e32 v72, v32, v71
	v_max_i32_e32 v73, v139, v79
	v_max_i32_e32 v131, v26, v82
	v_min_i32_e32 v21, v33, v21
	v_min_i32_e32 v30, v28, v29
	v_min_i32_e32 v138, v145, v135
	v_min_i32_e32 v79, v72, v73
	v_min_i32_e32 v33, v131, v21
	v_min_i32_e32 v76, v76, v132
	v_min_i32_e32 v31, v18, v30
	v_min_i32_e32 v26, v26, v82
	v_min_i32_e32 v22, v24, v22
	v_min_i32_e32 v23, v23, v129
	v_max3_i32 v23, v127, v128, v23
	v_max3_i32 v22, v126, v66, v22
	v_max3_i32 v24, v130, v67, v26
	v_max3_i32 v26, v134, v68, v33
	v_max3_i32 v21, v69, v131, v21
	v_max3_i32 v33, v140, v141, v76
	v_max3_i32 v66, v142, v143, v138
	v_max3_i32 v67, v144, v145, v135
	v_max3_i32 v68, v80, v136, v79
	v_max3_i32 v69, v137, v72, v73
	v_max3_i32 v32, v78, v32, v71
	v_max3_i32 v31, v124, v75, v31
	v_max3_i32 v18, v125, v18, v30
	v_max3_i32 v28, v81, v28, v29
	v_max3_i32 v25, v77, v25, v27
	v_max3_i32 v19, v74, v19, v20
	v_max_i32_e32 v20, v23, v68
	v_min_i32_e32 v23, v23, v68
	v_max_i32_e32 v27, v22, v69
	v_min_i32_e32 v22, v22, v69
	v_max_i32_e32 v29, v24, v32
	v_min_i32_e32 v24, v24, v32
	v_max_i32_e32 v30, v26, v31
	v_min_i32_e32 v26, v26, v31
	v_max_i32_e32 v31, v21, v18
	v_min_i32_e32 v18, v21, v18
	v_max_i32_e32 v21, v33, v28
	v_min_i32_e32 v28, v33, v28
	v_max_i32_e32 v32, v66, v25
	v_min_i32_e32 v25, v66, v25
	v_max_i32_e32 v33, v67, v19
	v_min_i32_e32 v19, v67, v19
	ds_read_b128 v[66:69], v94 offset:27648
	v_max_i32_e32 v70, v20, v31
	v_min_i32_e32 v74, v20, v31
	v_max_i32_e32 v20, v27, v21
	v_min_i32_e32 v75, v27, v21
	v_max_i32_e32 v21, v29, v32
	v_max_i32_e32 v27, v30, v33
	v_max_i32_e32 v127, v70, v21
	v_min_i32_e32 v128, v70, v21
	ds_read_b128 v[70:73], v94 offset:27680
	v_min_i32_e32 v76, v29, v32
	v_min_i32_e32 v77, v30, v33
	v_max_i32_e32 v78, v23, v18
	v_min_i32_e32 v79, v23, v18
	v_max_i32_e32 v80, v22, v28
	v_min_i32_e32 v81, v22, v28
	v_max_i32_e32 v82, v24, v25
	v_min_i32_e32 v124, v24, v25
	v_max_i32_e32 v125, v26, v19
	v_min_i32_e32 v126, v26, v19
	v_max_i32_e32 v129, v20, v27
	v_min_i32_e32 v130, v20, v27
	s_waitcnt lgkmcnt(1)
; #define LAS __attribute__((address_space(3)))
; #define MFMA32(a, b, c) __builtin_amdgcn_mfma_f32_32x32x16_bf16((a), (b), (c), 0, 0, 0)
; __device__ __forceinline__ void route_task(int task, int tl0, const bf16* QP  , const LAS bf16* KHL, LAS unsigned short* EL, LAS float* GL, int lane) {
;     ...
; #pragma unroll
;             for (int i = 0; i < 16; ++i) X[i] = 8.f;
;             const LAS bf16* khp = KHL + (half * 128 + 32 * kt + r) * 72 + 8 * hi;
; #pragma unroll
;             for (int ks = 0; ks < 4; ++ks) {
;                 const bf16x8 kh = lds8(khp + 16 * ks);
;                 X = MFMA32(kh, qa[half][ks], X);
;             }
;             int grp[16];
; #pragma unroll
;             for (int i = 0; i < 16; ++i) grp[i] = (int)((__float_as_uint(X[i]) | 127u) - (unsigned)(32 * kt + (i & 3) + 8 * (i >> 2)));
;             sort16_desc(grp);
;             if (kt == 0) {
; #pragma unroll
;                 for (int i = 0; i < 16; ++i) cur[i] = grp[i];
;             } else merge16_desc(cur, grp);
	v_mfma_f32_32x32x16_bf16 v[18:33], v[66:69], v[46:49], v[2:17]
	ds_read_b128 v[66:69], v94 offset:27712
	v_max_i32_e32 v131, v74, v76
	v_min_i32_e32 v74, v74, v76
	v_max_i32_e32 v76, v75, v77
	v_min_i32_e32 v75, v75, v77
	v_max_i32_e32 v77, v78, v82
	v_min_i32_e32 v78, v78, v82
	s_waitcnt lgkmcnt(1)
	v_mfma_f32_32x32x16_bf16 v[18:33], v[70:73], v[42:45], v[18:33]
	ds_read_b128 v[70:73], v94 offset:27744
	v_max_i32_e32 v82, v80, v125
	v_min_i32_e32 v80, v80, v125
	v_max_i32_e32 v125, v79, v124
	v_min_i32_e32 v79, v79, v124
	v_max_i32_e32 v124, v81, v126
	v_min_i32_e32 v81, v81, v126
	s_waitcnt lgkmcnt(1)
	v_mfma_f32_32x32x16_bf16 v[18:33], v[66:69], v[38:41], v[18:33]
	v_min_i32_e32 v126, v127, v129
	v_min_i32_e32 v66, v128, v130
	v_min_i32_e32 v67, v131, v76
	v_min_i32_e32 v69, v77, v82
	v_min_i32_e32 v132, v78, v80
	v_min_i32_e32 v133, v125, v124
	v_min_i32_e32 v68, v74, v75
	s_waitcnt lgkmcnt(0)
	v_mfma_f32_32x32x16_bf16 v[18:33], v[70:73], v[34:37], v[18:33]
	v_min_i32_e32 v134, v79, v81
	s_nop 10
	v_and_or_b32 v21, v21, s43, 60
	v_and_or_b32 v32, v32, s43, 37
	v_and_or_b32 v22, v22, s43, 55
	v_and_or_b32 v26, v26, s43, 47
	v_bitop3_b32 v18, v18, s42, 64 bitop3:0x56
	v_and_or_b32 v31, v31, s43, 38
	v_and_or_b32 v23, v23, s43, 54
	v_and_or_b32 v24, v24, s43, 53
	v_and_or_b32 v27, v27, s43, 46
	v_and_or_b32 v28, v28, s43, 45
	v_and_or_b32 v20, v20, s43, 61
	v_and_or_b32 v33, v33, s43, 36
	v_and_or_b32 v25, v25, s43, 52
	v_and_or_b32 v29, v29, s43, 44
	v_and_or_b32 v19, v19, s43, 62
	v_and_or_b32 v30, v30, s43, 39
	v_max_i32_e32 v70, v21, v32
	v_max_i32_e32 v71, v22, v26
	v_max_i32_e32 v73, v18, v31
	v_max_i32_e32 v135, v23, v24
	v_min_i32_e32 v138, v27, v28
	v_min_i32_e32 v139, v20, v33
	v_min_i32_e32 v141, v25, v29
	v_min_i32_e32 v142, v19, v30
	v_min_i32_e32 v23, v23, v24
	v_min_i32_e32 v18, v18, v31
	v_min_i32_e32 v22, v22, v26
	v_min_i32_e32 v21, v21, v32
	v_max_i32_e32 v19, v19, v30
	v_max_i32_e32 v25, v25, v29
	v_max_i32_e32 v20, v20, v33
	v_max_i32_e32 v27, v27, v28
	v_min_i32_e32 v72, v70, v71
	v_min_i32_e32 v136, v73, v135
	v_max_i32_e32 v140, v138, v139
	v_max_i32_e32 v143, v141, v142
	v_max_i32_e32 v24, v23, v18
	v_max_i32_e32 v26, v22, v21
	v_min_i32_e32 v29, v19, v25
	v_min_i32_e32 v28, v20, v27
	v_min_i32_e32 v141, v141, v142
	v_min_i32_e32 v18, v23, v18
	v_min_i32_e32 v21, v22, v21
	v_min_i32_e32 v22, v138, v139
	v_max_i32_e32 v73, v73, v135
	v_max_i32_e32 v19, v19, v25
	v_max_i32_e32 v20, v20, v27
	v_max_i32_e32 v27, v70, v71
	v_min_i32_e32 v137, v72, v136
	v_min_i32_e32 v144, v140, v143
	v_max_i32_e32 v31, v24, v26
	v_max_i32_e32 v30, v29, v28
	v_min_i32_e32 v24, v24, v26
	v_min_i32_e32 v26, v29, v28
	v_max_i32_e32 v29, v72, v136
	v_max_i32_e32 v72, v140, v143
	v_min_i32_e32 v23, v141, v18
	v_min_i32_e32 v138, v21, v22
	v_max_i32_e32 v18, v141, v18
	v_max_i32_e32 v21, v21, v22
	v_min_i32_e32 v25, v73, v19
	v_min_i32_e32 v70, v20, v27
	v_max_i32_e32 v19, v73, v19
	v_max_i32_e32 v20, v20, v27
	v_min_i32_e32 v32, v31, v30
	v_max_i32_e32 v28, v24, v26
	v_min_i32_e32 v136, v29, v72
	v_min_i32_e32 v24, v24, v26
	v_min_i32_e32 v26, v137, v144
	v_max_i32_e32 v139, v23, v138
	v_min_i32_e32 v22, v18, v21
	v_min_i32_e32 v71, v25, v70
	v_max_i32_e32 v25, v25, v70
	v_min_i32_e32 v27, v19, v20
	v_max_i32_e32 v29, v29, v72
	v_max_i32_e32 v30, v31, v30
	v_max_i32_e32 v145, v137, v144
	v_max_i32_e32 v137, v24, v26
	v_max_i32_e32 v141, v139, v22
	v_max_i32_e32 v18, v18, v21
	v_min_i32_e32 v70, v25, v27
	v_min_i32_e32 v31, v29, v30
	v_min_i32_e32 v33, v145, v32
	v_min_i32_e32 v140, v28, v136
	v_max_i32_e32 v142, v137, v141
	v_min_i32_e32 v21, v71, v18
	v_max_i32_e32 v18, v71, v18
	v_min_i32_e32 v71, v70, v31
	v_max_i32_e32 v32, v145, v32
	v_max_i32_e32 v28, v28, v136
	v_max_i32_e32 v143, v33, v140
	v_max_i32_e32 v135, v142, v21
	v_min_i32_e32 v72, v18, v71
	v_min_i32_e32 v73, v32, v28
	v_min_i32_e32 v33, v33, v140
	v_min_i32_e32 v21, v142, v21
	v_max_i32_e32 v18, v18, v71
	v_max_i32_e32 v28, v32, v28
	v_min_i32_e32 v24, v24, v26
	v_min_i32_e32 v22, v139, v22
	v_max_i32_e32 v25, v25, v27
	v_max_i32_e32 v27, v29, v30
	v_max_i32_e32 v144, v143, v135
	v_min_i32_e32 v136, v72, v73
	v_min_i32_e32 v135, v143, v135
	v_max_i32_e32 v140, v33, v21
	v_min_i32_e32 v32, v18, v28
	v_max_i32_e32 v71, v72, v73
	v_max_i32_e32 v26, v24, v22
	v_min_i32_e32 v137, v137, v141
	v_max_i32_e32 v18, v18, v28
	v_max_i32_e32 v28, v70, v31
	v_min_i32_e32 v29, v25, v27
	v_min_i32_e32 v145, v144, v136
	v_max_i32_e32 v142, v135, v140
	v_min_i32_e32 v72, v32, v71
	v_max_i32_e32 v73, v144, v136
	v_max_i32_e32 v139, v26, v137
	v_min_i32_e32 v21, v33, v21
	v_min_i32_e32 v30, v28, v29
	v_min_i32_e32 v143, v145, v142
	v_min_i32_e32 v136, v72, v73
	v_min_i32_e32 v33, v139, v21
	v_max_i32_e32 v21, v139, v21
	v_min_i32_e32 v135, v135, v140
	v_max_i32_e32 v32, v32, v71
	v_min_i32_e32 v31, v18, v30
	v_max_i32_e32 v18, v18, v30
	v_min_i32_e32 v26, v26, v137
	v_min_i32_e32 v22, v24, v22
	v_max_i32_e32 v24, v25, v27
	v_min_i32_e32 v23, v23, v138
	v_max3_i32 v23, v127, v129, v23
	v_max_i32_e32 v22, v126, v22
	v_max3_i32 v25, v128, v130, v26
	v_max_i32_e32 v26, v66, v33
	v_max3_i32 v21, v131, v76, v21
	v_max_i32_e32 v27, v67, v135
	v_max3_i32 v30, v74, v75, v143
	v_max3_i32 v66, v77, v82, v136
	v_max3_i32 v67, v69, v72, v73
	v_max3_i32 v32, v78, v80, v32
	v_max_i32_e32 v31, v132, v31
	v_max3_i32 v18, v125, v124, v18
	v_max3_i32 v28, v133, v28, v29
	v_max3_i32 v24, v79, v81, v24
	v_max3_i32 v33, v68, v145, v142
	v_max3_i32 v19, v134, v19, v20
	v_max_i32_e32 v20, v23, v66
	v_min_i32_e32 v23, v23, v66
	v_max_i32_e32 v29, v22, v67
	v_max_i32_e32 v66, v25, v32
	v_min_i32_e32 v25, v25, v32
	v_max_i32_e32 v32, v26, v31
	v_min_i32_e32 v26, v26, v31
	v_max_i32_e32 v31, v21, v18
	v_min_i32_e32 v18, v21, v18
	v_max_i32_e32 v21, v27, v28
	v_min_i32_e32 v27, v27, v28
	v_max_i32_e32 v28, v30, v24
	v_min_i32_e32 v22, v22, v67
	v_min_i32_e32 v24, v30, v24
	v_max_i32_e32 v30, v33, v19
	v_min_i32_e32 v19, v33, v19
	v_max_i32_e32 v33, v20, v31
	v_min_i32_e32 v74, v20, v31
	v_max_i32_e32 v20, v29, v21
	v_min_i32_e32 v75, v29, v21
	v_max_i32_e32 v21, v66, v28
	v_min_i32_e32 v76, v66, v28
	ds_read_b128 v[66:69], v98
	ds_read_b128 v[70:73], v98 offset:32
	v_max_i32_e32 v28, v32, v30
	v_min_i32_e32 v77, v32, v30
	v_max_i32_e32 v78, v23, v18
	v_min_i32_e32 v79, v23, v18
	v_max_i32_e32 v80, v22, v27
	v_min_i32_e32 v81, v22, v27
	v_max_i32_e32 v82, v25, v24
	v_min_i32_e32 v124, v25, v24
	v_max_i32_e32 v125, v26, v19
	v_min_i32_e32 v126, v26, v19
	v_max_i32_e32 v127, v33, v21
	v_min_i32_e32 v128, v33, v21
	v_max_i32_e32 v129, v20, v28
	v_min_i32_e32 v130, v20, v28
	s_waitcnt lgkmcnt(1)
; #define LAS __attribute__((address_space(3)))
; #define MFMA32(a, b, c) __builtin_amdgcn_mfma_f32_32x32x16_bf16((a), (b), (c), 0, 0, 0)
; __device__ __forceinline__ void route_task(int task, int tl0, const bf16* QP  , const LAS bf16* KHL, LAS unsigned short* EL, LAS float* GL, int lane) {
;     ...
; #pragma unroll
;             for (int i = 0; i < 16; ++i) X[i] = 8.f;
;             const LAS bf16* khp = KHL + (half * 128 + 32 * kt + r) * 72 + 8 * hi;
; #pragma unroll
;             for (int ks = 0; ks < 4; ++ks) {
;                 const bf16x8 kh = lds8(khp + 16 * ks);
;                 X = MFMA32(kh, qa[half][ks], X);
;             }
;             int grp[16];
; #pragma unroll
;             for (int i = 0; i < 16; ++i) grp[i] = (int)((__float_as_uint(X[i]) | 127u) - (unsigned)(32 * kt + (i & 3) + 8 * (i >> 2)));
;             sort16_desc(grp);
;             if (kt == 0) {
; #pragma unroll
;                 for (int i = 0; i < 16; ++i) cur[i] = grp[i];
;             } else merge16_desc(cur, grp);
	v_mfma_f32_32x32x16_bf16 v[18:33], v[66:69], v[46:49], v[2:17]
	ds_read_b128 v[46:49], v98 offset:64
	v_max_i32_e32 v67, v75, v77
	v_min_i32_e32 v68, v75, v77
	v_max_i32_e32 v75, v80, v125
	v_max_i32_e32 v131, v74, v76
	v_min_i32_e32 v66, v74, v76
	v_max_i32_e32 v69, v78, v82
	s_waitcnt lgkmcnt(1)
	v_mfma_f32_32x32x16_bf16 v[18:33], v[70:73], v[42:45], v[18:33]
	ds_read_b128 v[42:45], v98 offset:96
	v_min_i32_e32 v70, v80, v125
	v_max_i32_e32 v71, v79, v124
	v_min_i32_e32 v72, v79, v124
	v_min_i32_e32 v74, v78, v82
	v_max_i32_e32 v73, v81, v126
	v_min_i32_e32 v76, v81, v126
	s_waitcnt lgkmcnt(1)
	v_mfma_f32_32x32x16_bf16 v[18:33], v[46:49], v[38:41], v[18:33]
	v_min_i32_e32 v77, v127, v129
	v_min_i32_e32 v38, v128, v130
	v_min_i32_e32 v39, v131, v67
	v_min_i32_e32 v40, v66, v68
	v_min_i32_e32 v41, v69, v75
	v_min_i32_e32 v46, v74, v70
	v_min_i32_e32 v47, v71, v73
	s_waitcnt lgkmcnt(0)
	v_mfma_f32_32x32x16_bf16 v[18:33], v[42:45], v[34:37], v[18:33]
	v_min_i32_e32 v48, v72, v76
	s_nop 10
	v_and_or_b32 v25, v25, s43, 20
	v_and_or_b32 v29, v29, s43, 12
	v_and_or_b32 v19, v19, s43, 30
	v_and_or_b32 v30, v30, s43, 7
	v_and_or_b32 v23, v23, s43, 22
	v_and_or_b32 v24, v24, s43, 21
	v_and_or_b32 v18, v18, s43, 31
	v_and_or_b32 v31, v31, s43, 6
	v_and_or_b32 v22, v22, s43, 23
	v_and_or_b32 v26, v26, s43, 15
	v_and_or_b32 v21, v21, s43, 28
	v_and_or_b32 v32, v32, s43, 5
	v_and_or_b32 v27, v27, s43, 14
	v_and_or_b32 v28, v28, s43, 13
	v_and_or_b32 v20, v20, s43, 29
	v_and_or_b32 v33, v33, s43, 4
	v_min_i32_e32 v34, v25, v29
	v_min_i32_e32 v35, v19, v30
	v_min_i32_e32 v37, v23, v24
	v_min_i32_e32 v42, v18, v31
	v_min_i32_e32 v45, v22, v26
	v_min_i32_e32 v49, v21, v32
	v_min_i32_e32 v79, v27, v28
	v_min_i32_e32 v80, v20, v33
	v_max_i32_e32 v18, v18, v31
	v_max_i32_e32 v23, v23, v24
	v_max_i32_e32 v19, v19, v30
	v_max_i32_e32 v25, v25, v29
	v_max_i32_e32 v20, v20, v33
	v_max_i32_e32 v27, v27, v28
	v_max_i32_e32 v21, v21, v32
	v_max_i32_e32 v22, v22, v26
	v_max_i32_e32 v24, v18, v23
	v_max_i32_e32 v29, v19, v25
	v_max_i32_e32 v28, v20, v27
	v_max_i32_e32 v26, v21, v22
	v_min_i32_e32 v30, v24, v29
	v_min_i32_e32 v31, v28, v26
	v_min_i32_e32 v43, v37, v42
	v_min_i32_e32 v32, v30, v31
	v_max_i32_e32 v30, v30, v31
	v_min_i32_e32 v21, v21, v22
	v_min_i32_e32 v18, v18, v23
	v_max_i32_e32 v23, v79, v80
	v_max_i32_e32 v31, v34, v35
	v_max_i32_e32 v37, v37, v42
	v_max_i32_e32 v42, v45, v49
	v_min_i32_e32 v19, v19, v25
	v_min_i32_e32 v20, v20, v27
	v_min_i32_e32 v36, v34, v35
	v_min_i32_e32 v78, v45, v49
	v_min_i32_e32 v81, v79, v80
	v_max_i32_e32 v22, v21, v18
	v_max_i32_e32 v45, v37, v42
	v_max_i32_e32 v25, v19, v20
	v_min_i32_e32 v18, v21, v18
	v_min_i32_e32 v21, v23, v31
	v_min_i32_e32 v44, v36, v43
	v_min_i32_e32 v82, v78, v81
	v_max_i32_e32 v33, v36, v43
	v_max_i32_e32 v36, v78, v81
	v_max_i32_e32 v24, v24, v29
	v_max_i32_e32 v26, v28, v26
	v_max_i32_e32 v34, v23, v31
	v_max_i32_e32 v27, v45, v25
	v_max_i32_e32 v23, v18, v21
	v_min_i32_e32 v25, v45, v25
	v_min_i32_e32 v37, v37, v42
	v_min_i32_e32 v19, v19, v20
	v_max_i32_e32 v43, v33, v36
	v_min_i32_e32 v28, v24, v26
	v_max_i32_e32 v35, v22, v34
	v_max_i32_e32 v31, v23, v25
	v_max_i32_e32 v20, v37, v19
	v_min_i32_e32 v23, v23, v25
	v_min_i32_e32 v19, v37, v19
	v_min_i32_e32 v18, v18, v21
	v_max_i32_e32 v25, v44, v82
	v_min_i32_e32 v33, v33, v36
	v_min_i32_e32 v29, v30, v28
	v_min_i32_e32 v49, v35, v27
	v_min_i32_e32 v22, v22, v34
	v_max_i32_e32 v21, v19, v18
	v_max_i32_e32 v36, v25, v33
	v_max_i32_e32 v78, v32, v43
	v_min_i32_e32 v79, v29, v49
	v_max_i32_e32 v34, v20, v22
	v_min_i32_e32 v20, v20, v22
	v_max_i32_e32 v37, v21, v36
	v_min_i32_e32 v32, v32, v43
	v_max_i32_e32 v80, v78, v79
	v_max_i32_e32 v42, v31, v34
	v_min_i32_e32 v78, v78, v79
	v_min_i32_e32 v31, v31, v34
	v_max_i32_e32 v22, v23, v20
	v_max_i32_e32 v43, v37, v32
	v_min_i32_e32 v18, v19, v18
	v_min_i32_e32 v19, v25, v33
	v_min_i32_e32 v20, v23, v20
	v_min_i32_e32 v23, v37, v32
	v_max_i32_e32 v28, v30, v28
	v_max_i32_e32 v27, v35, v27
	v_min_i32_e32 v124, v44, v82
	v_min_i32_e32 v45, v80, v42
	v_max_i32_e32 v34, v78, v31
	v_max_i32_e32 v44, v22, v43
	v_min_i32_e32 v31, v78, v31
	v_max_i32_e32 v25, v18, v19
	v_min_i32_e32 v21, v21, v36
	v_min_i32_e32 v32, v20, v23
	v_max_i32_e32 v29, v29, v49
	v_min_i32_e32 v30, v28, v27
	v_min_i32_e32 v22, v22, v43
	v_max_i32_e32 v20, v20, v23
	v_min_i32_e32 v79, v45, v34
	v_max_i32_e32 v78, v44, v31
	v_max_i32_e32 v33, v25, v21
	v_max_i32_e32 v37, v80, v42
	v_min_i32_e32 v35, v29, v30
	v_min_i32_e32 v31, v44, v31
	v_max_i32_e32 v23, v22, v20
	v_min_i32_e32 v81, v79, v78
	v_max_i32_e32 v36, v33, v32
	v_max_i32_e32 v42, v37, v35
	v_min_i32_e32 v21, v25, v21
	v_max_i32_e32 v25, v45, v34
	v_min_i32_e32 v43, v31, v23
	v_max_i32_e32 v27, v28, v27
	v_min_i32_e32 v18, v18, v19
	v_min_i32_e32 v20, v22, v20
	v_min_i32_e32 v32, v33, v32
	v_min_i32_e32 v33, v37, v35
	v_max3_i32 v124, v127, v129, v124
	v_max3_i32 v69, v69, v75, v81
	v_max3_i32 v36, v131, v67, v36
	v_max3_i32 v42, v71, v73, v42
	v_max3_i32 v21, v128, v130, v21
	v_max3_i32 v25, v74, v70, v25
	v_max3_i32 v43, v66, v68, v43
	v_max3_i32 v27, v72, v76, v27
	v_max_i32_e32 v18, v77, v18
	v_max3_i32 v19, v41, v79, v78
	v_max_i32_e32 v20, v39, v20
	v_max3_i32 v22, v47, v29, v30
	v_max_i32_e32 v32, v38, v32
	v_max_i32_e32 v33, v46, v33
	v_max3_i32 v23, v40, v31, v23
	v_max3_i32 v24, v48, v24, v26
	v_min_i32_e32 v49, v36, v42
	v_min_i32_e32 v34, v21, v25
	v_min_i32_e32 v41, v18, v19
	v_min_i32_e32 v29, v20, v22
	v_min_i32_e32 v26, v23, v24
	v_max_i32_e32 v39, v124, v69
	v_max_i32_e32 v36, v36, v42
	v_max_i32_e32 v21, v21, v25
	v_max_i32_e32 v25, v43, v27
; __device__ __forceinline__ void route_task(int task, int tl0, const bf16* QP  , const LAS bf16* KHL, LAS unsigned short* EL, LAS float* GL, int lane) {
;     ...
;         { const unsigned h4 = 4u * (unsigned)hi;
; #pragma unroll
;           for (int i = 0; i < 16; ++i) cur[i] -= (int)h4; }
;         int oth[16];
; #pragma unroll
;         for (int i = 0; i < 16; ++i) oth[i] = __shfl_xor(cur[i], 32);
;         merge16_desc(cur, oth);
; #pragma unroll
;         for (int i = 0; i < 16; ++i) top[half][i] = cur[i];
;     }
;     unsigned P1[4], P2[4];
; #pragma unroll
;     for (int q = 0; q < 4; ++q) { P1[q] = 0u; P2[q] = 0u;
; #pragma unroll
;         for (int s = 0; s < 4; ++s) { P1[q] |= (127u - ((unsigned)top[0][4 * q + s] & 127u)) << (8 * s); P2[q] |= (127u - ((unsigned)top[1][4 * q + s] & 127u)) << (8 * s); } }
	v_max_i32_e32 v18, v18, v19
	v_max_i32_e32 v19, v20, v22
	v_max_i32_e32 v22, v32, v33
	v_max_i32_e32 v23, v23, v24
	v_min_i32_e32 v28, v43, v27
	v_max_i32_e32 v40, v39, v36
	v_max_i32_e32 v27, v21, v25
	v_max_i32_e32 v20, v18, v19
	v_max_i32_e32 v24, v22, v23
	v_min_i32_e32 v35, v32, v33
	v_max_i32_e32 v42, v40, v27
	v_max_i32_e32 v32, v20, v24
	v_min_i32_e32 v27, v40, v27
	v_min_i32_e32 v20, v20, v24
	v_max_i32_e32 v24, v27, v20
	v_min_i32_e32 v20, v27, v20
	v_min_i32_e32 v27, v39, v36
	v_min_i32_e32 v21, v21, v25
	v_min_i32_e32 v18, v18, v19
	v_min_i32_e32 v19, v22, v23
	v_min_i32_e32 v75, v124, v69
	v_max_i32_e32 v25, v27, v21
	v_max_i32_e32 v22, v18, v19
	v_min_i32_e32 v21, v27, v21
	v_min_i32_e32 v18, v18, v19
	v_min_i32_e32 v44, v34, v28
	v_min_i32_e32 v31, v35, v26
	v_max_i32_e32 v23, v25, v22
	v_min_i32_e32 v22, v25, v22
	v_max_i32_e32 v19, v21, v18
	v_min_i32_e32 v18, v21, v18
	v_max_i32_e32 v21, v75, v49
	v_max_i32_e32 v25, v34, v28
	v_max_i32_e32 v28, v41, v29
	v_max_i32_e32 v26, v35, v26
	v_min_i32_e32 v67, v75, v49
	v_min_i32_e32 v30, v41, v29
	v_max_i32_e32 v27, v21, v25
	v_min_i32_e32 v21, v21, v25
	v_min_i32_e32 v25, v28, v26
	v_min_i32_e32 v45, v67, v44
	v_min_i32_e32 v37, v30, v31
	v_max_i32_e32 v29, v28, v26
	v_max_i32_e32 v26, v21, v25
	v_min_i32_e32 v21, v21, v25
	v_max_i32_e32 v25, v67, v44
	v_max_i32_e32 v28, v30, v31
	v_min_i32_e32 v38, v45, v37
	v_max_i32_e32 v33, v42, v32
	v_min_i32_e32 v32, v42, v32
	v_max_i32_e32 v34, v27, v29
	v_min_i32_e32 v27, v27, v29
	v_max_i32_e32 v29, v25, v28
	v_min_i32_e32 v25, v25, v28
	v_max_i32_e32 v28, v45, v37
	v_sub_u32_e32 v30, v33, v87
	v_sub_u32_e32 v31, v32, v87
	v_sub_u32_e32 v24, v24, v87
	v_sub_u32_e32 v20, v20, v87
	v_sub_u32_e32 v23, v23, v87
	v_sub_u32_e32 v22, v22, v87
	v_sub_u32_e32 v19, v19, v87
	v_sub_u32_e32 v18, v18, v87
	v_sub_u32_e32 v32, v34, v87
	v_sub_u32_e32 v27, v27, v87
	v_sub_u32_e32 v26, v26, v87
	v_sub_u32_e32 v21, v21, v87
	v_sub_u32_e32 v29, v29, v87
	v_sub_u32_e32 v25, v25, v87
	v_sub_u32_e32 v28, v28, v87
	v_sub_u32_e32 v33, v38, v87
	ds_bpermute_b32 v34, v123, v30
	ds_bpermute_b32 v35, v123, v31
	ds_bpermute_b32 v36, v123, v24
	ds_bpermute_b32 v37, v123, v20
	ds_bpermute_b32 v38, v123, v23
	ds_bpermute_b32 v39, v123, v22
	ds_bpermute_b32 v40, v123, v19
	ds_bpermute_b32 v41, v123, v18
	ds_bpermute_b32 v42, v123, v32
	ds_bpermute_b32 v43, v123, v27
	ds_bpermute_b32 v44, v123, v26
	ds_bpermute_b32 v45, v123, v33
	ds_bpermute_b32 v46, v123, v28
	ds_bpermute_b32 v47, v123, v25
	ds_bpermute_b32 v48, v123, v29
	ds_bpermute_b32 v49, v123, v21
	s_waitcnt lgkmcnt(4)
	v_max_i32_e32 v30, v30, v45
	s_waitcnt lgkmcnt(3)
	v_max_i32_e32 v31, v31, v46
	s_waitcnt lgkmcnt(2)
	v_max_i32_e32 v24, v24, v47
	s_waitcnt lgkmcnt(1)
	v_max_i32_e32 v20, v20, v48
	s_waitcnt lgkmcnt(0)
	v_max_i32_e32 v23, v23, v49
	v_max_i32_e32 v22, v22, v44
	v_max_i32_e32 v19, v19, v43
	v_max_i32_e32 v18, v18, v42
	v_max_i32_e32 v32, v32, v41
	v_max_i32_e32 v27, v27, v40
	v_max_i32_e32 v26, v26, v39
	v_max_i32_e32 v21, v21, v38
	v_max_i32_e32 v29, v29, v37
	v_max_i32_e32 v25, v25, v36
	v_max_i32_e32 v28, v28, v35
	v_max_i32_e32 v33, v33, v34
	v_max_i32_e32 v34, v30, v32
	v_min_i32_e32 v30, v30, v32
	v_max_i32_e32 v32, v31, v27
	v_min_i32_e32 v27, v31, v27
	v_max_i32_e32 v31, v24, v26
	v_min_i32_e32 v24, v24, v26
	v_max_i32_e32 v26, v20, v21
	v_min_i32_e32 v20, v20, v21
	v_max_i32_e32 v21, v23, v29
	v_min_i32_e32 v23, v23, v29
	v_max_i32_e32 v29, v22, v25
	v_min_i32_e32 v22, v22, v25
	v_max_i32_e32 v25, v19, v28
	v_min_i32_e32 v19, v19, v28
	v_max_i32_e32 v28, v18, v33
	v_min_i32_e32 v18, v18, v33
	v_max_i32_e32 v33, v34, v21
	v_min_i32_e32 v21, v34, v21
	v_max_i32_e32 v34, v32, v29
	v_min_i32_e32 v29, v32, v29
	v_max_i32_e32 v32, v31, v25
	v_min_i32_e32 v25, v31, v25
	v_max_i32_e32 v31, v26, v28
	v_min_i32_e32 v26, v26, v28
	v_max_i32_e32 v28, v30, v23
	v_min_i32_e32 v23, v30, v23
	v_max_i32_e32 v30, v27, v22
	v_min_i32_e32 v22, v27, v22
	v_max_i32_e32 v27, v24, v19
	v_min_i32_e32 v19, v24, v19
	v_max_i32_e32 v24, v20, v18
	v_min_i32_e32 v18, v20, v18
	v_max_i32_e32 v20, v33, v32
	v_min_i32_e32 v32, v33, v32
	v_max_i32_e32 v33, v34, v31
	v_min_i32_e32 v31, v34, v31
	v_max_i32_e32 v34, v21, v25
	v_min_i32_e32 v21, v21, v25
	v_max_i32_e32 v25, v29, v26
	v_min_i32_e32 v29, v29, v26
	v_max_i32_e32 v35, v28, v27
	v_min_i32_e32 v27, v28, v27
	v_max_i32_e32 v28, v30, v24
	v_min_i32_e32 v24, v30, v24
	v_max_i32_e32 v30, v23, v19
	v_min_i32_e32 v19, v23, v19
	v_max_i32_e32 v23, v22, v18
	v_min_i32_e32 v18, v22, v18
	v_max_i32_e32 v26, v20, v33
	v_min_i32_e32 v33, v20, v33
	v_lshlrev_b32_e32 v20, 8, v65
	v_lshlrev_b32_e32 v22, 16, v64
	v_max_i32_e32 v36, v32, v31
	v_max_i32_e32 v40, v19, v18
	v_min_i32_e32 v41, v19, v18
	v_and_b32_e32 v18, 0x7f, v63
	v_and_b32_e32 v20, 0x7f00, v20
	v_and_b32_e32 v22, 0x7f0000, v22
	v_max_i32_e32 v37, v21, v29
	v_min_i32_e32 v29, v21, v29
	v_lshlrev_b32_e32 v21, 8, v33
	v_or3_b32 v18, v20, v18, v22
	v_lshlrev_b32_e32 v20, 16, v36
	v_and_b32_e32 v19, 0x7f, v26
	v_and_b32_e32 v21, 0x7f00, v21
	v_and_b32_e32 v20, 0x7f0000, v20
	v_or3_b32 v20, v21, v19, v20
	v_lshlrev_b32_e32 v19, 24, v62
	v_min_i32_e32 v31, v32, v31
	v_and_b32_e32 v19, 0x7f000000, v19
	v_bitop3_b32 v19, v18, s68, v19 bitop3:0x36
	v_lshlrev_b32_e32 v18, 24, v31
	v_max_i32_e32 v38, v35, v28
	v_min_i32_e32 v28, v35, v28
	v_max_i32_e32 v35, v27, v24
	v_min_i32_e32 v27, v27, v24
	v_and_b32_e32 v18, 0x7f000000, v18
	v_lshlrev_b32_e32 v22, 8, v60
	v_lshlrev_b32_e32 v24, 16, v59
	v_max_i32_e32 v32, v34, v25
	v_min_i32_e32 v34, v34, v25
	v_bitop3_b32 v18, v20, s68, v18 bitop3:0x36
	v_and_b32_e32 v20, 0x7f, v61
; __device__ __forceinline__ void route_task(int task, int tl0, const bf16* QP  , const LAS bf16* KHL, LAS unsigned short* EL, LAS float* GL, int lane) {
;     ...
;     unsigned P1[4], P2[4];
; #pragma unroll
;     for (int q = 0; q < 4; ++q) { P1[q] = 0u; P2[q] = 0u;
; #pragma unroll
;         for (int s = 0; s < 4; ++s) { P1[q] |= (127u - ((unsigned)top[0][4 * q + s] & 127u)) << (8 * s); P2[q] |= (127u - ((unsigned)top[1][4 * q + s] & 127u)) << (8 * s); } }
;     int bk[16];
;     {
;         int hi2 = hi; asm volatile("" : "+v"(hi2));
;         const bool h1 = hi2 != 0;
;         constexpr int A1[16] = {1, 1, 1, 1, 1, 1, 1, 1, 2, 2, 2, 2, 2, 3, 3, 3}, B1[16] = {0, 1, 2, 3, 4, 5, 6, 7, 0, 1, 2, 3, 4, 0, 1, 2};
; #pragma unroll
;         for (int i = 0; i < 16; ++i) { const float ta = __int_as_float(h1 ? top[0][A1[i]] : top[0][0]), tb = __int_as_float(h1 ? top[1][B1[i]] : top[1][i]); const unsigned code = h1 ? (unsigned)(A1[i] * 16 + B1[i]) : (unsigned)i;
;             bk[i] = (int)((__float_as_uint(ta + tb) | 255u) - code); }
;         sort16_desc(bk);
	v_and_b32_e32 v22, 0x7f00, v22
	v_and_b32_e32 v24, 0x7f0000, v24
	v_max_i32_e32 v39, v30, v23
	v_min_i32_e32 v30, v30, v23
	v_lshlrev_b32_e32 v23, 8, v34
	v_or3_b32 v20, v22, v20, v24
	v_lshlrev_b32_e32 v22, 16, v37
	v_and_b32_e32 v21, 0x7f, v32
	v_and_b32_e32 v23, 0x7f00, v23
	v_and_b32_e32 v22, 0x7f0000, v22
	v_or3_b32 v22, v23, v21, v22
	v_lshlrev_b32_e32 v21, 24, v57
	v_and_b32_e32 v21, 0x7f000000, v21
	v_bitop3_b32 v21, v20, s68, v21 bitop3:0x36
	v_lshlrev_b32_e32 v20, 24, v29
	v_and_b32_e32 v20, 0x7f000000, v20
	v_lshlrev_b32_e32 v24, 8, v58
	v_lshlrev_b32_e32 v42, 16, v56
	v_bitop3_b32 v20, v22, s68, v20 bitop3:0x36
	v_and_b32_e32 v22, 0x7f, v55
	v_and_b32_e32 v24, 0x7f00, v24
	v_and_b32_e32 v42, 0x7f0000, v42
	v_lshlrev_b32_e32 v25, 8, v28
	v_or3_b32 v22, v24, v22, v42
	v_lshlrev_b32_e32 v24, 16, v35
	v_and_b32_e32 v23, 0x7f, v38
	v_and_b32_e32 v25, 0x7f00, v25
	v_and_b32_e32 v24, 0x7f0000, v24
	v_or3_b32 v24, v25, v23, v24
	v_lshlrev_b32_e32 v23, 24, v54
	v_and_b32_e32 v23, 0x7f000000, v23
	v_bitop3_b32 v23, v22, s68, v23 bitop3:0x36
	v_lshlrev_b32_e32 v22, 24, v27
	v_and_b32_e32 v22, 0x7f000000, v22
	v_lshlrev_b32_e32 v42, 8, v52
	v_lshlrev_b32_e32 v44, 16, v51
	v_bitop3_b32 v22, v24, s68, v22 bitop3:0x36
	v_and_b32_e32 v24, 0x7f, v53
	v_and_b32_e32 v42, 0x7f00, v42
	v_and_b32_e32 v44, 0x7f0000, v44
	v_lshlrev_b32_e32 v43, 8, v30
	v_or3_b32 v24, v42, v24, v44
	v_lshlrev_b32_e32 v42, 16, v40
	v_and_b32_e32 v25, 0x7f, v39
	v_and_b32_e32 v43, 0x7f00, v43
	v_and_b32_e32 v42, 0x7f0000, v42
	v_or3_b32 v42, v43, v25, v42
	v_lshlrev_b32_e32 v25, 24, v50
	v_and_b32_e32 v25, 0x7f000000, v25
	v_bitop3_b32 v25, v24, s68, v25 bitop3:0x36
	v_lshlrev_b32_e32 v24, 24, v41
	v_and_b32_e32 v24, 0x7f000000, v24
	v_bitop3_b32 v24, v42, s68, v24 bitop3:0x36
	v_mov_b32_e32 v42, v86
	v_add_f32_e32 v55, v55, v26
	v_cmp_eq_u32_e32 vcc, 0, v42
	v_add_f32_e32 v56, v56, v26
	v_add_f32_e32 v54, v54, v26
	v_cndmask_b32_e32 v42, v65, v63, vcc
	v_add_f32_e32 v44, v42, v26
	v_cndmask_b32_e64 v43, -16, 0, vcc
	v_or_b32_e32 v44, 0xff, v44
	v_add_f32_e32 v45, v42, v33
	v_add_u32_e32 v43, v44, v43
	v_cndmask_b32_e64 v44, v99, -1, vcc
	v_or_b32_e32 v45, 0xff, v45
	v_add_f32_e32 v46, v42, v36
	v_add_u32_e32 v44, v45, v44
	v_cndmask_b32_e64 v45, v100, -2, vcc
	v_or_b32_e32 v46, 0xff, v46
	v_add_f32_e32 v47, v42, v31
	v_add_u32_e32 v45, v46, v45
	v_cndmask_b32_e64 v46, v101, -3, vcc
	v_or_b32_e32 v47, 0xff, v47
	v_add_f32_e32 v48, v42, v32
	v_add_u32_e32 v46, v47, v46
	v_cndmask_b32_e64 v47, v102, -4, vcc
	v_or_b32_e32 v48, 0xff, v48
	v_add_f32_e32 v34, v42, v34
	v_add_f32_e32 v37, v42, v37
	v_add_f32_e32 v29, v42, v29
	v_cndmask_b32_e32 v42, v64, v63, vcc
	v_cndmask_b32_e32 v32, v32, v39, vcc
	v_add_u32_e32 v47, v48, v47
	v_cndmask_b32_e64 v48, v103, -5, vcc
	v_or_b32_e32 v34, 0xff, v34
	v_add_f32_e32 v32, v42, v32
	v_add_u32_e32 v34, v34, v48
	v_cndmask_b32_e64 v48, v104, -6, vcc
	v_or_b32_e32 v37, 0xff, v37
	v_cndmask_b32_e32 v38, v26, v38, vcc
	v_cndmask_b32_e64 v39, v116, -12, vcc
	v_or_b32_e32 v32, 0xff, v32
	v_add_u32_e32 v37, v37, v48
	v_cndmask_b32_e64 v48, v105, -7, vcc
	v_or_b32_e32 v29, 0xff, v29
	v_add_f32_e32 v38, v42, v38
	v_cndmask_b32_e32 v28, v33, v28, vcc
	v_add_u32_e32 v32, v32, v39
	v_cndmask_b32_e32 v39, v62, v63, vcc
	v_cndmask_b32_e32 v30, v26, v30, vcc
	v_add_u32_e32 v29, v29, v48
	v_cndmask_b32_e64 v48, v106, -8, vcc
	v_or_b32_e32 v38, 0xff, v38
	v_add_f32_e32 v28, v42, v28
	v_cndmask_b32_e32 v35, v36, v35, vcc
	v_cndmask_b32_e32 v27, v31, v27, vcc
	v_add_f32_e32 v30, v39, v30
	v_cndmask_b32_e32 v40, v33, v40, vcc
	v_add_u32_e32 v38, v38, v48
	v_cndmask_b32_e64 v48, v107, -9, vcc
	v_or_b32_e32 v28, 0xff, v28
	v_add_f32_e32 v35, v42, v35
	v_add_f32_e32 v27, v42, v27
	v_cndmask_b32_e64 v42, v117, -13, vcc
	v_or_b32_e32 v30, 0xff, v30
	v_add_f32_e32 v40, v39, v40
	v_cndmask_b32_e32 v41, v36, v41, vcc
	v_add_u32_e32 v28, v28, v48
	v_cndmask_b32_e64 v48, v114, -10, vcc
	v_or_b32_e32 v35, 0xff, v35
	v_add_u32_e32 v30, v30, v42
	v_cndmask_b32_e64 v42, v118, -14, vcc
	v_or_b32_e32 v40, 0xff, v40
	v_add_f32_e32 v39, v39, v41
	v_add_u32_e32 v35, v35, v48
	v_cndmask_b32_e64 v48, v115, -11, vcc
	v_or_b32_e32 v27, 0xff, v27
	v_add_u32_e32 v40, v40, v42
	v_cndmask_b32_e64 v42, v119, -15, vcc
	v_or_b32_e32 v39, 0xff, v39
	v_add_u32_e32 v27, v27, v48
	v_add_u32_e32 v39, v39, v42
	v_max_i32_e32 v41, v43, v30
	v_min_i32_e32 v30, v43, v30
	v_max_i32_e32 v42, v44, v32
	v_min_i32_e32 v32, v44, v32
	v_max_i32_e32 v43, v45, v39
	v_min_i32_e32 v39, v45, v39
	v_max_i32_e32 v44, v46, v40
	v_min_i32_e32 v40, v46, v40
	v_max_i32_e32 v45, v47, v38
	v_min_i32_e32 v38, v47, v38
	v_max_i32_e32 v46, v34, v37
	v_min_i32_e32 v34, v34, v37
	v_max_i32_e32 v37, v29, v27
	v_min_i32_e32 v27, v29, v27
	v_max_i32_e32 v29, v28, v35
	v_min_i32_e32 v28, v28, v35
	v_max_i32_e32 v35, v41, v46
	v_min_i32_e32 v41, v41, v46
	v_max_i32_e32 v46, v42, v37
	v_min_i32_e32 v37, v42, v37
	v_max_i32_e32 v42, v43, v29
	v_min_i32_e32 v29, v43, v29
	v_max_i32_e32 v43, v44, v45
	v_min_i32_e32 v44, v44, v45
	v_max_i32_e32 v45, v34, v30
	v_min_i32_e32 v30, v34, v30
	v_max_i32_e32 v34, v38, v40
	v_min_i32_e32 v38, v38, v40
	v_max_i32_e32 v40, v28, v39
	v_min_i32_e32 v28, v28, v39
	v_max_i32_e32 v39, v27, v32
	v_min_i32_e32 v27, v27, v32
	v_max_i32_e32 v32, v35, v46
	v_min_i32_e32 v35, v35, v46
	v_max_i32_e32 v46, v42, v43
	v_min_i32_e32 v42, v42, v43
	v_max_i32_e32 v43, v44, v41
	v_min_i32_e32 v41, v44, v41
	v_max_i32_e32 v44, v45, v34
	v_min_i32_e32 v34, v45, v34
	v_max_i32_e32 v45, v37, v29
	v_min_i32_e32 v29, v37, v29
	v_max_i32_e32 v37, v40, v39
	v_min_i32_e32 v39, v40, v39
	v_max_i32_e32 v40, v27, v30
; #define CAND(a, b) (int)((__float_as_uint(__int_as_float(top[0][a]) + __int_as_float(top[1][b])) | 255u) - (unsigned)((a) * 16 + (b)))
; __device__ __forceinline__ void route_task(int task, int tl0, const bf16* QP  , const LAS bf16* KHL, LAS unsigned short* EL, LAS float* GL, int lane) {
;     ...
;         sort16_desc(bk);
;         int oth[16];
; #pragma unroll
;         for (int i = 0; i < 16; ++i) oth[i] = __shfl_xor(bk[i], 32);
;         merge16_desc(bk, oth);
;     }
;     ...
;     {
;         int gk[16];
;         gk[0] = CAND(3, 3); gk[1] = CAND(4, 0); gk[2] = CAND(4, 1); gk[3] = CAND(4, 2); gk[4] = CAND(5, 0); gk[5] = CAND(5, 1); gk[6] = CAND(6, 0); gk[7] = CAND(6, 1);
;         gk[8] = CAND(7, 0); gk[9] = CAND(7, 1); gk[10] = CAND(8, 0); gk[11] = CAND(9, 0); gk[12] = CAND(10, 0); gk[13] = CAND(11, 0); gk[14] = CAND(12, 0); gk[15] = CAND(13, 0);
;         sort16_desc(gk);
	v_min_i32_e32 v27, v27, v30
	v_max_i32_e32 v30, v38, v28
	v_min_i32_e32 v28, v38, v28
	v_max_i32_e32 v38, v32, v46
	v_min_i32_e32 v32, v32, v46
	v_max_i32_e32 v46, v35, v42
	v_min_i32_e32 v35, v35, v42
	v_max_i32_e32 v42, v43, v37
	v_min_i32_e32 v37, v43, v37
	v_max_i32_e32 v43, v41, v39
	v_min_i32_e32 v39, v41, v39
	v_max_i32_e32 v41, v44, v45
	v_min_i32_e32 v44, v44, v45
	v_max_i32_e32 v45, v34, v29
	v_min_i32_e32 v29, v34, v29
	v_max_i32_e32 v34, v40, v30
	v_min_i32_e32 v30, v40, v30
	v_max_i32_e32 v40, v27, v28
	v_min_i32_e32 v27, v27, v28
	v_max_i32_e32 v28, v46, v32
	v_min_i32_e32 v32, v46, v32
	v_max_i32_e32 v46, v35, v34
	v_min_i32_e32 v34, v35, v34
	v_max_i32_e32 v35, v42, v41
	v_min_i32_e32 v41, v42, v41
	v_max_i32_e32 v42, v43, v44
	v_min_i32_e32 v43, v43, v44
	v_max_i32_e32 v44, v45, v37
	v_min_i32_e32 v37, v45, v37
	v_max_i32_e32 v45, v29, v39
	v_min_i32_e32 v29, v29, v39
	v_max_i32_e32 v39, v40, v30
	v_min_i32_e32 v30, v40, v30
	v_max_i32_e32 v40, v28, v35
	v_min_i32_e32 v28, v28, v35
	v_max_i32_e32 v35, v32, v41
	v_min_i32_e32 v32, v32, v41
	v_max_i32_e32 v41, v42, v44
	v_min_i32_e32 v42, v42, v44
	v_max_i32_e32 v44, v43, v37
	v_min_i32_e32 v37, v43, v37
	v_max_i32_e32 v43, v45, v39
	v_min_i32_e32 v39, v45, v39
	v_max_i32_e32 v45, v29, v30
	v_min_i32_e32 v29, v29, v30
	v_max_i32_e32 v30, v35, v28
	v_min_i32_e32 v28, v35, v28
	v_max_i32_e32 v35, v46, v32
	v_min_i32_e32 v32, v46, v32
	v_max_i32_e32 v46, v43, v34
	v_min_i32_e32 v34, v43, v34
	v_max_i32_e32 v43, v45, v39
	v_min_i32_e32 v39, v45, v39
	v_max_i32_e32 v45, v35, v41
	v_min_i32_e32 v35, v35, v41
	v_max_i32_e32 v41, v32, v42
	v_min_i32_e32 v32, v32, v42
	v_max_i32_e32 v42, v44, v46
	v_min_i32_e32 v44, v44, v46
	v_max_i32_e32 v46, v37, v34
	v_min_i32_e32 v34, v37, v34
	v_max_i32_e32 v37, v45, v28
	v_min_i32_e32 v28, v45, v28
	v_max_i32_e32 v45, v35, v41
	v_min_i32_e32 v35, v35, v41
	v_max_i32_e32 v41, v42, v32
	v_min_i32_e32 v32, v42, v32
	v_max_i32_e32 v42, v44, v46
	v_min_i32_e32 v44, v44, v46
	v_max_i32_e32 v46, v43, v34
	v_min_i32_e32 v34, v43, v34
	v_max_i32_e32 v43, v35, v41
	v_min_i32_e32 v35, v35, v41
	v_max_i32_e32 v41, v32, v42
	v_min_i32_e32 v32, v32, v42
	ds_bpermute_b32 v67, v123, v41
	ds_bpermute_b32 v68, v123, v32
	ds_bpermute_b32 v69, v123, v44
	ds_bpermute_b32 v64, v123, v45
	ds_bpermute_b32 v65, v123, v43
	ds_bpermute_b32 v66, v123, v35
	s_waitcnt lgkmcnt(4)
	v_max_i32_e32 v43, v43, v68
	s_waitcnt lgkmcnt(3)
	v_max_i32_e32 v45, v45, v69
	v_max_i32_e32 v35, v35, v67
	v_add_f32_e32 v31, v62, v31
	v_add_f32_e32 v62, v61, v26
	v_add_f32_e32 v67, v61, v33
	v_add_f32_e32 v36, v61, v36
	v_add_f32_e32 v61, v60, v26
	v_add_f32_e32 v60, v60, v33
	v_add_f32_e32 v68, v59, v26
	v_add_f32_e32 v59, v59, v33
	v_add_f32_e32 v69, v57, v26
	v_add_f32_e32 v33, v57, v33
	v_add_f32_e32 v57, v58, v26
	v_add_f32_e32 v53, v53, v26
	v_add_f32_e32 v52, v52, v26
	ds_bpermute_b32 v70, v123, v27
	v_or_b32_e32 v31, 0xff, v31
	v_or_b32_e32 v62, 0xff, v62
	v_or_b32_e32 v67, 0xff, v67
	v_or_b32_e32 v36, 0xff, v36
	v_or_b32_e32 v61, 0xff, v61
	v_or_b32_e32 v60, 0xff, v60
	v_or_b32_e32 v68, 0xff, v68
	v_or_b32_e32 v59, 0xff, v59
	v_or_b32_e32 v69, 0xff, v69
	v_or_b32_e32 v33, 0xff, v33
	v_or_b32_e32 v55, 0xff, v55
	v_or_b32_e32 v57, 0xff, v57
	v_or_b32_e32 v56, 0xff, v56
	v_or_b32_e32 v54, 0xff, v54
	v_or_b32_e32 v53, 0xff, v53
	v_or_b32_e32 v52, 0xff, v52
	v_subrev_u32_e32 v31, 51, v31
	v_subrev_u32_e32 v62, 64, v62
	v_add_u32_e32 v67, 0xffffffbf, v67
	v_add_u32_e32 v36, 0xffffffbe, v36
	v_add_u32_e32 v61, 0xffffffb0, v61
	v_add_u32_e32 v60, 0xffffffaf, v60
	v_add_u32_e32 v68, 0xffffffa0, v68
	v_add_u32_e32 v59, 0xffffff9f, v59
	v_add_u32_e32 v69, 0xffffff90, v69
	v_add_u32_e32 v33, 0xffffff8f, v33
	v_add_u32_e32 v55, 0xffffff80, v55
	v_add_u32_e32 v57, 0xffffff70, v57
	v_add_u32_e32 v56, 0xffffff60, v56
	v_add_u32_e32 v54, 0xffffff50, v54
	v_add_u32_e32 v53, 0xffffff40, v53
	v_add_u32_e32 v52, 0xffffff30, v52
	ds_bpermute_b32 v42, v123, v38
	ds_bpermute_b32 v47, v123, v40
	ds_bpermute_b32 v48, v123, v30
	ds_bpermute_b32 v49, v123, v37
	ds_bpermute_b32 v63, v123, v28
	ds_bpermute_b32 v71, v123, v29
	ds_bpermute_b32 v72, v123, v39
	ds_bpermute_b32 v73, v123, v34
	ds_bpermute_b32 v74, v123, v46
	v_max_i32_e32 v58, v31, v54
	v_min_i32_e32 v31, v31, v54
	v_max_i32_e32 v54, v62, v56
	v_min_i32_e32 v56, v62, v56
	v_max_i32_e32 v62, v67, v52
	v_min_i32_e32 v52, v67, v52
	v_max_i32_e32 v67, v36, v53
	v_min_i32_e32 v36, v36, v53
	v_max_i32_e32 v53, v61, v69
	v_min_i32_e32 v61, v61, v69
	v_max_i32_e32 v69, v60, v68
	v_min_i32_e32 v60, v60, v68
	v_max_i32_e32 v68, v59, v57
	v_min_i32_e32 v57, v59, v57
	v_max_i32_e32 v59, v33, v55
	v_min_i32_e32 v33, v33, v55
	v_max_i32_e32 v55, v58, v69
	v_min_i32_e32 v58, v58, v69
	v_max_i32_e32 v69, v54, v68
	v_min_i32_e32 v54, v54, v68
	v_max_i32_e32 v68, v62, v59
	v_min_i32_e32 v59, v62, v59
	v_max_i32_e32 v62, v67, v53
	v_min_i32_e32 v53, v67, v53
	v_max_i32_e32 v67, v60, v31
	v_min_i32_e32 v31, v60, v31
	v_max_i32_e32 v60, v61, v36
	v_min_i32_e32 v36, v61, v36
	v_max_i32_e32 v61, v33, v52
	v_min_i32_e32 v33, v33, v52
	v_max_i32_e32 v52, v57, v56
	v_min_i32_e32 v56, v57, v56
	v_max_i32_e32 v57, v55, v69
	v_min_i32_e32 v55, v55, v69
	v_max_i32_e32 v69, v68, v62
	v_min_i32_e32 v62, v68, v62
	v_max_i32_e32 v68, v53, v58
	v_min_i32_e32 v53, v53, v58
	v_max_i32_e32 v58, v67, v60
	v_min_i32_e32 v60, v67, v60
	v_max_i32_e32 v67, v54, v59
	v_min_i32_e32 v54, v54, v59
	v_max_i32_e32 v59, v61, v52
	v_min_i32_e32 v52, v61, v52
	v_max_i32_e32 v61, v56, v31
	v_min_i32_e32 v31, v56, v31
	v_max_i32_e32 v56, v36, v33
	v_min_i32_e32 v33, v36, v33
	s_waitcnt lgkmcnt(9)
; #define CAND(a, b) (int)((__float_as_uint(__int_as_float(top[0][a]) + __int_as_float(top[1][b])) | 255u) - (unsigned)((a) * 16 + (b)))
; __device__ __forceinline__ void route_task(int task, int tl0, const bf16* QP  , const LAS bf16* KHL, LAS unsigned short* EL, LAS float* GL, int lane) {
;     ...
;         int oth[16];
; #pragma unroll
;         for (int i = 0; i < 16; ++i) oth[i] = __shfl_xor(bk[i], 32);
;         merge16_desc(bk, oth);
;     }
;     ...
;     {
;         int gk[16];
;         gk[0] = CAND(3, 3); gk[1] = CAND(4, 0); gk[2] = CAND(4, 1); gk[3] = CAND(4, 2); gk[4] = CAND(5, 0); gk[5] = CAND(5, 1); gk[6] = CAND(6, 0); gk[7] = CAND(6, 1);
;         gk[8] = CAND(7, 0); gk[9] = CAND(7, 1); gk[10] = CAND(8, 0); gk[11] = CAND(9, 0); gk[12] = CAND(10, 0); gk[13] = CAND(11, 0); gk[14] = CAND(12, 0); gk[15] = CAND(13, 0);
;         sort16_desc(gk);
;         merge16_desc(bk, gk);
	v_max_i32_e32 v38, v38, v70
	v_min_i32_e32 v36, v57, v69
	v_max_i32_e32 v70, v55, v62
	v_min_i32_e32 v55, v55, v62
	v_max_i32_e32 v62, v68, v59
	v_min_i32_e32 v59, v68, v59
	v_max_i32_e32 v68, v53, v52
	v_min_i32_e32 v52, v53, v52
	v_max_i32_e32 v53, v58, v67
	v_min_i32_e32 v58, v58, v67
	v_max_i32_e32 v67, v60, v54
	v_min_i32_e32 v54, v60, v54
	v_max_i32_e32 v60, v61, v56
	v_min_i32_e32 v56, v61, v56
	v_max_i32_e32 v61, v31, v33
	v_min_i32_e32 v31, v31, v33
	v_max_i32_e32 v33, v70, v36
	v_min_i32_e32 v36, v70, v36
	v_max_i32_e32 v70, v55, v60
	v_min_i32_e32 v55, v55, v60
	v_max_i32_e32 v60, v62, v53
	v_min_i32_e32 v53, v62, v53
	v_max_i32_e32 v62, v68, v58
	v_min_i32_e32 v58, v68, v58
	v_max_i32_e32 v68, v67, v59
	v_min_i32_e32 v59, v67, v59
	v_max_i32_e32 v67, v54, v52
	v_min_i32_e32 v52, v54, v52
	v_max_i32_e32 v54, v61, v56
	s_waitcnt lgkmcnt(3)
	v_max_i32_e32 v40, v40, v71
	s_waitcnt lgkmcnt(2)
	v_max_i32_e32 v30, v30, v72
	s_waitcnt lgkmcnt(1)
	v_max_i32_e32 v37, v37, v73
	s_waitcnt lgkmcnt(0)
	v_max_i32_e32 v28, v28, v74
	v_max_i32_e32 v41, v41, v66
	v_max_i32_e32 v32, v32, v65
	v_max_i32_e32 v44, v44, v64
	v_max_i32_e32 v46, v46, v63
	v_max_i32_e32 v34, v34, v49
	v_max_i32_e32 v39, v39, v48
	v_max_i32_e32 v29, v29, v47
	v_max_i32_e32 v27, v27, v42
	v_min_i32_e32 v56, v61, v56
	v_max_i32_e32 v61, v33, v60
	v_min_i32_e32 v33, v33, v60
	v_max_i32_e32 v60, v36, v53
	v_min_i32_e32 v36, v36, v53
	v_max_i32_e32 v53, v62, v68
	v_min_i32_e32 v62, v62, v68
	v_max_i32_e32 v68, v58, v59
	v_min_i32_e32 v58, v58, v59
	v_max_i32_e32 v59, v67, v54
	v_max_i32_e32 v42, v38, v41
	v_min_i32_e32 v38, v38, v41
	v_max_i32_e32 v41, v40, v32
	v_min_i32_e32 v32, v40, v32
	v_max_i32_e32 v40, v30, v44
	v_min_i32_e32 v30, v30, v44
	v_max_i32_e32 v44, v37, v46
	v_min_i32_e32 v37, v37, v46
	v_max_i32_e32 v46, v28, v34
	v_min_i32_e32 v28, v28, v34
	v_max_i32_e32 v34, v45, v39
	v_min_i32_e32 v39, v45, v39
	v_max_i32_e32 v45, v43, v29
	v_min_i32_e32 v29, v43, v29
	v_max_i32_e32 v43, v35, v27
	v_min_i32_e32 v27, v35, v27
	v_min_i32_e32 v54, v67, v54
	v_max_i32_e32 v67, v52, v56
	v_max_i32_e32 v71, v70, v36
	v_min_i32_e32 v36, v70, v36
	v_max_i32_e32 v70, v59, v55
	v_min_i32_e32 v55, v59, v55
	v_max_i32_e32 v35, v42, v46
	v_min_i32_e32 v42, v42, v46
	v_max_i32_e32 v46, v41, v34
	v_min_i32_e32 v34, v41, v34
	v_max_i32_e32 v41, v40, v45
	v_min_i32_e32 v40, v40, v45
	v_max_i32_e32 v45, v44, v43
	v_min_i32_e32 v43, v44, v43
	v_max_i32_e32 v44, v38, v28
	v_min_i32_e32 v28, v38, v28
	v_max_i32_e32 v38, v32, v39
	v_min_i32_e32 v32, v32, v39
	v_max_i32_e32 v39, v30, v29
	v_min_i32_e32 v29, v30, v29
	v_max_i32_e32 v30, v37, v27
	v_min_i32_e32 v27, v37, v27
	v_min_i32_e32 v52, v52, v56
	v_min_i32_e32 v56, v60, v33
	v_max_i32_e32 v59, v67, v54
	v_min_i32_e32 v54, v67, v54
	v_max_i32_e32 v67, v71, v53
	v_min_i32_e32 v53, v71, v53
	v_max_i32_e32 v71, v36, v62
	v_min_i32_e32 v36, v36, v62
	v_max_i32_e32 v62, v68, v70
	v_min_i32_e32 v68, v68, v70
	v_max_i32_e32 v70, v58, v55
	v_max_i32_e32 v37, v35, v41
	v_min_i32_e32 v35, v35, v41
	v_max_i32_e32 v41, v46, v45
	v_min_i32_e32 v45, v46, v45
	v_max_i32_e32 v46, v42, v40
	v_min_i32_e32 v40, v42, v40
	v_max_i32_e32 v42, v34, v43
	v_min_i32_e32 v34, v34, v43
	v_max_i32_e32 v43, v44, v39
	v_min_i32_e32 v39, v44, v39
	v_max_i32_e32 v44, v38, v30
	v_min_i32_e32 v30, v38, v30
	v_max_i32_e32 v38, v28, v29
	v_min_i32_e32 v28, v28, v29
	v_max_i32_e32 v29, v32, v27
	v_min_i32_e32 v27, v32, v27
	v_min_i32_e32 v55, v58, v55
	v_max_i32_e32 v58, v67, v56
	v_min_i32_e32 v56, v67, v56
	v_max_i32_e32 v67, v53, v71
	v_min_i32_e32 v53, v53, v71
	v_max_i32_e32 v71, v62, v36
	v_min_i32_e32 v36, v62, v36
	v_max_i32_e32 v62, v68, v70
	v_min_i32_e32 v32, v37, v41
	v_min_i32_e32 v47, v35, v45
	v_min_i32_e32 v48, v46, v42
	v_min_i32_e32 v49, v40, v34
	v_min_i32_e32 v63, v43, v44
	v_min_i32_e32 v64, v39, v30
	v_min_i32_e32 v65, v38, v29
	v_min_i32_e32 v66, v28, v27
	v_min_i32_e32 v68, v68, v70
	v_max_i32_e32 v70, v59, v55
	v_min_i32_e32 v55, v59, v55
	v_min_i32_e32 v59, v53, v71
	v_min_i32_e32 v72, v36, v62
	v_max3_i32 v31, v37, v41, v31
	v_max_i32_e32 v32, v32, v52
	v_max3_i32 v35, v35, v45, v54
	v_max_i32_e32 v37, v47, v55
	v_max3_i32 v41, v46, v42, v70
	v_max_i32_e32 v42, v48, v68
	v_max3_i32 v34, v40, v34, v72
	v_max3_i32 v36, v49, v36, v62
	v_max3_i32 v40, v43, v44, v59
	v_max3_i32 v43, v63, v53, v71
	v_max3_i32 v30, v39, v30, v67
	v_max_i32_e32 v39, v64, v56
	v_max3_i32 v29, v38, v29, v58
	v_max3_i32 v33, v65, v60, v33
	v_max3_i32 v27, v28, v27, v61
	v_max3_i32 v28, v66, v57, v69
	v_max_i32_e32 v38, v31, v40
	v_min_i32_e32 v31, v31, v40
	v_max_i32_e32 v40, v32, v43
	v_min_i32_e32 v32, v32, v43
	v_max_i32_e32 v43, v35, v30
	v_min_i32_e32 v30, v35, v30
	v_max_i32_e32 v35, v37, v39
	v_min_i32_e32 v37, v37, v39
	v_max_i32_e32 v39, v41, v29
	v_min_i32_e32 v29, v41, v29
	v_max_i32_e32 v41, v42, v33
	v_min_i32_e32 v33, v42, v33
	v_max_i32_e32 v42, v34, v27
	v_min_i32_e32 v27, v34, v27
	v_max_i32_e32 v34, v36, v28
	v_min_i32_e32 v28, v36, v28
	v_max_i32_e32 v36, v38, v39
	v_min_i32_e32 v38, v38, v39
	v_max_i32_e32 v39, v40, v41
	v_min_i32_e32 v40, v40, v41
	v_max_i32_e32 v41, v43, v42
	v_min_i32_e32 v42, v43, v42
	v_max_i32_e32 v43, v35, v34
	v_min_i32_e32 v34, v35, v34
	v_max_i32_e32 v35, v31, v29
	v_min_i32_e32 v29, v31, v29
	v_max_i32_e32 v31, v32, v33
	v_min_i32_e32 v32, v32, v33
	v_max_i32_e32 v33, v30, v27
	v_min_i32_e32 v27, v30, v27
	v_max_i32_e32 v30, v37, v28
	v_min_i32_e32 v28, v37, v28
	v_max_i32_e32 v37, v36, v41
	v_min_i32_e32 v36, v36, v41
	v_max_i32_e32 v41, v39, v43
	v_min_i32_e32 v39, v39, v43
	v_max_i32_e32 v43, v38, v42
	v_min_i32_e32 v38, v38, v42
; #define CAND(a, b) (int)((__float_as_uint(__int_as_float(top[0][a]) + __int_as_float(top[1][b])) | 255u) - (unsigned)((a) * 16 + (b)))
; __device__ __forceinline__ void route_task(int task, int tl0, const bf16* QP  , const LAS bf16* KHL, LAS unsigned short* EL, LAS float* GL, int lane) {
;     ...
;         merge16_desc(bk, gk);
;     }
;     {
;         const int c14 = CAND(14, 0), c15 = CAND(15, 0);
;         const int n14 = max(bk[14], c14), n15 = max(min(bk[14], c14), max(bk[15], c15));
;         bk[14] = n14; bk[15] = n15;
;     }
;     ...
;     int my[8];
; #pragma unroll
;     for (int i = 0; i < 8; ++i) { int lo_ = bk[i], hi_ = bk[8 + i]; asm volatile("" : "+v"(lo_), "+v"(hi_)); my[i] = hi ? hi_ : lo_; }
;     int bv[8];
; #pragma unroll
;     for (int i = 0; i < 8; ++i) {
;         const unsigned cd = 255u - ((unsigned)my[i] & 255u), ca = cd >> 4, cb = cd & 15u;
;         const unsigned wa = (ca >> 2) == 0u ? P1[0] : (ca >> 2) == 1u ? P1[1] : (ca >> 2) == 2u ? P1[2] : P1[3];
;         const unsigned wb = (cb >> 2) == 0u ? P2[0] : (cb >> 2) == 1u ? P2[1] : (cb >> 2) == 2u ? P2[2] : P2[3];
;         bv[i] = (int)((((wa >> (8u * (ca & 3u))) & 255u) << 7) | ((wb >> (8u * (cb & 3u))) & 255u));
	v_max_i32_e32 v42, v40, v34
	v_min_i32_e32 v34, v40, v34
	v_max_i32_e32 v40, v35, v33
	v_min_i32_e32 v33, v35, v33
	v_max_i32_e32 v35, v31, v30
	v_min_i32_e32 v30, v31, v30
	v_max_i32_e32 v31, v29, v27
	v_min_i32_e32 v27, v29, v27
	v_max_i32_e32 v29, v32, v28
	v_min_i32_e32 v28, v32, v28
	v_max_i32_e32 v32, v37, v41
	v_min_i32_e32 v37, v37, v41
	v_max_i32_e32 v41, v36, v39
	v_min_i32_e32 v36, v36, v39
	v_max_i32_e32 v39, v43, v42
	v_min_i32_e32 v42, v43, v42
	v_max_i32_e32 v43, v38, v34
	v_min_i32_e32 v34, v38, v34
	v_max_i32_e32 v38, v40, v35
	v_min_i32_e32 v35, v40, v35
	v_max_i32_e32 v40, v33, v30
	v_min_i32_e32 v30, v33, v30
	v_max_i32_e32 v33, v31, v29
	v_min_i32_e32 v29, v31, v29
	v_max_i32_e32 v31, v27, v28
	v_min_i32_e32 v27, v27, v28
	v_add_f32_e32 v28, v51, v26
	v_or_b32_e32 v28, 0xff, v28
	v_add_f32_e32 v26, v50, v26
	v_add_u32_e32 v28, 0xffffff20, v28
	v_or_b32_e32 v26, 0xff, v26
	v_add_u32_e32 v26, 0xffffff10, v26
	v_max_i32_e32 v44, v31, v28
	v_min_i32_e32 v28, v31, v28
	v_max3_i32 v26, v28, v27, v26
	v_mov_b32_e32 v27, v32
	s_nop 0
	v_cndmask_b32_e64 v27, v38, v27, s[6:7]
	v_not_b32_e32 v28, v27
	v_bfe_u32 v45, v28, 6, 2
	v_cmp_eq_u32_e32 vcc, 2, v45
	v_cndmask_b32_e64 v34, v26, v34, s[6:7]
	v_bitop3_b32 v26, v27, s3, v27 bitop3:0xc
	v_cndmask_b32_e32 v46, v25, v23, vcc
	v_cmp_eq_u32_e32 vcc, 1, v45
	v_cndmask_b32_e64 v31, v35, v37, s[6:7]
	v_not_b32_e32 v35, v31
	v_cndmask_b32_e32 v45, v46, v21, vcc
	v_cmp_gt_u32_e32 vcc, 64, v26
	v_cndmask_b32_e64 v37, v40, v41, s[6:7]
	v_cndmask_b32_e64 v41, v44, v43, s[6:7]
	v_cndmask_b32_e32 v26, v45, v19, vcc
	v_bfe_u32 v45, v28, 2, 2
	v_cmp_eq_u32_e32 vcc, 2, v45
	v_bitop3_b32 v44, v27, 15, v27 bitop3:0xc
	v_bfe_u32 v47, v35, 6, 2
	v_cndmask_b32_e32 v46, v24, v22, vcc
	v_cmp_eq_u32_e32 vcc, 1, v45
	v_not_b32_e32 v38, v37
	v_bfe_u32 v49, v38, 6, 2
	v_cndmask_b32_e32 v45, v46, v20, vcc
	v_cmp_gt_u32_e32 vcc, 4, v44
	v_bitop3_b32 v46, v31, 15, v31 bitop3:0xc
	v_cndmask_b32_e64 v30, v30, v36, s[6:7]
	v_cndmask_b32_e32 v44, v45, v18, vcc
	v_cmp_eq_u32_e32 vcc, 2, v47
	v_bitop3_b32 v45, v31, s3, v31 bitop3:0xc
	v_not_b32_e32 v36, v30
	v_cndmask_b32_e32 v48, v25, v23, vcc
	v_cmp_eq_u32_e32 vcc, 1, v47
	v_bfe_u32 v51, v36, 6, 2
	v_cndmask_b32_e64 v33, v33, v39, s[6:7]
	v_cndmask_b32_e32 v47, v48, v21, vcc
	v_cmp_gt_u32_e32 vcc, 64, v45
	v_not_b32_e32 v39, v33
	v_bfe_u32 v53, v39, 6, 2
	v_cndmask_b32_e32 v45, v47, v19, vcc
	v_bfe_u32 v47, v35, 2, 2
	v_cmp_eq_u32_e32 vcc, 2, v47
	v_cndmask_b32_e64 v29, v29, v42, s[6:7]
	v_not_b32_e32 v40, v29
	v_cndmask_b32_e32 v48, v24, v22, vcc
	v_cmp_eq_u32_e32 vcc, 1, v47
	v_bfe_u32 v55, v40, 6, 2
	v_not_b32_e32 v42, v41
	v_cndmask_b32_e32 v47, v48, v20, vcc
	v_cmp_gt_u32_e32 vcc, 4, v46
	v_bitop3_b32 v48, v37, 15, v37 bitop3:0xc
	v_bfe_u32 v57, v42, 6, 2
	v_cndmask_b32_e32 v46, v47, v18, vcc
	v_cmp_eq_u32_e32 vcc, 2, v49
	v_bitop3_b32 v47, v37, s3, v37 bitop3:0xc
	v_not_b32_e32 v43, v34
	v_cndmask_b32_e32 v50, v25, v23, vcc
	v_cmp_eq_u32_e32 vcc, 1, v49
	v_bfe_u32 v59, v43, 6, 2
	v_or_b32_e32 v82, s10, v88
	v_cndmask_b32_e32 v49, v50, v21, vcc
	v_cmp_gt_u32_e32 vcc, 64, v47
	s_nop 1
	v_cndmask_b32_e32 v47, v49, v19, vcc
	v_bfe_u32 v49, v38, 2, 2
	v_cmp_eq_u32_e32 vcc, 2, v49
	s_nop 1
	v_cndmask_b32_e32 v50, v24, v22, vcc
	v_cmp_eq_u32_e32 vcc, 1, v49
	s_nop 1
	v_cndmask_b32_e32 v49, v50, v20, vcc
	v_cmp_gt_u32_e32 vcc, 4, v48
	v_bitop3_b32 v50, v30, 15, v30 bitop3:0xc
	s_nop 0
	v_cndmask_b32_e32 v48, v49, v18, vcc
	v_cmp_eq_u32_e32 vcc, 2, v51
	v_bitop3_b32 v49, v30, s3, v30 bitop3:0xc
	s_nop 0
	v_cndmask_b32_e32 v52, v25, v23, vcc
	v_cmp_eq_u32_e32 vcc, 1, v51
	s_nop 1
	v_cndmask_b32_e32 v51, v52, v21, vcc
	v_cmp_gt_u32_e32 vcc, 64, v49
	s_nop 1
	v_cndmask_b32_e32 v49, v51, v19, vcc
	v_bfe_u32 v51, v36, 2, 2
	v_cmp_eq_u32_e32 vcc, 2, v51
	s_nop 1
	v_cndmask_b32_e32 v52, v24, v22, vcc
	v_cmp_eq_u32_e32 vcc, 1, v51
	s_nop 1
	v_cndmask_b32_e32 v51, v52, v20, vcc
	v_cmp_gt_u32_e32 vcc, 4, v50
	v_bitop3_b32 v52, v33, 15, v33 bitop3:0xc
	s_nop 0
	v_cndmask_b32_e32 v50, v51, v18, vcc
	v_cmp_eq_u32_e32 vcc, 2, v53
	v_bitop3_b32 v51, v33, s3, v33 bitop3:0xc
	s_nop 0
	v_cndmask_b32_e32 v54, v25, v23, vcc
	v_cmp_eq_u32_e32 vcc, 1, v53
	s_nop 1
	v_cndmask_b32_e32 v53, v54, v21, vcc
	v_cmp_gt_u32_e32 vcc, 64, v51
	s_nop 1
	v_cndmask_b32_e32 v51, v53, v19, vcc
	v_bfe_u32 v53, v39, 2, 2
	v_cmp_eq_u32_e32 vcc, 2, v53
	s_nop 1
	v_cndmask_b32_e32 v54, v24, v22, vcc
	v_cmp_eq_u32_e32 vcc, 1, v53
	s_nop 1
	v_cndmask_b32_e32 v53, v54, v20, vcc
	v_cmp_gt_u32_e32 vcc, 4, v52
	v_bitop3_b32 v54, v29, 15, v29 bitop3:0xc
	s_nop 0
	v_cndmask_b32_e32 v52, v53, v18, vcc
	v_cmp_eq_u32_e32 vcc, 2, v55
	v_bitop3_b32 v53, v29, s3, v29 bitop3:0xc
	s_nop 0
	v_cndmask_b32_e32 v56, v25, v23, vcc
	v_cmp_eq_u32_e32 vcc, 1, v55
	s_nop 1
	v_cndmask_b32_e32 v55, v56, v21, vcc
	v_cmp_gt_u32_e32 vcc, 64, v53
	s_nop 1
	v_cndmask_b32_e32 v53, v55, v19, vcc
	v_bfe_u32 v55, v40, 2, 2
	v_cmp_eq_u32_e32 vcc, 2, v55
	s_nop 1
	v_cndmask_b32_e32 v56, v24, v22, vcc
	v_cmp_eq_u32_e32 vcc, 1, v55
	s_nop 1
	v_cndmask_b32_e32 v55, v56, v20, vcc
	v_cmp_gt_u32_e32 vcc, 4, v54
	v_bitop3_b32 v56, v41, 15, v41 bitop3:0xc
	s_nop 0
	v_cndmask_b32_e32 v54, v55, v18, vcc
	v_cmp_eq_u32_e32 vcc, 2, v57
	v_bitop3_b32 v55, v41, s3, v41 bitop3:0xc
	s_nop 0
	v_cndmask_b32_e32 v58, v25, v23, vcc
	v_cmp_eq_u32_e32 vcc, 1, v57
	s_nop 1
	v_cndmask_b32_e32 v57, v58, v21, vcc
	v_cmp_gt_u32_e32 vcc, 64, v55
	s_nop 1
	v_cndmask_b32_e32 v55, v57, v19, vcc
	v_bfe_u32 v57, v42, 2, 2
	v_cmp_eq_u32_e32 vcc, 2, v57
	s_nop 1
	v_cndmask_b32_e32 v58, v24, v22, vcc
	v_cmp_eq_u32_e32 vcc, 1, v57
	s_nop 1
	v_cndmask_b32_e32 v57, v58, v20, vcc
; __device__ __forceinline__ void route_task(int task, int tl0, const bf16* QP  , const LAS bf16* KHL, LAS unsigned short* EL, LAS float* GL, int lane) {
;     const int r = lane & 31, hi = lane >> 5, t = 4 * task + (r >> 3), head = r & 7;
;     int top[2][16]; bf16x8 qa[2][4];
;     { unsigned qo = (unsigned)t * (unsigned)D + (unsigned)(head * 128 + 8 * hi); asm volatile("" : "+v"(qo)); const bf16* qp = QP + qo;
; #pragma unroll
;       for (int hf = 0; hf < 2; ++hf)
; #pragma unroll
;         for (int ks = 0; ks < 4; ++ks) qa[hf][ks] = ldg8(qp + 64 * hf + 16 * ks); }
; #pragma unroll
;     for (int half = 0; half < 2; ++half) {
;         int cur[16];
; #pragma unroll
;         for (int kt = 0; kt < 4; ++kt) {
;             f32x16 X;
; #pragma unroll
;             for (int i = 0; i < 16; ++i) X[i] = 8.f;
;             const LAS bf16* khp = KHL + (half * 128 + 32 * kt + r) * 72 + 8 * hi;
; #pragma unroll
;             for (int ks = 0; ks < 4; ++ks) {
;                 const bf16x8 kh = lds8(khp + 16 * ks);
;                 X = MFMA32(kh, qa[half][ks], X);
;     ...
;     for (int i = 0; i < 8; ++i) {
;         const unsigned cd = 255u - ((unsigned)my[i] & 255u), ca = cd >> 4, cb = cd & 15u;
;         const unsigned wa = (ca >> 2) == 0u ? P1[0] : (ca >> 2) == 1u ? P1[1] : (ca >> 2) == 2u ? P1[2] : P1[3];
;         const unsigned wb = (cb >> 2) == 0u ? P2[0] : (cb >> 2) == 1u ? P2[1] : (cb >> 2) == 2u ? P2[2] : P2[3];
;         bv[i] = (int)((((wa >> (8u * (ca & 3u))) & 255u) << 7) | ((wb >> (8u * (cb & 3u))) & 255u));
;     }
;     float e[8], se = 0.f;
; #pragma unroll
;     for (int i = 0; i < 8; ++i) { e[i] = __expf(__int_as_float(my[i]) - __int_as_float(bk[0])); se += e[i]; }
;     se += __shfl_xor(se, 32);
;     const float inv = 1.f / se;
;     {
;         int l2 = lane; asm volatile("" : "+v"(l2));
;         const int o2 = (tl0 + ((l2 & 31) >> 3)) * 128 + (l2 & 7) * 16 + 8 * (l2 >> 5);
;         LAS v4u* ip = (LAS v4u*)(EL + o2); typedef float f4v __attribute__((ext_vector_type(4))); LAS f4v* gp = (LAS f4v*)(GL + o2);
;         ip[0] = (v4u){(unsigned)bv[0] | ((unsigned)bv[1] << 16), (unsigned)bv[2] | ((unsigned)bv[3] << 16), (unsigned)bv[4] | ((unsigned)bv[5] << 16), (unsigned)bv[6] | ((unsigned)bv[7] << 16)};
;         gp[0] = (f4v){e[0] * inv, e[1] * inv, e[2] * inv, e[3] * inv}; gp[1] = (f4v){e[4] * inv, e[5] * inv, e[6] * inv, e[7] * inv};
;     }
; }
	v_cmp_gt_u32_e32 vcc, 4, v56
	v_bitop3_b32 v58, v34, 15, v34 bitop3:0xc
	s_nop 0
	v_cndmask_b32_e32 v56, v57, v18, vcc
	v_cmp_eq_u32_e32 vcc, 2, v59
	v_bitop3_b32 v57, v34, s3, v34 bitop3:0xc
	s_nop 0
	v_cndmask_b32_e32 v23, v25, v23, vcc
	v_cmp_eq_u32_e32 vcc, 1, v59
	v_sub_f32_e32 v25, v30, v32
	v_mul_f32_e32 v25, 0x3fb8aa3b, v25
	v_cndmask_b32_e32 v21, v23, v21, vcc
	v_cmp_gt_u32_e32 vcc, 64, v57
	v_lshrrev_b32_e32 v23, 1, v39
	v_and_b32_e32 v23, 24, v23
	v_cndmask_b32_e32 v19, v21, v19, vcc
	v_bfe_u32 v21, v43, 2, 2
	v_cmp_eq_u32_e32 vcc, 2, v21
	v_lshrrev_b32_e32 v23, v23, v51
	v_lshlrev_b32_e32 v23, 7, v23
	v_cndmask_b32_e32 v22, v24, v22, vcc
	v_cmp_eq_u32_e32 vcc, 1, v21
	v_lshrrev_b32_e32 v21, 1, v42
	v_and_b32_e32 v21, 24, v21
	v_cndmask_b32_e32 v20, v22, v20, vcc
	v_cmp_gt_u32_e32 vcc, 4, v58
	v_lshrrev_b32_e32 v21, v21, v55
	v_lshrrev_b32_e32 v22, 1, v40
	v_cndmask_b32_e32 v18, v20, v18, vcc
	v_lshlrev_b32_e32 v20, 3, v42
	v_lshlrev_b32_e32 v21, 7, v21
	v_and_b32_e32 v22, 24, v22
	v_lshrrev_b32_e32 v20, v20, v56
	v_and_b32_e32 v21, 0x7f80, v21
	v_lshrrev_b32_e32 v22, v22, v53
	v_and_or_b32 v21, v20, s3, v21
	v_lshlrev_b32_e32 v20, 3, v40
	v_lshlrev_b32_e32 v22, 7, v22
	v_lshrrev_b32_e32 v20, v20, v54
	v_and_b32_e32 v22, 0x7f80, v22
	v_and_or_b32 v20, v20, s3, v22
	v_lshlrev_b32_e32 v22, 3, v39
	v_lshrrev_b32_e32 v22, v22, v52
	v_and_b32_e32 v23, 0x7f80, v23
	v_and_or_b32 v39, v22, s3, v23
	v_lshrrev_b32_e32 v23, 1, v36
	v_and_b32_e32 v23, 24, v23
	v_lshrrev_b32_e32 v23, v23, v49
	v_lshlrev_b32_e32 v22, 3, v36
	v_lshlrev_b32_e32 v23, 7, v23
	v_lshrrev_b32_e32 v22, v22, v50
	v_and_b32_e32 v23, 0x7f80, v23
	v_and_or_b32 v36, v22, s3, v23
	v_lshrrev_b32_e32 v23, 1, v38
	v_and_b32_e32 v23, 24, v23
	v_lshrrev_b32_e32 v23, v23, v47
	v_lshlrev_b32_e32 v22, 3, v38
	v_lshlrev_b32_e32 v23, 7, v23
	v_lshrrev_b32_e32 v22, v22, v48
	v_and_b32_e32 v23, 0x7f80, v23
	v_and_or_b32 v38, v22, s3, v23
	v_lshrrev_b32_e32 v23, 1, v35
	v_and_b32_e32 v23, 24, v23
	v_lshrrev_b32_e32 v23, v23, v45
	v_lshlrev_b32_e32 v22, 3, v35
	v_lshlrev_b32_e32 v23, 7, v23
	v_lshrrev_b32_e32 v22, v22, v46
	v_and_b32_e32 v23, 0x7f80, v23
	v_and_or_b32 v35, v22, s3, v23
	v_lshrrev_b32_e32 v23, 1, v28
	v_and_b32_e32 v23, 24, v23
	v_lshrrev_b32_e32 v23, v23, v26
	v_lshlrev_b32_e32 v22, 3, v28
	v_lshlrev_b32_e32 v23, 7, v23
	v_lshrrev_b32_e32 v22, v22, v44
	v_and_b32_e32 v23, 0x7f80, v23
	v_and_or_b32 v40, v22, s3, v23
	v_sub_f32_e32 v22, v27, v32
	v_mul_f32_e32 v22, 0x3fb8aa3b, v22
	v_sub_f32_e32 v23, v31, v32
	v_exp_f32_e32 v22, v22
	v_mul_f32_e32 v23, 0x3fb8aa3b, v23
	v_sub_f32_e32 v24, v37, v32
	v_exp_f32_e32 v23, v23
	v_mul_f32_e32 v24, 0x3fb8aa3b, v24
	v_exp_f32_e32 v24, v24
	v_exp_f32_e32 v25, v25
	v_add_f32_e32 v26, 0, v22
	v_add_f32_e32 v26, v23, v26
	v_add_f32_e32 v26, v24, v26
	v_add_f32_e32 v30, v25, v26
	v_sub_f32_e32 v26, v33, v32
	v_mul_f32_e32 v26, 0x3fb8aa3b, v26
	v_sub_f32_e32 v27, v29, v32
	v_exp_f32_e32 v26, v26
	v_mul_f32_e32 v27, 0x3fb8aa3b, v27
	v_sub_f32_e32 v28, v41, v32
	v_exp_f32_e32 v27, v27
	v_mul_f32_e32 v28, 0x3fb8aa3b, v28
	v_sub_f32_e32 v29, v34, v32
	v_exp_f32_e32 v28, v28
	v_mul_f32_e32 v29, 0x3fb8aa3b, v29
	v_exp_f32_e32 v29, v29
	v_add_f32_e32 v30, v26, v30
	v_add_f32_e32 v30, v27, v30
	v_add_f32_e32 v30, v28, v30
	v_add_f32_e32 v30, v29, v30
	ds_bpermute_b32 v31, v123, v30
	v_lshrrev_b32_e32 v42, 1, v43
	v_and_b32_e32 v32, 24, v42
	v_lshrrev_b32_e32 v19, v32, v19
	v_lshlrev_b32_e32 v19, 7, v19
	s_waitcnt lgkmcnt(0)
	v_add_f32_e32 v30, v30, v31
	v_div_scale_f32 v31, s[12:13], v30, v30, 1.0
	v_rcp_f32_e32 v32, v31
	v_lshlrev_b32_e32 v33, 3, v43
	v_and_b32_e32 v19, 0x7f80, v19
	v_lshrrev_b32_e32 v18, v33, v18
	v_and_or_b32 v33, v18, s3, v19
	v_fma_f32 v18, -v31, v32, 1.0
	v_fmac_f32_e32 v32, v18, v32
	v_div_scale_f32 v18, vcc, 1.0, v30, 1.0
	v_mul_f32_e32 v19, v18, v32
	v_fma_f32 v34, -v31, v19, v18
	v_fmac_f32_e32 v19, v34, v32
	v_fma_f32 v18, -v31, v19, v18
	v_div_fmas_f32 v18, v18, v32, v19
	v_div_fixup_f32 v30, v18, v30, 1.0
	v_mov_b32_e32 v18, v1
	v_lshl_or_b32 v20, v20, 16, v39
	v_lshrrev_b32_e32 v19, 3, v18
	v_and_or_b32 v19, v19, 3, s55
	v_lshlrev_b32_e32 v31, 4, v18
	v_ashrrev_i32_e32 v18, 2, v18
	v_lshlrev_b32_e32 v19, 7, v19
	v_and_b32_e32 v31, 0x70, v31
	v_and_b32_e32 v18, -8, v18
	v_add3_u32 v18, v18, v31, v19
	v_lshl_add_u32 v31, v18, 1, s11
	v_lshl_add_u32 v32, v18, 2, s69
	v_lshl_or_b32 v18, v35, 16, v40
	v_lshl_or_b32 v19, v36, 16, v38
	v_lshl_or_b32 v21, v33, 16, v21
	ds_write_b128 v31, v[18:21]
	v_pk_mul_f32 v[20:21], v[24:25], v[30:31] op_sel_hi:[1,0]
	v_pk_mul_f32 v[18:19], v[22:23], v[30:31] op_sel_hi:[1,0]
	ds_write_b128 v32, v[18:21]
	v_pk_mul_f32 v[20:21], v[28:29], v[30:31] op_sel_hi:[1,0]
	v_pk_mul_f32 v[18:19], v[26:27], v[30:31] op_sel_hi:[1,0]
	ds_write_b128 v32, v[18:21] offset:16
	v_mov_b64_e32 v[32:33], s[30:31]
	v_lshl_add_u64 v[128:129], v[82:83], 1, s[80:81]
	global_load_dwordx4 v[78:81], v[128:129], off
	global_load_dwordx4 v[74:77], v[128:129], off offset:32
	global_load_dwordx4 v[70:73], v[128:129], off offset:64
	global_load_dwordx4 v[66:69], v[128:129], off offset:96
	ds_read_b128 v[50:53], v94
	ds_read_b128 v[54:57], v94 offset:32
	v_mov_b64_e32 v[30:31], s[28:29]
	v_mov_b64_e32 v[28:29], s[26:27]
	v_mov_b64_e32 v[26:27], s[24:25]
	v_mov_b64_e32 v[24:25], s[22:23]
	v_mov_b64_e32 v[22:23], s[20:21]
	v_mov_b64_e32 v[20:21], s[18:19]
	v_mov_b64_e32 v[18:19], s[16:17]
	s_waitcnt vmcnt(3) lgkmcnt(1)
	s_nop 0
	v_mfma_f32_32x32x16_bf16 v[34:49], v[50:53], v[78:81], v[18:33]
	ds_read_b128 v[50:53], v94 offset:64
	ds_read_b128 v[124:127], v94 offset:96
	s_waitcnt vmcnt(2) lgkmcnt(2)
; #define LAS __attribute__((address_space(3)))
; #define MFMA32(a, b, c) __builtin_amdgcn_mfma_f32_32x32x16_bf16((a), (b), (c), 0, 0, 0)
; __device__ __forceinline__ void route_task(int task, int tl0, const bf16* QP  , const LAS bf16* KHL, LAS unsigned short* EL, LAS float* GL, int lane) {
;     ...
;     { unsigned qo = (unsigned)t * (unsigned)D + (unsigned)(head * 128 + 8 * hi); asm volatile("" : "+v"(qo)); const bf16* qp = QP + qo;
; #pragma unroll
;       for (int hf = 0; hf < 2; ++hf)
; #pragma unroll
;         for (int ks = 0; ks < 4; ++ks) qa[hf][ks] = ldg8(qp + 64 * hf + 16 * ks); }
; #pragma unroll
;     for (int half = 0; half < 2; ++half) {
;         int cur[16];
; #pragma unroll
;         for (int kt = 0; kt < 4; ++kt) {
;             f32x16 X;
; #pragma unroll
;             for (int i = 0; i < 16; ++i) X[i] = 8.f;
;             const LAS bf16* khp = KHL + (half * 128 + 32 * kt + r) * 72 + 8 * hi;
; #pragma unroll
;             for (int ks = 0; ks < 4; ++ks) {
;                 const bf16x8 kh = lds8(khp + 16 * ks);
;                 X = MFMA32(kh, qa[half][ks], X);
;             }
;             int grp[16];
; #pragma unroll
;             for (int i = 0; i < 16; ++i) grp[i] = (int)((__float_as_uint(X[i]) | 127u) - (unsigned)(32 * kt + (i & 3) + 8 * (i >> 2)));
;             sort16_desc(grp);
;             if (kt == 0) {
; #pragma unroll
;                 for (int i = 0; i < 16; ++i) cur[i] = grp[i];
;             } else merge16_desc(cur, grp);
	v_mfma_f32_32x32x16_bf16 v[34:49], v[54:57], v[74:77], v[34:49]
	s_waitcnt vmcnt(1) lgkmcnt(1)
	v_mfma_f32_32x32x16_bf16 v[34:49], v[50:53], v[70:73], v[34:49]
	global_load_dwordx4 v[62:65], v[128:129], off offset:128
	global_load_dwordx4 v[58:61], v[128:129], off offset:160
	global_load_dwordx4 v[54:57], v[128:129], off offset:192
	global_load_dwordx4 v[50:53], v[128:129], off offset:224
	s_waitcnt vmcnt(4) lgkmcnt(0)
	v_mfma_f32_32x32x16_bf16 v[34:49], v[124:127], v[66:69], v[34:49]
	s_nop 11
	v_bitop3_b32 v37, v37, s42, 3 bitop3:0x56
	v_bitop3_b32 v48, v48, s42, 26 bitop3:0x56
	v_bitop3_b32 v38, v38, s42, 8 bitop3:0x56
	v_bitop3_b32 v42, v42, s42, 16 bitop3:0x56
	v_bitop3_b32 v47, v47, s42, 25 bitop3:0x56
	v_bitop3_b32 v39, v39, s42, 9 bitop3:0x56
	v_bitop3_b32 v40, v40, s42, 10 bitop3:0x56
	v_bitop3_b32 v43, v43, s42, 17 bitop3:0x56
	v_bitop3_b32 v44, v44, s42, 18 bitop3:0x56
	v_bitop3_b32 v36, v36, s42, 2 bitop3:0x56
	v_bitop3_b32 v49, v49, s42, 27 bitop3:0x56
	v_bitop3_b32 v41, v41, s42, 11 bitop3:0x56
	v_bitop3_b32 v45, v45, s42, 19 bitop3:0x56
	v_bitop3_b32 v35, v35, s42, 1 bitop3:0x56
	v_bitop3_b32 v46, v46, s42, 24 bitop3:0x56
	v_or_b32_e32 v34, 0x7f, v34
	v_max_i32_e32 v82, v37, v48
	v_max_i32_e32 v124, v38, v42
	v_max_i32_e32 v126, v34, v47
	v_max_i32_e32 v127, v39, v40
	v_min_i32_e32 v130, v43, v44
	v_min_i32_e32 v131, v36, v49
	v_min_i32_e32 v133, v41, v45
	v_min_i32_e32 v134, v35, v46
	v_min_i32_e32 v39, v39, v40
	v_min_i32_e32 v34, v34, v47
	v_min_i32_e32 v38, v38, v42
	v_min_i32_e32 v37, v37, v48
	v_max_i32_e32 v35, v35, v46
	v_max_i32_e32 v41, v41, v45
	v_max_i32_e32 v36, v36, v49
	v_max_i32_e32 v43, v43, v44
	v_min_i32_e32 v125, v82, v124
	v_min_i32_e32 v128, v126, v127
	v_max_i32_e32 v132, v130, v131
	v_max_i32_e32 v135, v133, v134
	v_max_i32_e32 v40, v39, v34
	v_max_i32_e32 v42, v38, v37
	v_min_i32_e32 v45, v35, v41
	v_min_i32_e32 v44, v36, v43
	v_min_i32_e32 v129, v125, v128
	v_max_i32_e32 v47, v40, v42
	v_max_i32_e32 v46, v45, v44
	v_min_i32_e32 v40, v40, v42
	v_min_i32_e32 v42, v45, v44
	v_max_i32_e32 v45, v125, v128
	v_max_i32_e32 v125, v132, v135
	v_min_i32_e32 v128, v45, v125
	v_min_i32_e32 v34, v39, v34
	v_max_i32_e32 v39, v126, v127
	v_max_i32_e32 v35, v35, v41
	v_max_i32_e32 v41, v82, v124
	v_max_i32_e32 v148, v45, v125
	ds_read_b128 v[124:127], v95
	v_max_i32_e32 v44, v40, v42
	v_min_i32_e32 v138, v40, v42
	v_min_i32_e32 v40, v133, v134
	v_min_i32_e32 v37, v38, v37
	v_min_i32_e32 v38, v130, v131
	v_max_i32_e32 v36, v36, v43
	v_min_i32_e32 v136, v132, v135
	v_min_i32_e32 v133, v40, v34
	v_min_i32_e32 v134, v37, v38
	v_max_i32_e32 v34, v40, v34
	v_max_i32_e32 v37, v37, v38
	v_min_i32_e32 v40, v39, v35
	v_min_i32_e32 v42, v36, v41
	v_max_i32_e32 v144, v39, v35
	v_max_i32_e32 v145, v36, v41
	v_max_i32_e32 v137, v129, v136
	v_min_i32_e32 v136, v129, v136
	v_max_i32_e32 v140, v133, v134
	v_min_i32_e32 v141, v34, v37
	v_max_i32_e32 v143, v40, v42
	v_min_i32_e32 v146, v144, v145
	v_max_i32_e32 v149, v47, v46
	v_min_i32_e32 v48, v47, v46
	v_max_i32_e32 v139, v138, v136
	v_max_i32_e32 v142, v140, v141
	v_min_i32_e32 v43, v40, v42
	v_max_i32_e32 v34, v34, v37
	v_min_i32_e32 v147, v143, v146
	v_min_i32_e32 v150, v148, v149
	v_min_i32_e32 v49, v137, v48
	v_min_i32_e32 v132, v44, v128
	v_max_i32_e32 v38, v139, v142
	v_min_i32_e32 v37, v43, v34
	v_max_i32_e32 v34, v43, v34
	v_min_i32_e32 v35, v147, v150
	v_max_i32_e32 v39, v137, v48
	v_max_i32_e32 v40, v44, v128
	v_max_i32_e32 v135, v49, v132
	v_max_i32_e32 v82, v38, v37
	v_min_i32_e32 v36, v34, v35
	v_min_i32_e32 v41, v39, v40
	v_max_i32_e32 v129, v135, v82
	v_min_i32_e32 v42, v36, v41
	v_min_i32_e32 v137, v129, v42
	v_max_i32_e32 v159, v129, v42
	ds_read_b128 v[128:131], v95 offset:32
	v_min_i32_e32 v82, v135, v82
	v_min_i32_e32 v132, v49, v132
	v_min_i32_e32 v135, v38, v37
	v_max_i32_e32 v154, v34, v35
	v_max_i32_e32 v155, v39, v40
	v_max_i32_e32 v157, v36, v41
	s_waitcnt lgkmcnt(1)
	v_mfma_f32_32x32x16_bf16 v[34:49], v[124:127], v[78:81], v[18:33]
	ds_read_b128 v[124:127], v95 offset:64
	v_max_i32_e32 v151, v132, v135
	v_max_i32_e32 v152, v82, v151
	v_min_i32_e32 v136, v138, v136
	v_min_i32_e32 v138, v140, v141
	v_min_i32_e32 v82, v82, v151
	v_max_i32_e32 v147, v147, v150
	s_waitcnt lgkmcnt(1)
	v_mfma_f32_32x32x16_bf16 v[34:49], v[128:131], v[74:77], v[34:49]
	ds_read_b128 v[128:131], v95 offset:96
	v_max_i32_e32 v143, v143, v146
	v_min_i32_e32 v133, v133, v134
	v_min_i32_e32 v156, v154, v155
	v_max_i32_e32 v140, v136, v138
	v_min_i32_e32 v139, v139, v142
	v_max_i32_e32 v142, v154, v155
	s_waitcnt lgkmcnt(1)
	v_mfma_f32_32x32x16_bf16 v[34:49], v[124:127], v[70:73], v[34:49]
	v_max_i32_e32 v124, v148, v149
	v_min_i32_e32 v136, v136, v138
	v_max_i32_e32 v141, v140, v139
	v_min_i32_e32 v139, v140, v139
	v_min_i32_e32 v125, v143, v124
	v_min_i32_e32 v158, v156, v157
	v_min_i32_e32 v132, v132, v135
	s_waitcnt lgkmcnt(0)
; #define LAS __attribute__((address_space(3)))
; #define MFMA32(a, b, c) __builtin_amdgcn_mfma_f32_32x32x16_bf16((a), (b), (c), 0, 0, 0)
; __device__ __forceinline__ void route_task(int task, int tl0, const bf16* QP  , const LAS bf16* KHL, LAS unsigned short* EL, LAS float* GL, int lane) {
;     ...
; #pragma unroll
;             for (int i = 0; i < 16; ++i) X[i] = 8.f;
;             const LAS bf16* khp = KHL + (half * 128 + 32 * kt + r) * 72 + 8 * hi;
; #pragma unroll
;             for (int ks = 0; ks < 4; ++ks) {
;                 const bf16x8 kh = lds8(khp + 16 * ks);
;                 X = MFMA32(kh, qa[half][ks], X);
;             }
;             int grp[16];
; #pragma unroll
;             for (int i = 0; i < 16; ++i) grp[i] = (int)((__float_as_uint(X[i]) | 127u) - (unsigned)(32 * kt + (i & 3) + 8 * (i >> 2)));
;             sort16_desc(grp);
;             if (kt == 0) {
; #pragma unroll
;                 for (int i = 0; i < 16; ++i) cur[i] = grp[i];
;             } else merge16_desc(cur, grp);
	v_mfma_f32_32x32x16_bf16 v[34:49], v[128:131], v[66:69], v[34:49]
	v_min_i32_e32 v126, v147, v125
	v_min_i32_e32 v153, v137, v152
	v_min_i32_e32 v160, v158, v159
	v_min_i32_e32 v135, v141, v132
	v_min_i32_e32 v127, v142, v126
	s_nop 6
	v_bitop3_b32 v37, v37, s42, 35 bitop3:0x56
	v_bitop3_b32 v48, v48, s42, 58 bitop3:0x56
	v_bitop3_b32 v38, v38, s42, 40 bitop3:0x56
	v_bitop3_b32 v42, v42, s42, 48 bitop3:0x56
	v_bitop3_b32 v34, v34, s42, 32 bitop3:0x56
	v_bitop3_b32 v47, v47, s42, 57 bitop3:0x56
	v_bitop3_b32 v39, v39, s42, 41 bitop3:0x56
	v_bitop3_b32 v40, v40, s42, 42 bitop3:0x56
	v_bitop3_b32 v43, v43, s42, 49 bitop3:0x56
	v_bitop3_b32 v44, v44, s42, 50 bitop3:0x56
	v_bitop3_b32 v36, v36, s42, 34 bitop3:0x56
	v_bitop3_b32 v49, v49, s42, 59 bitop3:0x56
	v_bitop3_b32 v41, v41, s42, 43 bitop3:0x56
	v_bitop3_b32 v45, v45, s42, 51 bitop3:0x56
	v_bitop3_b32 v35, v35, s42, 33 bitop3:0x56
	v_bitop3_b32 v46, v46, s42, 56 bitop3:0x56
	v_max_i32_e32 v128, v37, v48
	v_max_i32_e32 v129, v38, v42
	v_max_i32_e32 v131, v34, v47
	v_max_i32_e32 v134, v39, v40
	v_min_i32_e32 v146, v43, v44
	v_min_i32_e32 v148, v36, v49
	v_min_i32_e32 v150, v41, v45
	v_min_i32_e32 v151, v35, v46
	v_min_i32_e32 v39, v39, v40
	v_min_i32_e32 v34, v34, v47
	v_min_i32_e32 v38, v38, v42
	v_min_i32_e32 v37, v37, v48
	v_max_i32_e32 v35, v35, v46
	v_max_i32_e32 v41, v41, v45
	v_max_i32_e32 v36, v36, v49
	v_max_i32_e32 v43, v43, v44
	v_min_i32_e32 v130, v128, v129
	v_min_i32_e32 v138, v131, v134
	v_max_i32_e32 v149, v146, v148
	v_max_i32_e32 v154, v150, v151
	v_max_i32_e32 v40, v39, v34
	v_max_i32_e32 v42, v38, v37
	v_min_i32_e32 v45, v35, v41
	v_min_i32_e32 v44, v36, v43
	v_min_i32_e32 v150, v150, v151
	v_min_i32_e32 v34, v39, v34
	v_min_i32_e32 v37, v38, v37
	v_min_i32_e32 v38, v146, v148
	v_max_i32_e32 v131, v131, v134
	v_max_i32_e32 v35, v35, v41
	v_max_i32_e32 v36, v36, v43
	v_max_i32_e32 v43, v128, v129
	v_min_i32_e32 v140, v130, v138
	v_min_i32_e32 v155, v149, v154
	v_max_i32_e32 v47, v40, v42
	v_max_i32_e32 v46, v45, v44
	v_min_i32_e32 v40, v40, v42
	v_min_i32_e32 v42, v45, v44
	v_max_i32_e32 v45, v130, v138
	v_max_i32_e32 v130, v149, v154
	v_min_i32_e32 v39, v150, v34
	v_min_i32_e32 v146, v37, v38
	v_max_i32_e32 v34, v150, v34
	v_max_i32_e32 v37, v37, v38
	v_min_i32_e32 v41, v131, v35
	v_min_i32_e32 v128, v36, v43
	v_max_i32_e32 v35, v131, v35
	v_max_i32_e32 v36, v36, v43
	v_min_i32_e32 v48, v47, v46
	v_max_i32_e32 v44, v40, v42
	v_min_i32_e32 v138, v45, v130
	v_min_i32_e32 v40, v40, v42
	v_min_i32_e32 v42, v140, v155
	v_max_i32_e32 v148, v39, v146
	v_min_i32_e32 v38, v34, v37
	v_min_i32_e32 v129, v41, v128
	v_max_i32_e32 v41, v41, v128
	v_min_i32_e32 v43, v35, v36
	v_max_i32_e32 v45, v45, v130
	v_max_i32_e32 v46, v47, v46
	v_max_i32_e32 v161, v140, v155
	v_max_i32_e32 v140, v40, v42
	v_max_i32_e32 v150, v148, v38
	v_max_i32_e32 v34, v34, v37
	v_min_i32_e32 v128, v41, v43
	v_min_i32_e32 v47, v45, v46
	v_min_i32_e32 v49, v161, v48
	v_min_i32_e32 v149, v44, v138
	v_max_i32_e32 v151, v140, v150
	v_min_i32_e32 v37, v129, v34
	v_max_i32_e32 v34, v129, v34
	v_min_i32_e32 v129, v128, v47
	v_max_i32_e32 v48, v161, v48
	v_max_i32_e32 v44, v44, v138
	v_max_i32_e32 v154, v49, v149
	v_max_i32_e32 v134, v151, v37
	v_min_i32_e32 v130, v34, v129
	v_min_i32_e32 v131, v48, v44
	v_min_i32_e32 v49, v49, v149
	v_min_i32_e32 v37, v151, v37
	v_max_i32_e32 v34, v34, v129
	v_max_i32_e32 v44, v48, v44
	v_min_i32_e32 v40, v40, v42
	v_min_i32_e32 v38, v148, v38
	v_max_i32_e32 v41, v41, v43
	v_max_i32_e32 v43, v45, v46
	v_max_i32_e32 v155, v154, v134
	v_min_i32_e32 v138, v130, v131
	v_min_i32_e32 v134, v154, v134
	v_max_i32_e32 v149, v49, v37
	v_min_i32_e32 v48, v34, v44
	v_max_i32_e32 v129, v130, v131
	v_max_i32_e32 v42, v40, v38
	v_min_i32_e32 v140, v140, v150
	v_max_i32_e32 v34, v34, v44
	v_max_i32_e32 v44, v128, v47
	v_min_i32_e32 v45, v41, v43
	v_min_i32_e32 v161, v155, v138
	v_max_i32_e32 v151, v134, v149
	v_min_i32_e32 v130, v48, v129
	v_max_i32_e32 v131, v155, v138
	v_max_i32_e32 v148, v42, v140
	v_min_i32_e32 v37, v49, v37
	v_min_i32_e32 v46, v44, v45
	v_min_i32_e32 v154, v161, v151
	v_min_i32_e32 v138, v130, v131
	v_min_i32_e32 v49, v148, v37
	v_min_i32_e32 v134, v134, v149
	v_min_i32_e32 v47, v34, v46
	v_min_i32_e32 v42, v42, v140
	v_min_i32_e32 v38, v40, v38
	v_min_i32_e32 v39, v39, v146
	v_max3_i32 v39, v144, v145, v39
	v_max3_i32 v38, v143, v124, v38
	v_max3_i32 v40, v147, v125, v42
	v_max3_i32 v42, v142, v126, v49
	v_max3_i32 v37, v127, v148, v37
	v_max3_i32 v49, v156, v157, v134
	v_max3_i32 v124, v158, v159, v154
	v_max3_i32 v125, v160, v161, v151
	v_max3_i32 v126, v137, v152, v138
	v_max3_i32 v127, v153, v130, v131
	v_max3_i32 v48, v82, v48, v129
	v_max3_i32 v47, v141, v132, v47
	v_max3_i32 v34, v135, v34, v46
	v_max3_i32 v44, v139, v44, v45
	v_max3_i32 v41, v136, v41, v43
	v_max3_i32 v35, v133, v35, v36
	v_max_i32_e32 v36, v39, v126
	v_min_i32_e32 v39, v39, v126
	v_max_i32_e32 v43, v38, v127
	v_min_i32_e32 v38, v38, v127
	v_max_i32_e32 v45, v40, v48
	v_min_i32_e32 v40, v40, v48
	v_max_i32_e32 v46, v42, v47
	v_min_i32_e32 v42, v42, v47
	v_max_i32_e32 v47, v37, v34
	v_min_i32_e32 v34, v37, v34
	v_max_i32_e32 v37, v49, v44
	v_min_i32_e32 v44, v49, v44
	v_max_i32_e32 v48, v124, v41
	v_min_i32_e32 v41, v124, v41
	v_max_i32_e32 v49, v125, v35
	v_min_i32_e32 v35, v125, v35
	ds_read_b128 v[124:127], v94 offset:9216
	ds_read_b128 v[128:131], v94 offset:9248
	v_max_i32_e32 v82, v36, v47
	v_min_i32_e32 v132, v36, v47
	v_max_i32_e32 v36, v43, v37
	v_min_i32_e32 v133, v43, v37
	v_max_i32_e32 v37, v45, v48
	v_max_i32_e32 v43, v46, v49
	v_min_i32_e32 v134, v45, v48
	v_min_i32_e32 v135, v46, v49
	v_max_i32_e32 v136, v39, v34
	v_min_i32_e32 v137, v39, v34
	v_max_i32_e32 v138, v38, v44
	v_min_i32_e32 v139, v38, v44
	v_max_i32_e32 v140, v40, v41
	v_min_i32_e32 v141, v40, v41
	v_max_i32_e32 v142, v42, v35
	v_min_i32_e32 v143, v42, v35
	v_max_i32_e32 v144, v82, v37
	v_min_i32_e32 v82, v82, v37
	v_max_i32_e32 v145, v36, v43
	v_min_i32_e32 v146, v36, v43
	s_waitcnt lgkmcnt(1)
; #define LAS __attribute__((address_space(3)))
; #define MFMA32(a, b, c) __builtin_amdgcn_mfma_f32_32x32x16_bf16((a), (b), (c), 0, 0, 0)
; __device__ __forceinline__ void route_task(int task, int tl0, const bf16* QP  , const LAS bf16* KHL, LAS unsigned short* EL, LAS float* GL, int lane) {
;     ...
; #pragma unroll
;             for (int i = 0; i < 16; ++i) X[i] = 8.f;
;             const LAS bf16* khp = KHL + (half * 128 + 32 * kt + r) * 72 + 8 * hi;
; #pragma unroll
;             for (int ks = 0; ks < 4; ++ks) {
;                 const bf16x8 kh = lds8(khp + 16 * ks);
;                 X = MFMA32(kh, qa[half][ks], X);
;             }
;             int grp[16];
; #pragma unroll
;             for (int i = 0; i < 16; ++i) grp[i] = (int)((__float_as_uint(X[i]) | 127u) - (unsigned)(32 * kt + (i & 3) + 8 * (i >> 2)));
;             sort16_desc(grp);
;             if (kt == 0) {
; #pragma unroll
;                 for (int i = 0; i < 16; ++i) cur[i] = grp[i];
;             } else merge16_desc(cur, grp);
	v_mfma_f32_32x32x16_bf16 v[34:49], v[124:127], v[78:81], v[18:33]
	ds_read_b128 v[124:127], v94 offset:9280
	v_max_i32_e32 v147, v132, v134
	v_min_i32_e32 v132, v132, v134
	v_max_i32_e32 v134, v133, v135
	v_min_i32_e32 v133, v133, v135
	v_max_i32_e32 v135, v136, v140
	v_min_i32_e32 v136, v136, v140
	s_waitcnt lgkmcnt(1)
	v_mfma_f32_32x32x16_bf16 v[34:49], v[128:131], v[74:77], v[34:49]
	ds_read_b128 v[128:131], v94 offset:9312
	v_max_i32_e32 v140, v138, v142
	v_min_i32_e32 v138, v138, v142
	v_max_i32_e32 v142, v137, v141
	v_min_i32_e32 v137, v137, v141
	v_max_i32_e32 v141, v139, v143
	v_min_i32_e32 v139, v139, v143
	s_waitcnt lgkmcnt(1)
	v_mfma_f32_32x32x16_bf16 v[34:49], v[124:127], v[70:73], v[34:49]
	v_min_i32_e32 v143, v144, v145
	v_min_i32_e32 v124, v82, v146
	v_min_i32_e32 v127, v135, v140
	v_min_i32_e32 v125, v147, v134
	v_min_i32_e32 v126, v132, v133
	v_min_i32_e32 v149, v142, v141
	v_min_i32_e32 v148, v136, v138
	s_waitcnt lgkmcnt(0)
	v_mfma_f32_32x32x16_bf16 v[34:49], v[128:131], v[66:69], v[34:49]
	v_min_i32_e32 v150, v137, v139
	s_nop 10
	v_and_or_b32 v37, v37, s43, 60
	v_and_or_b32 v48, v48, s43, 37
	v_and_or_b32 v38, v38, s43, 55
	v_and_or_b32 v42, v42, s43, 47
	v_bitop3_b32 v34, v34, s42, 64 bitop3:0x56
	v_and_or_b32 v47, v47, s43, 38
	v_and_or_b32 v39, v39, s43, 54
	v_and_or_b32 v40, v40, s43, 53
	v_and_or_b32 v43, v43, s43, 46
	v_and_or_b32 v44, v44, s43, 45
	v_and_or_b32 v36, v36, s43, 61
	v_and_or_b32 v49, v49, s43, 36
	v_and_or_b32 v41, v41, s43, 52
	v_and_or_b32 v45, v45, s43, 44
	v_and_or_b32 v35, v35, s43, 62
	v_and_or_b32 v46, v46, s43, 39
	v_max_i32_e32 v128, v37, v48
	v_max_i32_e32 v129, v38, v42
	v_max_i32_e32 v131, v34, v47
	v_max_i32_e32 v151, v39, v40
	v_min_i32_e32 v154, v43, v44
	v_min_i32_e32 v155, v36, v49
	v_min_i32_e32 v157, v41, v45
	v_min_i32_e32 v158, v35, v46
	v_min_i32_e32 v39, v39, v40
	v_min_i32_e32 v34, v34, v47
	v_min_i32_e32 v38, v38, v42
	v_min_i32_e32 v37, v37, v48
	v_max_i32_e32 v35, v35, v46
	v_max_i32_e32 v41, v41, v45
	v_max_i32_e32 v36, v36, v49
	v_max_i32_e32 v43, v43, v44
	v_min_i32_e32 v130, v128, v129
	v_min_i32_e32 v152, v131, v151
	v_max_i32_e32 v156, v154, v155
	v_max_i32_e32 v159, v157, v158
	v_max_i32_e32 v40, v39, v34
	v_max_i32_e32 v42, v38, v37
	v_min_i32_e32 v45, v35, v41
	v_min_i32_e32 v44, v36, v43
	v_min_i32_e32 v157, v157, v158
	v_min_i32_e32 v34, v39, v34
	v_min_i32_e32 v37, v38, v37
	v_min_i32_e32 v38, v154, v155
	v_max_i32_e32 v131, v131, v151
	v_max_i32_e32 v35, v35, v41
	v_max_i32_e32 v36, v36, v43
	v_max_i32_e32 v43, v128, v129
	v_min_i32_e32 v153, v130, v152
	v_min_i32_e32 v160, v156, v159
	v_max_i32_e32 v47, v40, v42
	v_max_i32_e32 v46, v45, v44
	v_min_i32_e32 v40, v40, v42
	v_min_i32_e32 v42, v45, v44
	v_max_i32_e32 v45, v130, v152
	v_max_i32_e32 v130, v156, v159
	v_min_i32_e32 v39, v157, v34
	v_min_i32_e32 v154, v37, v38
	v_max_i32_e32 v34, v157, v34
	v_max_i32_e32 v37, v37, v38
	v_min_i32_e32 v41, v131, v35
	v_min_i32_e32 v128, v36, v43
	v_max_i32_e32 v35, v131, v35
	v_max_i32_e32 v36, v36, v43
	v_min_i32_e32 v48, v47, v46
	v_max_i32_e32 v44, v40, v42
	v_min_i32_e32 v152, v45, v130
	v_min_i32_e32 v40, v40, v42
	v_min_i32_e32 v42, v153, v160
	v_max_i32_e32 v155, v39, v154
	v_min_i32_e32 v38, v34, v37
	v_min_i32_e32 v129, v41, v128
	v_max_i32_e32 v41, v41, v128
	v_min_i32_e32 v43, v35, v36
	v_max_i32_e32 v45, v45, v130
	v_max_i32_e32 v46, v47, v46
	v_max_i32_e32 v161, v153, v160
	v_max_i32_e32 v153, v40, v42
	v_max_i32_e32 v157, v155, v38
	v_max_i32_e32 v34, v34, v37
	v_min_i32_e32 v128, v41, v43
	v_min_i32_e32 v47, v45, v46
	v_min_i32_e32 v49, v161, v48
	v_min_i32_e32 v156, v44, v152
	v_max_i32_e32 v158, v153, v157
	v_min_i32_e32 v37, v129, v34
	v_max_i32_e32 v34, v129, v34
	v_min_i32_e32 v129, v128, v47
	v_max_i32_e32 v48, v161, v48
	v_max_i32_e32 v44, v44, v152
	v_min_i32_e32 v40, v40, v42
	v_min_i32_e32 v38, v155, v38
	v_max_i32_e32 v159, v49, v156
	v_max_i32_e32 v151, v158, v37
	v_min_i32_e32 v130, v34, v129
	v_min_i32_e32 v131, v48, v44
	v_min_i32_e32 v49, v49, v156
	v_min_i32_e32 v37, v158, v37
	v_max_i32_e32 v34, v34, v129
	v_max_i32_e32 v44, v48, v44
	v_max_i32_e32 v42, v40, v38
	v_min_i32_e32 v153, v153, v157
	v_max_i32_e32 v160, v159, v151
	v_min_i32_e32 v152, v130, v131
	v_max_i32_e32 v156, v49, v37
	v_min_i32_e32 v48, v34, v44
	v_max_i32_e32 v129, v130, v131
	v_max_i32_e32 v155, v42, v153
	v_min_i32_e32 v37, v49, v37
	v_min_i32_e32 v151, v159, v151
	v_min_i32_e32 v130, v48, v129
	v_max_i32_e32 v131, v160, v152
	v_min_i32_e32 v49, v155, v37
	v_max_i32_e32 v41, v41, v43
	v_max_i32_e32 v43, v45, v46
	v_min_i32_e32 v42, v42, v153
	v_min_i32_e32 v38, v40, v38
	v_min_i32_e32 v161, v160, v152
	v_max_i32_e32 v158, v151, v156
	v_min_i32_e32 v151, v151, v156
	v_max_i32_e32 v34, v34, v44
	v_max_i32_e32 v44, v128, v47
	v_min_i32_e32 v45, v41, v43
	v_max_i32_e32 v40, v41, v43
	v_max_i32_e32 v38, v143, v38
	v_max3_i32 v41, v82, v146, v42
	v_max_i32_e32 v42, v124, v49
	v_max3_i32 v124, v127, v130, v131
	v_min_i32_e32 v46, v44, v45
	v_max_i32_e32 v43, v125, v151
	v_max3_i32 v49, v126, v161, v158
	v_max3_i32 v44, v149, v44, v45
	v_max_i32_e32 v45, v38, v124
	v_min_i32_e32 v38, v38, v124
	ds_read_b128 v[124:127], v96
	v_min_i32_e32 v159, v161, v158
	v_min_i32_e32 v152, v130, v131
	v_max_i32_e32 v37, v155, v37
	v_max_i32_e32 v48, v48, v129
	v_min_i32_e32 v47, v34, v46
	v_max_i32_e32 v34, v34, v46
	v_min_i32_e32 v39, v39, v154
	v_max3_i32 v39, v144, v145, v39
	v_max3_i32 v37, v147, v134, v37
	v_max3_i32 v46, v132, v133, v159
	v_max3_i32 v82, v135, v140, v152
	v_max3_i32 v48, v136, v138, v48
	v_max_i32_e32 v47, v148, v47
	v_max3_i32 v34, v142, v141, v34
	v_max3_i32 v40, v137, v139, v40
	v_max3_i32 v35, v150, v35, v36
	v_max_i32_e32 v36, v39, v82
	v_min_i32_e32 v39, v39, v82
	v_max_i32_e32 v82, v41, v48
	v_min_i32_e32 v41, v41, v48
	v_max_i32_e32 v48, v42, v47
	v_min_i32_e32 v42, v42, v47
	v_max_i32_e32 v47, v37, v34
	v_min_i32_e32 v34, v37, v34
	v_max_i32_e32 v37, v43, v44
	v_min_i32_e32 v43, v43, v44
	v_max_i32_e32 v44, v46, v40
	v_min_i32_e32 v40, v46, v40
	v_max_i32_e32 v46, v49, v35
	v_min_i32_e32 v35, v49, v35
	v_max_i32_e32 v49, v36, v47
	v_min_i32_e32 v132, v36, v47
	v_max_i32_e32 v36, v45, v37
	v_min_i32_e32 v133, v45, v37
	v_max_i32_e32 v37, v82, v44
	v_min_i32_e32 v82, v82, v44
	v_max_i32_e32 v44, v48, v46
	ds_read_b128 v[128:131], v96 offset:32
	v_min_i32_e32 v134, v48, v46
	v_max_i32_e32 v135, v39, v34
	v_min_i32_e32 v136, v39, v34
	v_max_i32_e32 v137, v38, v43
	v_min_i32_e32 v138, v38, v43
	v_max_i32_e32 v139, v41, v40
	v_min_i32_e32 v140, v41, v40
	v_max_i32_e32 v141, v42, v35
	v_min_i32_e32 v142, v42, v35
	v_max_i32_e32 v143, v49, v37
	v_min_i32_e32 v144, v49, v37
	v_max_i32_e32 v145, v36, v44
	v_min_i32_e32 v146, v36, v44
	s_waitcnt lgkmcnt(1)
; #define LAS __attribute__((address_space(3)))
; #define MFMA32(a, b, c) __builtin_amdgcn_mfma_f32_32x32x16_bf16((a), (b), (c), 0, 0, 0)
; __device__ __forceinline__ void route_task(int task, int tl0, const bf16* QP  , const LAS bf16* KHL, LAS unsigned short* EL, LAS float* GL, int lane) {
;     ...
; #pragma unroll
;             for (int i = 0; i < 16; ++i) X[i] = 8.f;
;             const LAS bf16* khp = KHL + (half * 128 + 32 * kt + r) * 72 + 8 * hi;
; #pragma unroll
;             for (int ks = 0; ks < 4; ++ks) {
;                 const bf16x8 kh = lds8(khp + 16 * ks);
;                 X = MFMA32(kh, qa[half][ks], X);
;             }
;             int grp[16];
; #pragma unroll
;             for (int i = 0; i < 16; ++i) grp[i] = (int)((__float_as_uint(X[i]) | 127u) - (unsigned)(32 * kt + (i & 3) + 8 * (i >> 2)));
;             sort16_desc(grp);
;             if (kt == 0) {
; #pragma unroll
;                 for (int i = 0; i < 16; ++i) cur[i] = grp[i];
;             } else merge16_desc(cur, grp);
	v_mfma_f32_32x32x16_bf16 v[34:49], v[124:127], v[78:81], v[18:33]
	ds_read_b128 v[78:81], v96 offset:64
	v_max_i32_e32 v147, v132, v82
	v_min_i32_e32 v82, v132, v82
	v_max_i32_e32 v132, v137, v141
	v_max_i32_e32 v124, v133, v134
	v_min_i32_e32 v125, v133, v134
	v_max_i32_e32 v126, v135, v139
	s_waitcnt lgkmcnt(1)
	v_mfma_f32_32x32x16_bf16 v[34:49], v[128:131], v[74:77], v[34:49]
	ds_read_b128 v[74:77], v96 offset:96
	v_min_i32_e32 v128, v137, v141
	v_max_i32_e32 v129, v136, v140
	v_min_i32_e32 v130, v136, v140
	v_min_i32_e32 v127, v135, v139
	v_max_i32_e32 v131, v138, v142
	v_min_i32_e32 v133, v138, v142
	s_waitcnt lgkmcnt(1)
	v_mfma_f32_32x32x16_bf16 v[34:49], v[78:81], v[70:73], v[34:49]
	v_min_i32_e32 v134, v143, v145
	v_min_i32_e32 v70, v144, v146
	v_min_i32_e32 v71, v147, v124
	v_min_i32_e32 v72, v82, v125
	v_min_i32_e32 v73, v126, v132
	v_min_i32_e32 v78, v127, v128
	v_min_i32_e32 v79, v129, v131
	s_waitcnt lgkmcnt(0)
	v_mfma_f32_32x32x16_bf16 v[34:49], v[74:77], v[66:69], v[34:49]
	v_min_i32_e32 v80, v130, v133
	s_nop 10
	v_and_or_b32 v41, v41, s43, 20
	v_and_or_b32 v45, v45, s43, 12
	v_and_or_b32 v35, v35, s43, 30
	v_and_or_b32 v46, v46, s43, 7
	v_and_or_b32 v39, v39, s43, 22
	v_and_or_b32 v40, v40, s43, 21
	v_and_or_b32 v34, v34, s43, 31
	v_and_or_b32 v47, v47, s43, 6
	v_and_or_b32 v38, v38, s43, 23
	v_and_or_b32 v42, v42, s43, 15
	v_and_or_b32 v37, v37, s43, 28
	v_and_or_b32 v48, v48, s43, 5
	v_and_or_b32 v43, v43, s43, 14
	v_and_or_b32 v44, v44, s43, 13
	v_and_or_b32 v36, v36, s43, 29
	v_and_or_b32 v49, v49, s43, 4
	v_min_i32_e32 v66, v41, v45
	v_min_i32_e32 v67, v35, v46
	v_min_i32_e32 v69, v39, v40
	v_min_i32_e32 v74, v34, v47
	v_min_i32_e32 v77, v38, v42
	v_min_i32_e32 v81, v37, v48
	v_min_i32_e32 v136, v43, v44
	v_min_i32_e32 v137, v36, v49
	v_max_i32_e32 v34, v34, v47
	v_max_i32_e32 v39, v39, v40
	v_max_i32_e32 v35, v35, v46
	v_max_i32_e32 v41, v41, v45
	v_max_i32_e32 v36, v36, v49
	v_max_i32_e32 v43, v43, v44
	v_max_i32_e32 v37, v37, v48
	v_max_i32_e32 v38, v38, v42
	v_max_i32_e32 v40, v34, v39
	v_max_i32_e32 v45, v35, v41
	v_max_i32_e32 v44, v36, v43
	v_max_i32_e32 v42, v37, v38
	v_min_i32_e32 v46, v40, v45
	v_min_i32_e32 v47, v44, v42
	v_min_i32_e32 v75, v69, v74
	v_min_i32_e32 v48, v46, v47
	v_max_i32_e32 v46, v46, v47
	v_min_i32_e32 v37, v37, v38
	v_min_i32_e32 v34, v34, v39
	v_max_i32_e32 v39, v136, v137
	v_max_i32_e32 v47, v66, v67
	v_max_i32_e32 v69, v69, v74
	v_max_i32_e32 v74, v77, v81
	v_min_i32_e32 v35, v35, v41
	v_min_i32_e32 v36, v36, v43
	v_min_i32_e32 v68, v66, v67
	v_min_i32_e32 v135, v77, v81
	v_min_i32_e32 v138, v136, v137
	v_max_i32_e32 v38, v37, v34
	v_max_i32_e32 v77, v69, v74
	v_max_i32_e32 v41, v35, v36
	v_min_i32_e32 v34, v37, v34
	v_min_i32_e32 v37, v39, v47
	v_min_i32_e32 v76, v68, v75
	v_min_i32_e32 v139, v135, v138
	v_max_i32_e32 v49, v68, v75
	v_max_i32_e32 v68, v135, v138
	v_max_i32_e32 v40, v40, v45
	v_max_i32_e32 v42, v44, v42
	v_max_i32_e32 v66, v39, v47
	v_max_i32_e32 v43, v77, v41
	v_max_i32_e32 v39, v34, v37
	v_min_i32_e32 v41, v77, v41
	v_min_i32_e32 v69, v69, v74
	v_min_i32_e32 v35, v35, v36
	v_max_i32_e32 v75, v49, v68
	v_min_i32_e32 v44, v40, v42
	v_max_i32_e32 v67, v38, v66
	v_max_i32_e32 v47, v39, v41
	v_max_i32_e32 v36, v69, v35
	v_min_i32_e32 v39, v39, v41
	v_min_i32_e32 v35, v69, v35
	v_min_i32_e32 v34, v34, v37
	v_max_i32_e32 v41, v76, v139
	v_min_i32_e32 v49, v49, v68
	v_min_i32_e32 v45, v46, v44
	v_min_i32_e32 v81, v67, v43
	v_min_i32_e32 v38, v38, v66
	v_max_i32_e32 v37, v35, v34
	v_max_i32_e32 v68, v41, v49
	v_max_i32_e32 v135, v48, v75
	v_min_i32_e32 v136, v45, v81
	v_max_i32_e32 v66, v36, v38
	v_min_i32_e32 v36, v36, v38
	v_max_i32_e32 v69, v37, v68
	v_min_i32_e32 v48, v48, v75
	v_max_i32_e32 v137, v135, v136
	v_max_i32_e32 v74, v47, v66
	v_min_i32_e32 v135, v135, v136
	v_min_i32_e32 v47, v47, v66
	v_max_i32_e32 v38, v39, v36
	v_max_i32_e32 v75, v69, v48
	v_min_i32_e32 v34, v35, v34
	v_min_i32_e32 v35, v41, v49
	v_min_i32_e32 v36, v39, v36
	v_min_i32_e32 v39, v69, v48
	v_max_i32_e32 v44, v46, v44
	v_max_i32_e32 v43, v67, v43
	v_min_i32_e32 v140, v76, v139
	v_min_i32_e32 v77, v137, v74
	v_max_i32_e32 v66, v135, v47
	v_max_i32_e32 v76, v38, v75
	v_min_i32_e32 v47, v135, v47
	v_max_i32_e32 v41, v34, v35
	v_min_i32_e32 v37, v37, v68
	v_min_i32_e32 v48, v36, v39
	v_max_i32_e32 v45, v45, v81
	v_min_i32_e32 v46, v44, v43
	v_min_i32_e32 v38, v38, v75
	v_max_i32_e32 v36, v36, v39
	v_min_i32_e32 v136, v77, v66
	v_max_i32_e32 v135, v76, v47
	v_max_i32_e32 v49, v41, v37
	v_max_i32_e32 v69, v137, v74
	v_min_i32_e32 v67, v45, v46
	v_min_i32_e32 v47, v76, v47
	v_max_i32_e32 v39, v38, v36
	v_min_i32_e32 v138, v136, v135
	v_max_i32_e32 v68, v49, v48
	v_max_i32_e32 v74, v69, v67
	v_min_i32_e32 v37, v41, v37
	v_max_i32_e32 v41, v77, v66
	v_min_i32_e32 v75, v47, v39
	v_max_i32_e32 v43, v44, v43
	v_min_i32_e32 v34, v34, v35
	v_min_i32_e32 v36, v38, v36
	v_min_i32_e32 v48, v49, v48
	v_min_i32_e32 v49, v69, v67
	v_max3_i32 v140, v143, v145, v140
	v_max3_i32 v126, v126, v132, v138
	v_max3_i32 v68, v147, v124, v68
	v_max3_i32 v74, v129, v131, v74
	v_max3_i32 v37, v144, v146, v37
	v_max3_i32 v41, v127, v128, v41
	v_max3_i32 v75, v82, v125, v75
	v_max3_i32 v43, v130, v133, v43
	v_max_i32_e32 v34, v134, v34
	v_max3_i32 v35, v73, v136, v135
	v_max_i32_e32 v36, v71, v36
	v_max3_i32 v38, v79, v45, v46
	v_max_i32_e32 v48, v70, v48
	v_max_i32_e32 v49, v78, v49
	v_max3_i32 v39, v72, v47, v39
	v_max3_i32 v40, v80, v40, v42
	v_min_i32_e32 v81, v68, v74
	v_min_i32_e32 v66, v37, v41
	v_min_i32_e32 v73, v34, v35
	v_min_i32_e32 v45, v36, v38
	v_min_i32_e32 v42, v39, v40
	v_max_i32_e32 v71, v140, v126
; #define LAS __attribute__((address_space(3)))
; #define MFMA32(a, b, c) __builtin_amdgcn_mfma_f32_32x32x16_bf16((a), (b), (c), 0, 0, 0)
; __device__ __forceinline__ void route_task(int task, int tl0, const bf16* QP  , const LAS bf16* KHL, LAS unsigned short* EL, LAS float* GL, int lane) {
;     ...
;         for (int kt = 0; kt < 4; ++kt) {
;             f32x16 X;
; #pragma unroll
;             for (int i = 0; i < 16; ++i) X[i] = 8.f;
;             const LAS bf16* khp = KHL + (half * 128 + 32 * kt + r) * 72 + 8 * hi;
; #pragma unroll
;             for (int ks = 0; ks < 4; ++ks) {
;                 const bf16x8 kh = lds8(khp + 16 * ks);
;                 X = MFMA32(kh, qa[half][ks], X);
;     ...
;         { const unsigned h4 = 4u * (unsigned)hi;
; #pragma unroll
;           for (int i = 0; i < 16; ++i) cur[i] -= (int)h4; }
;         int oth[16];
; #pragma unroll
;         for (int i = 0; i < 16; ++i) oth[i] = __shfl_xor(cur[i], 32);
;         merge16_desc(cur, oth);
; #pragma unroll
;         for (int i = 0; i < 16; ++i) top[half][i] = cur[i];
	v_max_i32_e32 v68, v68, v74
	v_max_i32_e32 v37, v37, v41
	v_max_i32_e32 v41, v75, v43
	v_max_i32_e32 v34, v34, v35
	v_max_i32_e32 v35, v36, v38
	v_max_i32_e32 v38, v48, v49
	v_max_i32_e32 v39, v39, v40
	v_min_i32_e32 v44, v75, v43
	v_max_i32_e32 v72, v71, v68
	v_max_i32_e32 v43, v37, v41
	v_max_i32_e32 v36, v34, v35
	v_max_i32_e32 v40, v38, v39
	v_min_i32_e32 v67, v48, v49
	v_max_i32_e32 v74, v72, v43
	v_max_i32_e32 v48, v36, v40
	v_min_i32_e32 v43, v72, v43
	v_min_i32_e32 v36, v36, v40
	v_max_i32_e32 v40, v43, v36
	v_min_i32_e32 v36, v43, v36
	v_min_i32_e32 v43, v71, v68
	v_min_i32_e32 v37, v37, v41
	v_min_i32_e32 v34, v34, v35
	v_min_i32_e32 v35, v38, v39
	v_min_i32_e32 v132, v140, v126
	v_max_i32_e32 v41, v43, v37
	v_max_i32_e32 v38, v34, v35
	v_min_i32_e32 v37, v43, v37
	v_min_i32_e32 v34, v34, v35
	v_min_i32_e32 v76, v66, v44
	v_min_i32_e32 v47, v67, v42
	v_max_i32_e32 v39, v41, v38
	v_min_i32_e32 v38, v41, v38
	v_max_i32_e32 v35, v37, v34
	v_min_i32_e32 v34, v37, v34
	v_max_i32_e32 v37, v132, v81
	v_max_i32_e32 v41, v66, v44
	v_max_i32_e32 v44, v73, v45
	v_max_i32_e32 v42, v67, v42
	v_min_i32_e32 v124, v132, v81
	v_min_i32_e32 v46, v73, v45
	v_max_i32_e32 v43, v37, v41
	v_min_i32_e32 v37, v37, v41
	v_min_i32_e32 v41, v44, v42
	v_min_i32_e32 v77, v124, v76
	v_min_i32_e32 v69, v46, v47
	v_max_i32_e32 v45, v44, v42
	v_max_i32_e32 v42, v37, v41
	v_min_i32_e32 v37, v37, v41
	v_max_i32_e32 v41, v124, v76
	v_max_i32_e32 v44, v46, v47
	v_min_i32_e32 v70, v77, v69
	v_max_i32_e32 v49, v74, v48
	v_min_i32_e32 v48, v74, v48
	v_max_i32_e32 v66, v43, v45
	v_min_i32_e32 v43, v43, v45
	v_max_i32_e32 v45, v41, v44
	v_min_i32_e32 v41, v41, v44
	v_max_i32_e32 v44, v77, v69
	v_sub_u32_e32 v46, v49, v87
	v_sub_u32_e32 v47, v48, v87
	v_sub_u32_e32 v40, v40, v87
	v_sub_u32_e32 v36, v36, v87
	v_sub_u32_e32 v39, v39, v87
	v_sub_u32_e32 v38, v38, v87
	v_sub_u32_e32 v35, v35, v87
	v_sub_u32_e32 v34, v34, v87
	v_sub_u32_e32 v48, v66, v87
	v_sub_u32_e32 v43, v43, v87
	v_sub_u32_e32 v42, v42, v87
	v_sub_u32_e32 v37, v37, v87
	v_sub_u32_e32 v45, v45, v87
	v_sub_u32_e32 v41, v41, v87
	v_sub_u32_e32 v44, v44, v87
	v_sub_u32_e32 v49, v70, v87
	ds_bpermute_b32 v66, v123, v46
	ds_bpermute_b32 v67, v123, v47
	ds_bpermute_b32 v68, v123, v40
	ds_bpermute_b32 v69, v123, v36
	ds_bpermute_b32 v70, v123, v39
	ds_bpermute_b32 v71, v123, v38
	ds_bpermute_b32 v72, v123, v35
	ds_bpermute_b32 v73, v123, v34
	ds_bpermute_b32 v74, v123, v48
	ds_bpermute_b32 v75, v123, v43
	ds_bpermute_b32 v76, v123, v42
	ds_bpermute_b32 v77, v123, v49
	ds_bpermute_b32 v78, v123, v44
	ds_bpermute_b32 v79, v123, v41
	ds_bpermute_b32 v80, v123, v45
	ds_bpermute_b32 v81, v123, v37
	s_waitcnt lgkmcnt(4)
	v_max_i32_e32 v46, v46, v77
	s_waitcnt lgkmcnt(3)
	v_max_i32_e32 v47, v47, v78
	s_waitcnt lgkmcnt(2)
	v_max_i32_e32 v40, v40, v79
	s_waitcnt lgkmcnt(1)
	v_max_i32_e32 v36, v36, v80
	s_waitcnt lgkmcnt(0)
	v_max_i32_e32 v39, v39, v81
	v_max_i32_e32 v38, v38, v76
	v_max_i32_e32 v35, v35, v75
	v_max_i32_e32 v34, v34, v74
	v_max_i32_e32 v48, v48, v73
	v_max_i32_e32 v43, v43, v72
	v_max_i32_e32 v42, v42, v71
	v_max_i32_e32 v37, v37, v70
	v_max_i32_e32 v45, v45, v69
	v_max_i32_e32 v41, v41, v68
	v_max_i32_e32 v44, v44, v67
	v_max_i32_e32 v49, v49, v66
	v_max_i32_e32 v66, v46, v48
	v_min_i32_e32 v46, v46, v48
	v_max_i32_e32 v48, v47, v43
	v_min_i32_e32 v43, v47, v43
	v_max_i32_e32 v47, v40, v42
	v_min_i32_e32 v40, v40, v42
	v_max_i32_e32 v42, v36, v37
	v_min_i32_e32 v36, v36, v37
	v_max_i32_e32 v37, v39, v45
	v_min_i32_e32 v39, v39, v45
	v_max_i32_e32 v45, v38, v41
	v_min_i32_e32 v38, v38, v41
	v_max_i32_e32 v41, v35, v44
	v_min_i32_e32 v35, v35, v44
	v_max_i32_e32 v44, v34, v49
	v_min_i32_e32 v34, v34, v49
	v_max_i32_e32 v49, v66, v37
	v_min_i32_e32 v37, v66, v37
	v_max_i32_e32 v66, v48, v45
	v_min_i32_e32 v45, v48, v45
	v_max_i32_e32 v48, v47, v41
	v_min_i32_e32 v41, v47, v41
	v_max_i32_e32 v47, v42, v44
	v_max_i32_e32 v80, v66, v47
	v_min_i32_e32 v124, v66, v47
	ds_read_b128 v[66:69], v94 offset:18432
	ds_read_b128 v[70:73], v94 offset:18464
	v_min_i32_e32 v42, v42, v44
	v_max_i32_e32 v44, v46, v39
	v_min_i32_e32 v74, v46, v39
	v_max_i32_e32 v39, v43, v38
	v_min_i32_e32 v75, v43, v38
	v_max_i32_e32 v38, v40, v35
	v_min_i32_e32 v76, v40, v35
	v_max_i32_e32 v35, v36, v34
	v_min_i32_e32 v77, v36, v34
	v_max_i32_e32 v78, v49, v48
	v_min_i32_e32 v82, v49, v48
	v_max_i32_e32 v125, v37, v41
	v_min_i32_e32 v126, v37, v41
	v_max_i32_e32 v127, v45, v42
	v_min_i32_e32 v128, v45, v42
	v_max_i32_e32 v129, v44, v38
	v_min_i32_e32 v130, v44, v38
	v_max_i32_e32 v131, v39, v35
	v_min_i32_e32 v132, v39, v35
	s_waitcnt vmcnt(3) lgkmcnt(1)
	v_mfma_f32_32x32x16_bf16 v[34:49], v[66:69], v[62:65], v[18:33]
	ds_read_b128 v[66:69], v94 offset:18496
	v_max_i32_e32 v133, v74, v76
	v_min_i32_e32 v134, v74, v76
	v_max_i32_e32 v135, v75, v77
	v_min_i32_e32 v136, v75, v77
	v_max_i32_e32 v79, v78, v80
	v_min_i32_e32 v81, v78, v80
	s_waitcnt vmcnt(2) lgkmcnt(1)
	v_mfma_f32_32x32x16_bf16 v[34:49], v[70:73], v[58:61], v[34:49]
	v_max_i32_e32 v80, v82, v124
	v_min_i32_e32 v78, v82, v124
	v_max_i32_e32 v77, v125, v127
	v_min_i32_e32 v76, v125, v127
	v_max_i32_e32 v75, v126, v128
	v_min_i32_e32 v73, v126, v128
	ds_read_b128 v[124:127], v94 offset:18528
	s_waitcnt vmcnt(1) lgkmcnt(1)
	v_mfma_f32_32x32x16_bf16 v[34:49], v[66:69], v[54:57], v[34:49]
	v_max_i32_e32 v71, v129, v131
	v_min_i32_e32 v74, v129, v131
	v_max_i32_e32 v72, v130, v132
	v_min_i32_e32 v70, v130, v132
	v_max_i32_e32 v69, v133, v135
	v_min_i32_e32 v68, v133, v135
	v_max_i32_e32 v67, v134, v136
	s_waitcnt vmcnt(0) lgkmcnt(0)
; #define LAS __attribute__((address_space(3)))
; #define MFMA32(a, b, c) __builtin_amdgcn_mfma_f32_32x32x16_bf16((a), (b), (c), 0, 0, 0)
; __device__ __forceinline__ void route_task(int task, int tl0, const bf16* QP  , const LAS bf16* KHL, LAS unsigned short* EL, LAS float* GL, int lane) {
;     ...
; #pragma unroll
;             for (int i = 0; i < 16; ++i) X[i] = 8.f;
;             const LAS bf16* khp = KHL + (half * 128 + 32 * kt + r) * 72 + 8 * hi;
; #pragma unroll
;             for (int ks = 0; ks < 4; ++ks) {
;                 const bf16x8 kh = lds8(khp + 16 * ks);
;                 X = MFMA32(kh, qa[half][ks], X);
;             }
;             int grp[16];
; #pragma unroll
;             for (int i = 0; i < 16; ++i) grp[i] = (int)((__float_as_uint(X[i]) | 127u) - (unsigned)(32 * kt + (i & 3) + 8 * (i >> 2)));
;             sort16_desc(grp);
;             if (kt == 0) {
; #pragma unroll
;                 for (int i = 0; i < 16; ++i) cur[i] = grp[i];
;             } else merge16_desc(cur, grp);
	v_mfma_f32_32x32x16_bf16 v[34:49], v[124:127], v[50:53], v[34:49]
	v_min_i32_e32 v66, v134, v136
	s_nop 10
	v_bitop3_b32 v37, v37, s42, 3 bitop3:0x56
	v_bitop3_b32 v48, v48, s42, 26 bitop3:0x56
	v_bitop3_b32 v38, v38, s42, 8 bitop3:0x56
	v_bitop3_b32 v42, v42, s42, 16 bitop3:0x56
	v_bitop3_b32 v47, v47, s42, 25 bitop3:0x56
	v_bitop3_b32 v39, v39, s42, 9 bitop3:0x56
	v_bitop3_b32 v40, v40, s42, 10 bitop3:0x56
	v_bitop3_b32 v43, v43, s42, 17 bitop3:0x56
	v_bitop3_b32 v44, v44, s42, 18 bitop3:0x56
	v_bitop3_b32 v36, v36, s42, 2 bitop3:0x56
	v_bitop3_b32 v49, v49, s42, 27 bitop3:0x56
	v_bitop3_b32 v41, v41, s42, 11 bitop3:0x56
	v_bitop3_b32 v45, v45, s42, 19 bitop3:0x56
	v_bitop3_b32 v35, v35, s42, 1 bitop3:0x56
	v_bitop3_b32 v46, v46, s42, 24 bitop3:0x56
	v_or_b32_e32 v34, 0x7f, v34
	v_max_i32_e32 v82, v37, v48
	v_max_i32_e32 v124, v38, v42
	v_max_i32_e32 v126, v34, v47
	v_max_i32_e32 v127, v39, v40
	v_min_i32_e32 v130, v43, v44
	v_min_i32_e32 v131, v36, v49
	v_min_i32_e32 v133, v41, v45
	v_min_i32_e32 v134, v35, v46
	v_min_i32_e32 v39, v39, v40
	v_min_i32_e32 v34, v34, v47
	v_min_i32_e32 v38, v38, v42
	v_min_i32_e32 v37, v37, v48
	v_max_i32_e32 v35, v35, v46
	v_max_i32_e32 v41, v41, v45
	v_max_i32_e32 v36, v36, v49
	v_max_i32_e32 v43, v43, v44
	v_min_i32_e32 v125, v82, v124
	v_min_i32_e32 v128, v126, v127
	v_max_i32_e32 v132, v130, v131
	v_max_i32_e32 v135, v133, v134
	v_max_i32_e32 v40, v39, v34
	v_max_i32_e32 v42, v38, v37
	v_min_i32_e32 v45, v35, v41
	v_min_i32_e32 v44, v36, v43
	v_min_i32_e32 v129, v125, v128
	v_max_i32_e32 v47, v40, v42
	v_max_i32_e32 v46, v45, v44
	v_min_i32_e32 v40, v40, v42
	v_min_i32_e32 v42, v45, v44
	v_max_i32_e32 v45, v125, v128
	v_max_i32_e32 v125, v132, v135
	v_min_i32_e32 v128, v45, v125
	v_min_i32_e32 v34, v39, v34
	v_max_i32_e32 v39, v126, v127
	v_max_i32_e32 v35, v35, v41
	v_max_i32_e32 v41, v82, v124
	v_max_i32_e32 v148, v45, v125
	ds_read_b128 v[124:127], v97
	v_max_i32_e32 v44, v40, v42
	v_min_i32_e32 v138, v40, v42
	v_min_i32_e32 v40, v133, v134
	v_min_i32_e32 v37, v38, v37
	v_min_i32_e32 v38, v130, v131
	v_max_i32_e32 v36, v36, v43
	v_min_i32_e32 v136, v132, v135
	v_min_i32_e32 v133, v40, v34
	v_min_i32_e32 v134, v37, v38
	v_max_i32_e32 v34, v40, v34
	v_max_i32_e32 v37, v37, v38
	v_min_i32_e32 v40, v39, v35
	v_min_i32_e32 v42, v36, v41
	v_max_i32_e32 v144, v39, v35
	v_max_i32_e32 v145, v36, v41
	v_max_i32_e32 v137, v129, v136
	v_min_i32_e32 v136, v129, v136
	v_max_i32_e32 v140, v133, v134
	v_min_i32_e32 v141, v34, v37
	v_max_i32_e32 v143, v40, v42
	v_min_i32_e32 v146, v144, v145
	v_max_i32_e32 v149, v47, v46
	v_min_i32_e32 v48, v47, v46
	v_max_i32_e32 v139, v138, v136
	v_max_i32_e32 v142, v140, v141
	v_min_i32_e32 v43, v40, v42
	v_max_i32_e32 v34, v34, v37
	v_min_i32_e32 v147, v143, v146
	v_min_i32_e32 v150, v148, v149
	v_min_i32_e32 v49, v137, v48
	v_min_i32_e32 v132, v44, v128
	v_max_i32_e32 v38, v139, v142
	v_min_i32_e32 v37, v43, v34
	v_max_i32_e32 v34, v43, v34
	v_min_i32_e32 v35, v147, v150
	v_max_i32_e32 v39, v137, v48
	v_max_i32_e32 v40, v44, v128
	v_max_i32_e32 v135, v49, v132
	v_max_i32_e32 v82, v38, v37
	v_min_i32_e32 v36, v34, v35
	v_min_i32_e32 v41, v39, v40
	v_max_i32_e32 v129, v135, v82
	v_min_i32_e32 v42, v36, v41
	v_min_i32_e32 v137, v129, v42
	v_max_i32_e32 v159, v129, v42
	ds_read_b128 v[128:131], v97 offset:32
	v_min_i32_e32 v82, v135, v82
	v_min_i32_e32 v132, v49, v132
	v_min_i32_e32 v135, v38, v37
	v_max_i32_e32 v154, v34, v35
	v_max_i32_e32 v155, v39, v40
	v_max_i32_e32 v157, v36, v41
	s_waitcnt lgkmcnt(1)
	v_mfma_f32_32x32x16_bf16 v[34:49], v[124:127], v[62:65], v[18:33]
	ds_read_b128 v[124:127], v97 offset:64
	v_max_i32_e32 v151, v132, v135
	v_max_i32_e32 v152, v82, v151
	v_min_i32_e32 v136, v138, v136
	v_min_i32_e32 v138, v140, v141
	v_min_i32_e32 v82, v82, v151
	v_max_i32_e32 v147, v147, v150
	s_waitcnt lgkmcnt(1)
	v_mfma_f32_32x32x16_bf16 v[34:49], v[128:131], v[58:61], v[34:49]
	ds_read_b128 v[128:131], v97 offset:96
	v_max_i32_e32 v143, v143, v146
	v_min_i32_e32 v133, v133, v134
	v_min_i32_e32 v156, v154, v155
	v_max_i32_e32 v140, v136, v138
	v_min_i32_e32 v139, v139, v142
	v_max_i32_e32 v142, v154, v155
	s_waitcnt lgkmcnt(1)
	v_mfma_f32_32x32x16_bf16 v[34:49], v[124:127], v[54:57], v[34:49]
	v_max_i32_e32 v124, v148, v149
	v_min_i32_e32 v136, v136, v138
	v_max_i32_e32 v141, v140, v139
	v_min_i32_e32 v139, v140, v139
	v_min_i32_e32 v125, v143, v124
	v_min_i32_e32 v158, v156, v157
	v_min_i32_e32 v132, v132, v135
	s_waitcnt lgkmcnt(0)
; #define LAS __attribute__((address_space(3)))
; #define MFMA32(a, b, c) __builtin_amdgcn_mfma_f32_32x32x16_bf16((a), (b), (c), 0, 0, 0)
; __device__ __forceinline__ void route_task(int task, int tl0, const bf16* QP  , const LAS bf16* KHL, LAS unsigned short* EL, LAS float* GL, int lane) {
;     ...
; #pragma unroll
;             for (int i = 0; i < 16; ++i) X[i] = 8.f;
;             const LAS bf16* khp = KHL + (half * 128 + 32 * kt + r) * 72 + 8 * hi;
; #pragma unroll
;             for (int ks = 0; ks < 4; ++ks) {
;                 const bf16x8 kh = lds8(khp + 16 * ks);
;                 X = MFMA32(kh, qa[half][ks], X);
;             }
;             int grp[16];
; #pragma unroll
;             for (int i = 0; i < 16; ++i) grp[i] = (int)((__float_as_uint(X[i]) | 127u) - (unsigned)(32 * kt + (i & 3) + 8 * (i >> 2)));
;             sort16_desc(grp);
;             if (kt == 0) {
; #pragma unroll
;                 for (int i = 0; i < 16; ++i) cur[i] = grp[i];
;             } else merge16_desc(cur, grp);
	v_mfma_f32_32x32x16_bf16 v[34:49], v[128:131], v[50:53], v[34:49]
	v_min_i32_e32 v126, v147, v125
	v_min_i32_e32 v153, v137, v152
	v_min_i32_e32 v160, v158, v159
	v_min_i32_e32 v135, v141, v132
	v_min_i32_e32 v127, v142, v126
	s_nop 6
	v_bitop3_b32 v37, v37, s42, 35 bitop3:0x56
	v_bitop3_b32 v48, v48, s42, 58 bitop3:0x56
	v_bitop3_b32 v38, v38, s42, 40 bitop3:0x56
	v_bitop3_b32 v42, v42, s42, 48 bitop3:0x56
	v_bitop3_b32 v34, v34, s42, 32 bitop3:0x56
	v_bitop3_b32 v47, v47, s42, 57 bitop3:0x56
	v_bitop3_b32 v39, v39, s42, 41 bitop3:0x56
	v_bitop3_b32 v40, v40, s42, 42 bitop3:0x56
	v_bitop3_b32 v43, v43, s42, 49 bitop3:0x56
	v_bitop3_b32 v44, v44, s42, 50 bitop3:0x56
	v_bitop3_b32 v36, v36, s42, 34 bitop3:0x56
	v_bitop3_b32 v49, v49, s42, 59 bitop3:0x56
	v_bitop3_b32 v41, v41, s42, 43 bitop3:0x56
	v_bitop3_b32 v45, v45, s42, 51 bitop3:0x56
	v_bitop3_b32 v35, v35, s42, 33 bitop3:0x56
	v_bitop3_b32 v46, v46, s42, 56 bitop3:0x56
	v_max_i32_e32 v128, v37, v48
	v_max_i32_e32 v129, v38, v42
	v_max_i32_e32 v131, v34, v47
	v_max_i32_e32 v134, v39, v40
	v_min_i32_e32 v146, v43, v44
	v_min_i32_e32 v148, v36, v49
	v_min_i32_e32 v150, v41, v45
	v_min_i32_e32 v151, v35, v46
	v_min_i32_e32 v39, v39, v40
	v_min_i32_e32 v34, v34, v47
	v_min_i32_e32 v38, v38, v42
	v_min_i32_e32 v37, v37, v48
	v_max_i32_e32 v35, v35, v46
	v_max_i32_e32 v41, v41, v45
	v_max_i32_e32 v36, v36, v49
	v_max_i32_e32 v43, v43, v44
	v_min_i32_e32 v130, v128, v129
	v_min_i32_e32 v138, v131, v134
	v_max_i32_e32 v149, v146, v148
	v_max_i32_e32 v154, v150, v151
	v_max_i32_e32 v40, v39, v34
	v_max_i32_e32 v42, v38, v37
	v_min_i32_e32 v45, v35, v41
	v_min_i32_e32 v44, v36, v43
	v_min_i32_e32 v150, v150, v151
	v_min_i32_e32 v34, v39, v34
	v_min_i32_e32 v37, v38, v37
	v_min_i32_e32 v38, v146, v148
	v_max_i32_e32 v131, v131, v134
	v_max_i32_e32 v35, v35, v41
	v_max_i32_e32 v36, v36, v43
	v_max_i32_e32 v43, v128, v129
	v_min_i32_e32 v140, v130, v138
	v_min_i32_e32 v155, v149, v154
	v_max_i32_e32 v47, v40, v42
	v_max_i32_e32 v46, v45, v44
	v_min_i32_e32 v40, v40, v42
	v_min_i32_e32 v42, v45, v44
	v_max_i32_e32 v45, v130, v138
	v_max_i32_e32 v130, v149, v154
	v_min_i32_e32 v39, v150, v34
	v_min_i32_e32 v146, v37, v38
	v_max_i32_e32 v34, v150, v34
	v_max_i32_e32 v37, v37, v38
	v_min_i32_e32 v41, v131, v35
	v_min_i32_e32 v128, v36, v43
	v_max_i32_e32 v35, v131, v35
	v_max_i32_e32 v36, v36, v43
	v_min_i32_e32 v48, v47, v46
	v_max_i32_e32 v44, v40, v42
	v_min_i32_e32 v138, v45, v130
	v_min_i32_e32 v40, v40, v42
	v_min_i32_e32 v42, v140, v155
	v_max_i32_e32 v148, v39, v146
	v_min_i32_e32 v38, v34, v37
	v_min_i32_e32 v129, v41, v128
	v_max_i32_e32 v41, v41, v128
	v_min_i32_e32 v43, v35, v36
	v_max_i32_e32 v45, v45, v130
	v_max_i32_e32 v46, v47, v46
	v_max_i32_e32 v161, v140, v155
	v_max_i32_e32 v140, v40, v42
	v_max_i32_e32 v150, v148, v38
	v_max_i32_e32 v34, v34, v37
	v_min_i32_e32 v128, v41, v43
	v_min_i32_e32 v47, v45, v46
	v_min_i32_e32 v49, v161, v48
	v_min_i32_e32 v149, v44, v138
	v_max_i32_e32 v151, v140, v150
	v_min_i32_e32 v37, v129, v34
	v_max_i32_e32 v34, v129, v34
	v_min_i32_e32 v129, v128, v47
	v_max_i32_e32 v48, v161, v48
	v_max_i32_e32 v44, v44, v138
	v_max_i32_e32 v154, v49, v149
	v_max_i32_e32 v134, v151, v37
	v_min_i32_e32 v130, v34, v129
	v_min_i32_e32 v131, v48, v44
	v_min_i32_e32 v49, v49, v149
	v_min_i32_e32 v37, v151, v37
	v_max_i32_e32 v34, v34, v129
	v_max_i32_e32 v44, v48, v44
	v_min_i32_e32 v40, v40, v42
	v_min_i32_e32 v38, v148, v38
	v_max_i32_e32 v41, v41, v43
	v_max_i32_e32 v43, v45, v46
	v_max_i32_e32 v155, v154, v134
	v_min_i32_e32 v138, v130, v131
	v_min_i32_e32 v134, v154, v134
	v_max_i32_e32 v149, v49, v37
	v_min_i32_e32 v48, v34, v44
	v_max_i32_e32 v129, v130, v131
	v_max_i32_e32 v42, v40, v38
	v_min_i32_e32 v140, v140, v150
	v_max_i32_e32 v34, v34, v44
	v_max_i32_e32 v44, v128, v47
	v_min_i32_e32 v45, v41, v43
	v_min_i32_e32 v161, v155, v138
	v_max_i32_e32 v151, v134, v149
	v_min_i32_e32 v130, v48, v129
	v_max_i32_e32 v131, v155, v138
	v_max_i32_e32 v148, v42, v140
	v_min_i32_e32 v37, v49, v37
	v_min_i32_e32 v46, v44, v45
	v_min_i32_e32 v154, v161, v151
	v_min_i32_e32 v138, v130, v131
	v_min_i32_e32 v49, v148, v37
	v_min_i32_e32 v134, v134, v149
	v_min_i32_e32 v47, v34, v46
	v_min_i32_e32 v42, v42, v140
	v_min_i32_e32 v38, v40, v38
	v_min_i32_e32 v39, v39, v146
	v_max3_i32 v39, v144, v145, v39
	v_max3_i32 v38, v143, v124, v38
	v_max3_i32 v40, v147, v125, v42
	v_max3_i32 v42, v142, v126, v49
	v_max3_i32 v37, v127, v148, v37
	v_max3_i32 v49, v156, v157, v134
	v_max3_i32 v124, v158, v159, v154
	v_max3_i32 v125, v160, v161, v151
	v_max3_i32 v126, v137, v152, v138
	v_max3_i32 v127, v153, v130, v131
	v_max3_i32 v48, v82, v48, v129
	v_max3_i32 v47, v141, v132, v47
	v_max3_i32 v34, v135, v34, v46
	v_max3_i32 v44, v139, v44, v45
	v_max3_i32 v41, v136, v41, v43
	v_max3_i32 v35, v133, v35, v36
	v_max_i32_e32 v36, v39, v126
	v_min_i32_e32 v39, v39, v126
	v_max_i32_e32 v43, v38, v127
	v_min_i32_e32 v38, v38, v127
	v_max_i32_e32 v45, v40, v48
	v_min_i32_e32 v40, v40, v48
	v_max_i32_e32 v46, v42, v47
	v_min_i32_e32 v42, v42, v47
	v_max_i32_e32 v47, v37, v34
	v_min_i32_e32 v34, v37, v34
	v_max_i32_e32 v37, v49, v44
	v_min_i32_e32 v44, v49, v44
	v_max_i32_e32 v48, v124, v41
	v_min_i32_e32 v41, v124, v41
	v_max_i32_e32 v49, v125, v35
	v_min_i32_e32 v35, v125, v35
	ds_read_b128 v[124:127], v94 offset:27648
	ds_read_b128 v[128:131], v94 offset:27680
	v_max_i32_e32 v82, v36, v47
	v_min_i32_e32 v132, v36, v47
	v_max_i32_e32 v36, v43, v37
	v_min_i32_e32 v133, v43, v37
	v_max_i32_e32 v37, v45, v48
	v_max_i32_e32 v43, v46, v49
	v_min_i32_e32 v134, v45, v48
	v_min_i32_e32 v135, v46, v49
	v_max_i32_e32 v136, v39, v34
	v_min_i32_e32 v137, v39, v34
	v_max_i32_e32 v138, v38, v44
	v_min_i32_e32 v139, v38, v44
	v_max_i32_e32 v140, v40, v41
	v_min_i32_e32 v141, v40, v41
	v_max_i32_e32 v142, v42, v35
	v_min_i32_e32 v143, v42, v35
	v_max_i32_e32 v144, v82, v37
	v_min_i32_e32 v82, v82, v37
	v_max_i32_e32 v145, v36, v43
	v_min_i32_e32 v146, v36, v43
	s_waitcnt lgkmcnt(1)
; #define LAS __attribute__((address_space(3)))
; #define MFMA32(a, b, c) __builtin_amdgcn_mfma_f32_32x32x16_bf16((a), (b), (c), 0, 0, 0)
; __device__ __forceinline__ void route_task(int task, int tl0, const bf16* QP  , const LAS bf16* KHL, LAS unsigned short* EL, LAS float* GL, int lane) {
;     ...
; #pragma unroll
;             for (int i = 0; i < 16; ++i) X[i] = 8.f;
;             const LAS bf16* khp = KHL + (half * 128 + 32 * kt + r) * 72 + 8 * hi;
; #pragma unroll
;             for (int ks = 0; ks < 4; ++ks) {
;                 const bf16x8 kh = lds8(khp + 16 * ks);
;                 X = MFMA32(kh, qa[half][ks], X);
;             }
;             int grp[16];
; #pragma unroll
;             for (int i = 0; i < 16; ++i) grp[i] = (int)((__float_as_uint(X[i]) | 127u) - (unsigned)(32 * kt + (i & 3) + 8 * (i >> 2)));
;             sort16_desc(grp);
;             if (kt == 0) {
; #pragma unroll
;                 for (int i = 0; i < 16; ++i) cur[i] = grp[i];
;             } else merge16_desc(cur, grp);
	v_mfma_f32_32x32x16_bf16 v[34:49], v[124:127], v[62:65], v[18:33]
	ds_read_b128 v[124:127], v94 offset:27712
	v_max_i32_e32 v147, v132, v134
	v_min_i32_e32 v132, v132, v134
	v_max_i32_e32 v134, v133, v135
	v_min_i32_e32 v133, v133, v135
	v_max_i32_e32 v135, v136, v140
	v_min_i32_e32 v136, v136, v140
	s_waitcnt lgkmcnt(1)
	v_mfma_f32_32x32x16_bf16 v[34:49], v[128:131], v[58:61], v[34:49]
	ds_read_b128 v[128:131], v94 offset:27744
	v_max_i32_e32 v140, v138, v142
	v_min_i32_e32 v138, v138, v142
	v_max_i32_e32 v142, v137, v141
	v_min_i32_e32 v137, v137, v141
	v_max_i32_e32 v141, v139, v143
	v_min_i32_e32 v139, v139, v143
	s_waitcnt lgkmcnt(1)
	v_mfma_f32_32x32x16_bf16 v[34:49], v[124:127], v[54:57], v[34:49]
	v_min_i32_e32 v143, v144, v145
	v_min_i32_e32 v124, v82, v146
	v_min_i32_e32 v127, v135, v140
	v_min_i32_e32 v125, v147, v134
	v_min_i32_e32 v126, v132, v133
	v_min_i32_e32 v149, v142, v141
	v_min_i32_e32 v148, v136, v138
	s_waitcnt lgkmcnt(0)
	v_mfma_f32_32x32x16_bf16 v[34:49], v[128:131], v[50:53], v[34:49]
	v_min_i32_e32 v150, v137, v139
	s_nop 10
	v_and_or_b32 v37, v37, s43, 60
	v_and_or_b32 v48, v48, s43, 37
	v_and_or_b32 v38, v38, s43, 55
	v_and_or_b32 v42, v42, s43, 47
	v_bitop3_b32 v34, v34, s42, 64 bitop3:0x56
	v_and_or_b32 v47, v47, s43, 38
	v_and_or_b32 v39, v39, s43, 54
	v_and_or_b32 v40, v40, s43, 53
	v_and_or_b32 v43, v43, s43, 46
	v_and_or_b32 v44, v44, s43, 45
	v_and_or_b32 v36, v36, s43, 61
	v_and_or_b32 v49, v49, s43, 36
	v_and_or_b32 v41, v41, s43, 52
	v_and_or_b32 v45, v45, s43, 44
	v_and_or_b32 v35, v35, s43, 62
	v_and_or_b32 v46, v46, s43, 39
	v_max_i32_e32 v128, v37, v48
	v_max_i32_e32 v129, v38, v42
	v_max_i32_e32 v131, v34, v47
	v_max_i32_e32 v151, v39, v40
	v_min_i32_e32 v154, v43, v44
	v_min_i32_e32 v155, v36, v49
	v_min_i32_e32 v157, v41, v45
	v_min_i32_e32 v158, v35, v46
	v_min_i32_e32 v39, v39, v40
	v_min_i32_e32 v34, v34, v47
	v_min_i32_e32 v38, v38, v42
	v_min_i32_e32 v37, v37, v48
	v_max_i32_e32 v35, v35, v46
	v_max_i32_e32 v41, v41, v45
	v_max_i32_e32 v36, v36, v49
	v_max_i32_e32 v43, v43, v44
	v_min_i32_e32 v130, v128, v129
	v_min_i32_e32 v152, v131, v151
	v_max_i32_e32 v156, v154, v155
	v_max_i32_e32 v159, v157, v158
	v_max_i32_e32 v40, v39, v34
	v_max_i32_e32 v42, v38, v37
	v_min_i32_e32 v45, v35, v41
	v_min_i32_e32 v44, v36, v43
	v_min_i32_e32 v157, v157, v158
	v_min_i32_e32 v34, v39, v34
	v_min_i32_e32 v37, v38, v37
	v_min_i32_e32 v38, v154, v155
	v_max_i32_e32 v131, v131, v151
	v_max_i32_e32 v35, v35, v41
	v_max_i32_e32 v36, v36, v43
	v_max_i32_e32 v43, v128, v129
	v_min_i32_e32 v153, v130, v152
	v_min_i32_e32 v160, v156, v159
	v_max_i32_e32 v47, v40, v42
	v_max_i32_e32 v46, v45, v44
	v_min_i32_e32 v40, v40, v42
	v_min_i32_e32 v42, v45, v44
	v_max_i32_e32 v45, v130, v152
	v_max_i32_e32 v130, v156, v159
	v_min_i32_e32 v39, v157, v34
	v_min_i32_e32 v154, v37, v38
	v_max_i32_e32 v34, v157, v34
	v_max_i32_e32 v37, v37, v38
	v_min_i32_e32 v41, v131, v35
	v_min_i32_e32 v128, v36, v43
	v_max_i32_e32 v35, v131, v35
	v_max_i32_e32 v36, v36, v43
	v_min_i32_e32 v48, v47, v46
	v_max_i32_e32 v44, v40, v42
	v_min_i32_e32 v152, v45, v130
	v_min_i32_e32 v40, v40, v42
	v_min_i32_e32 v42, v153, v160
	v_max_i32_e32 v155, v39, v154
	v_min_i32_e32 v38, v34, v37
	v_min_i32_e32 v129, v41, v128
	v_max_i32_e32 v41, v41, v128
	v_min_i32_e32 v43, v35, v36
	v_max_i32_e32 v45, v45, v130
	v_max_i32_e32 v46, v47, v46
	v_max_i32_e32 v161, v153, v160
	v_max_i32_e32 v153, v40, v42
	v_max_i32_e32 v157, v155, v38
	v_max_i32_e32 v34, v34, v37
	v_min_i32_e32 v128, v41, v43
	v_min_i32_e32 v47, v45, v46
	v_min_i32_e32 v49, v161, v48
	v_min_i32_e32 v156, v44, v152
	v_max_i32_e32 v158, v153, v157
	v_min_i32_e32 v37, v129, v34
	v_max_i32_e32 v34, v129, v34
	v_min_i32_e32 v129, v128, v47
	v_max_i32_e32 v48, v161, v48
	v_max_i32_e32 v44, v44, v152
	v_min_i32_e32 v40, v40, v42
	v_min_i32_e32 v38, v155, v38
	v_max_i32_e32 v159, v49, v156
	v_max_i32_e32 v151, v158, v37
	v_min_i32_e32 v130, v34, v129
	v_min_i32_e32 v131, v48, v44
	v_min_i32_e32 v49, v49, v156
	v_min_i32_e32 v37, v158, v37
	v_max_i32_e32 v34, v34, v129
	v_max_i32_e32 v44, v48, v44
	v_max_i32_e32 v42, v40, v38
	v_min_i32_e32 v153, v153, v157
	v_max_i32_e32 v160, v159, v151
	v_min_i32_e32 v152, v130, v131
	v_max_i32_e32 v156, v49, v37
	v_min_i32_e32 v48, v34, v44
	v_max_i32_e32 v129, v130, v131
	v_max_i32_e32 v155, v42, v153
	v_min_i32_e32 v37, v49, v37
	v_min_i32_e32 v151, v159, v151
	v_min_i32_e32 v130, v48, v129
	v_max_i32_e32 v131, v160, v152
	v_min_i32_e32 v49, v155, v37
	v_max_i32_e32 v41, v41, v43
	v_max_i32_e32 v43, v45, v46
	v_min_i32_e32 v42, v42, v153
	v_min_i32_e32 v38, v40, v38
	v_min_i32_e32 v161, v160, v152
	v_max_i32_e32 v158, v151, v156
	v_min_i32_e32 v151, v151, v156
	v_max_i32_e32 v34, v34, v44
	v_max_i32_e32 v44, v128, v47
	v_min_i32_e32 v45, v41, v43
	v_max_i32_e32 v40, v41, v43
	v_max_i32_e32 v38, v143, v38
	v_max3_i32 v41, v82, v146, v42
	v_max_i32_e32 v42, v124, v49
	v_max3_i32 v124, v127, v130, v131
	v_min_i32_e32 v46, v44, v45
	v_max_i32_e32 v43, v125, v151
	v_max3_i32 v49, v126, v161, v158
	v_max3_i32 v44, v149, v44, v45
	v_max_i32_e32 v45, v38, v124
	v_min_i32_e32 v38, v38, v124
	ds_read_b128 v[124:127], v98
	v_min_i32_e32 v159, v161, v158
	v_min_i32_e32 v152, v130, v131
	v_max_i32_e32 v37, v155, v37
	v_max_i32_e32 v48, v48, v129
	v_min_i32_e32 v47, v34, v46
	v_max_i32_e32 v34, v34, v46
	v_min_i32_e32 v39, v39, v154
	v_max3_i32 v39, v144, v145, v39
	v_max3_i32 v37, v147, v134, v37
	v_max3_i32 v46, v132, v133, v159
	v_max3_i32 v82, v135, v140, v152
	v_max3_i32 v48, v136, v138, v48
	v_max_i32_e32 v47, v148, v47
	v_max3_i32 v34, v142, v141, v34
	v_max3_i32 v40, v137, v139, v40
	v_max3_i32 v35, v150, v35, v36
	v_max_i32_e32 v36, v39, v82
	v_min_i32_e32 v39, v39, v82
	v_max_i32_e32 v82, v41, v48
	v_min_i32_e32 v41, v41, v48
	v_max_i32_e32 v48, v42, v47
	v_min_i32_e32 v42, v42, v47
	v_max_i32_e32 v47, v37, v34
	v_min_i32_e32 v34, v37, v34
	v_max_i32_e32 v37, v43, v44
	v_min_i32_e32 v43, v43, v44
	v_max_i32_e32 v44, v46, v40
	v_min_i32_e32 v40, v46, v40
	v_max_i32_e32 v46, v49, v35
	v_min_i32_e32 v35, v49, v35
	v_max_i32_e32 v49, v36, v47
	v_min_i32_e32 v132, v36, v47
	v_max_i32_e32 v36, v45, v37
	v_min_i32_e32 v133, v45, v37
	v_max_i32_e32 v37, v82, v44
	v_min_i32_e32 v82, v82, v44
	v_max_i32_e32 v44, v48, v46
	ds_read_b128 v[128:131], v98 offset:32
	v_min_i32_e32 v134, v48, v46
	v_max_i32_e32 v135, v39, v34
	v_min_i32_e32 v136, v39, v34
	v_max_i32_e32 v137, v38, v43
	v_min_i32_e32 v138, v38, v43
	v_max_i32_e32 v139, v41, v40
	v_min_i32_e32 v140, v41, v40
	v_max_i32_e32 v141, v42, v35
	v_min_i32_e32 v142, v42, v35
	v_max_i32_e32 v143, v49, v37
	v_min_i32_e32 v144, v49, v37
	v_max_i32_e32 v145, v36, v44
	v_min_i32_e32 v146, v36, v44
	s_waitcnt lgkmcnt(1)
; #define LAS __attribute__((address_space(3)))
; #define MFMA32(a, b, c) __builtin_amdgcn_mfma_f32_32x32x16_bf16((a), (b), (c), 0, 0, 0)
; __device__ __forceinline__ void route_task(int task, int tl0, const bf16* QP  , const LAS bf16* KHL, LAS unsigned short* EL, LAS float* GL, int lane) {
;     ...
; #pragma unroll
;         for (int kt = 0; kt < 4; ++kt) {
;             f32x16 X;
; #pragma unroll
;             for (int i = 0; i < 16; ++i) X[i] = 8.f;
;             const LAS bf16* khp = KHL + (half * 128 + 32 * kt + r) * 72 + 8 * hi;
; #pragma unroll
;             for (int ks = 0; ks < 4; ++ks) {
;                 const bf16x8 kh = lds8(khp + 16 * ks);
;                 X = MFMA32(kh, qa[half][ks], X);
;             }
;             int grp[16];
; #pragma unroll
;             for (int i = 0; i < 16; ++i) grp[i] = (int)((__float_as_uint(X[i]) | 127u) - (unsigned)(32 * kt + (i & 3) + 8 * (i >> 2)));
;             sort16_desc(grp);
;             if (kt == 0) {
; #pragma unroll
;                 for (int i = 0; i < 16; ++i) cur[i] = grp[i];
;             } else merge16_desc(cur, grp);
;         }
	v_mfma_f32_32x32x16_bf16 v[34:49], v[124:127], v[62:65], v[18:33]
	v_max_i32_e32 v147, v132, v82
	s_nop 5
	ds_read_b128 v[18:21], v98 offset:64
	ds_read_b128 v[22:25], v98 offset:96
	s_waitcnt lgkmcnt(2)
	v_mfma_f32_32x32x16_bf16 v[34:49], v[128:131], v[58:61], v[34:49]
	v_min_i32_e32 v26, v132, v82
	v_max_i32_e32 v27, v133, v134
	v_min_i32_e32 v30, v135, v139
	v_min_i32_e32 v32, v137, v141
	v_max_i32_e32 v33, v136, v140
	v_max_i32_e32 v59, v138, v142
	v_min_i32_e32 v28, v133, v134
	s_waitcnt lgkmcnt(1)
	v_mfma_f32_32x32x16_bf16 v[34:49], v[18:21], v[54:57], v[34:49]
	v_min_i32_e32 v19, v147, v27
	v_min_i32_e32 v54, v30, v32
	v_min_i32_e32 v55, v33, v59
	v_max_i32_e32 v29, v135, v139
	v_max_i32_e32 v31, v137, v141
	v_min_i32_e32 v58, v136, v140
	v_min_i32_e32 v60, v138, v142
	s_waitcnt lgkmcnt(0)
	v_mfma_f32_32x32x16_bf16 v[34:49], v[22:25], v[50:53], v[34:49]
	v_min_i32_e32 v18, v144, v146
	v_min_i32_e32 v61, v143, v145
	v_min_i32_e32 v20, v26, v28
	v_min_i32_e32 v21, v29, v31
	v_min_i32_e32 v56, v58, v60
	s_nop 6
	v_or_b32_e32 v22, 0x7f, v41
	v_or_b32_e32 v23, 0x7f, v45
	v_or_b32_e32 v25, 0x7f, v35
	v_or_b32_e32 v35, 0x7f, v46
	v_and_or_b32 v39, v39, s43, 22
	v_and_or_b32 v40, v40, s43, 21
	v_and_or_b32 v34, v34, s43, 31
	v_and_or_b32 v47, v47, s43, 6
	v_and_or_b32 v38, v38, s43, 23
	v_and_or_b32 v42, v42, s43, 15
	v_and_or_b32 v37, v37, s43, 28
	v_and_or_b32 v48, v48, s43, 5
	v_and_or_b32 v43, v43, s43, 14
	v_and_or_b32 v44, v44, s43, 13
	v_and_or_b32 v36, v36, s43, 29
	v_and_or_b32 v49, v49, s43, 4
	v_add_u32_e32 v22, 0xffffff95, v22
	v_add_u32_e32 v23, 0xffffff8d, v23
	v_add_u32_e32 v25, 0xffffff9f, v25
	v_add_u32_e32 v35, 0xffffff88, v35
	v_min_i32_e32 v24, v22, v23
	v_min_i32_e32 v41, v25, v35
	v_min_i32_e32 v46, v39, v40
	v_min_i32_e32 v50, v34, v47
	v_min_i32_e32 v53, v38, v42
	v_min_i32_e32 v57, v37, v48
	v_min_i32_e32 v63, v43, v44
	v_min_i32_e32 v64, v36, v49
	v_max_i32_e32 v34, v34, v47
	v_max_i32_e32 v39, v39, v40
	v_max_i32_e32 v25, v25, v35
	v_max_i32_e32 v22, v22, v23
	v_max_i32_e32 v36, v36, v49
	v_max_i32_e32 v43, v43, v44
	v_max_i32_e32 v37, v37, v48
	v_max_i32_e32 v38, v38, v42
	v_min_i32_e32 v45, v24, v41
	v_min_i32_e32 v51, v46, v50
	v_max_i32_e32 v40, v34, v39
	v_max_i32_e32 v23, v25, v22
	v_max_i32_e32 v44, v36, v43
	v_max_i32_e32 v42, v37, v38
	v_min_i32_e32 v37, v37, v38
	v_min_i32_e32 v34, v34, v39
	v_max_i32_e32 v39, v63, v64
	v_max_i32_e32 v24, v24, v41
	v_max_i32_e32 v46, v46, v50
	v_max_i32_e32 v50, v53, v57
	v_min_i32_e32 v22, v25, v22
	v_min_i32_e32 v25, v36, v43
	v_min_i32_e32 v62, v53, v57
	v_min_i32_e32 v65, v63, v64
	v_min_i32_e32 v35, v40, v23
	v_min_i32_e32 v47, v44, v42
	v_max_i32_e32 v23, v40, v23
	v_max_i32_e32 v40, v44, v42
	v_max_i32_e32 v38, v37, v34
	v_max_i32_e32 v41, v39, v24
	v_max_i32_e32 v53, v46, v50
	v_max_i32_e32 v36, v22, v25
	v_min_i32_e32 v46, v46, v50
	v_min_i32_e32 v22, v22, v25
	v_min_i32_e32 v52, v45, v51
	v_min_i32_e32 v82, v62, v65
	v_min_i32_e32 v48, v35, v47
	v_max_i32_e32 v45, v45, v51
	v_max_i32_e32 v49, v62, v65
	v_max_i32_e32 v35, v35, v47
	v_min_i32_e32 v42, v23, v40
	v_max_i32_e32 v47, v38, v41
	v_max_i32_e32 v43, v53, v36
	v_min_i32_e32 v34, v37, v34
	v_min_i32_e32 v24, v39, v24
	v_max_i32_e32 v25, v46, v22
	v_min_i32_e32 v38, v38, v41
	v_max_i32_e32 v51, v45, v49
	v_min_i32_e32 v44, v35, v42
	v_min_i32_e32 v57, v47, v43
	v_max_i32_e32 v37, v34, v24
	v_min_i32_e32 v36, v53, v36
	v_max_i32_e32 v41, v25, v38
	v_min_i32_e32 v25, v25, v38
	v_min_i32_e32 v22, v46, v22
	v_min_i32_e32 v24, v34, v24
	v_max_i32_e32 v38, v52, v82
	v_min_i32_e32 v45, v45, v49
	v_max_i32_e32 v62, v48, v51
	v_min_i32_e32 v63, v44, v57
	v_max_i32_e32 v39, v37, v36
	v_max_i32_e32 v34, v22, v24
	v_max_i32_e32 v46, v38, v45
	v_max_i32_e32 v64, v62, v63
	v_max_i32_e32 v50, v39, v41
	v_min_i32_e32 v62, v62, v63
	v_min_i32_e32 v39, v39, v41
	v_min_i32_e32 v36, v37, v36
	v_max_i32_e32 v49, v34, v46
	v_min_i32_e32 v48, v48, v51
	v_min_i32_e32 v22, v22, v24
	v_min_i32_e32 v24, v38, v45
	v_min_i32_e32 v53, v64, v50
	v_max_i32_e32 v41, v62, v39
	v_max_i32_e32 v37, v36, v25
	v_max_i32_e32 v51, v49, v48
	v_max_i32_e32 v38, v22, v24
	v_min_i32_e32 v34, v34, v46
	v_min_i32_e32 v25, v36, v25
	v_min_i32_e32 v36, v49, v48
	v_min_i32_e32 v124, v52, v82
	v_max_i32_e32 v52, v37, v51
	v_min_i32_e32 v39, v62, v39
	v_max_i32_e32 v45, v38, v34
	v_min_i32_e32 v46, v25, v36
	v_max_i32_e32 v35, v35, v42
	v_max_i32_e32 v42, v47, v43
	v_min_i32_e32 v34, v38, v34
	v_max_i32_e32 v38, v53, v41
	v_min_i32_e32 v37, v37, v51
	v_max_i32_e32 v25, v25, v36
	v_max_i32_e32 v48, v45, v46
	v_max_i32_e32 v44, v44, v57
	v_min_i32_e32 v43, v35, v42
	v_max3_i32 v30, v30, v32, v38
	v_min_i32_e32 v38, v52, v39
	v_max_i32_e32 v36, v37, v25
	v_min_i32_e32 v25, v37, v25
	v_min_i32_e32 v63, v53, v41
	v_max_i32_e32 v62, v52, v39
	v_max3_i32 v27, v147, v27, v48
	v_max_i32_e32 v48, v64, v50
	v_min_i32_e32 v47, v44, v43
	v_min_i32_e32 v39, v38, v36
	v_max_i32_e32 v19, v19, v25
	v_max3_i32 v25, v55, v44, v43
	v_min_i32_e32 v43, v45, v46
	v_min_i32_e32 v65, v63, v62
	v_max_i32_e32 v49, v48, v47
	v_max3_i32 v26, v26, v28, v39
	v_max_i32_e32 v28, v35, v42
	v_min_i32_e32 v22, v22, v24
	v_max_i32_e32 v18, v18, v43
	v_min_i32_e32 v43, v48, v47
	v_max3_i32 v124, v143, v145, v124
	v_max3_i32 v29, v29, v31, v65
	v_max3_i32 v33, v33, v59, v49
	v_max3_i32 v34, v144, v146, v34
	v_max3_i32 v28, v58, v60, v28
	v_max_i32_e32 v22, v61, v22
	v_max3_i32 v21, v21, v63, v62
	v_max_i32_e32 v43, v54, v43
	v_max3_i32 v20, v20, v38, v36
	v_max3_i32 v23, v56, v23, v40
	v_min_i32_e32 v31, v124, v29
	v_min_i32_e32 v49, v27, v33
	v_min_i32_e32 v32, v34, v30
	v_min_i32_e32 v35, v26, v28
; __device__ __forceinline__ void route_task(int task, int tl0, const bf16* QP  , const LAS bf16* KHL, LAS unsigned short* EL, LAS float* GL, int lane) {
;     ...
;             } else merge16_desc(cur, grp);
;         }
;         { const unsigned h4 = 4u * (unsigned)hi;
; #pragma unroll
;           for (int i = 0; i < 16; ++i) cur[i] -= (int)h4; }
;         int oth[16];
; #pragma unroll
;         for (int i = 0; i < 16; ++i) oth[i] = __shfl_xor(cur[i], 32);
;         merge16_desc(cur, oth);
; #pragma unroll
;         for (int i = 0; i < 16; ++i) top[half][i] = cur[i];
;     }
;     unsigned P1[4], P2[4];
; #pragma unroll
;     for (int q = 0; q < 4; ++q) { P1[q] = 0u; P2[q] = 0u;
; #pragma unroll
;         for (int s = 0; s < 4; ++s) { P1[q] |= (127u - ((unsigned)top[0][4 * q + s] & 127u)) << (8 * s); P2[q] |= (127u - ((unsigned)top[1][4 * q + s] & 127u)) << (8 * s); } }
	v_min_i32_e32 v24, v22, v21
	v_min_i32_e32 v37, v19, v25
	v_min_i32_e32 v44, v18, v43
	v_min_i32_e32 v36, v20, v23
	v_max_i32_e32 v29, v124, v29
	v_max_i32_e32 v27, v27, v33
	v_max_i32_e32 v30, v34, v30
	v_max_i32_e32 v26, v26, v28
	v_max_i32_e32 v21, v22, v21
	v_max_i32_e32 v19, v19, v25
	v_max_i32_e32 v18, v18, v43
	v_max_i32_e32 v20, v20, v23
	v_max_i32_e32 v33, v29, v27
	v_max_i32_e32 v28, v30, v26
	v_max_i32_e32 v22, v21, v19
	v_max_i32_e32 v23, v18, v20
	v_max_i32_e32 v34, v33, v28
	v_max_i32_e32 v25, v22, v23
	v_min_i32_e32 v28, v33, v28
	v_min_i32_e32 v22, v22, v23
	v_min_i32_e32 v27, v29, v27
	v_min_i32_e32 v26, v30, v26
	v_min_i32_e32 v19, v21, v19
	v_min_i32_e32 v18, v18, v20
	v_max_i32_e32 v23, v28, v22
	v_min_i32_e32 v22, v28, v22
	v_max_i32_e32 v28, v27, v26
	v_max_i32_e32 v20, v19, v18
	v_min_i32_e32 v26, v27, v26
	v_min_i32_e32 v18, v19, v18
	v_min_i32_e32 v42, v24, v37
	v_max_i32_e32 v19, v26, v18
	v_min_i32_e32 v18, v26, v18
	v_max_i32_e32 v26, v31, v49
	v_max_i32_e32 v27, v32, v35
	v_max_i32_e32 v24, v24, v37
	v_max_i32_e32 v29, v44, v36
	v_min_i32_e32 v50, v31, v49
	v_min_i32_e32 v39, v32, v35
	v_min_i32_e32 v38, v44, v36
	v_max_i32_e32 v21, v28, v20
	v_min_i32_e32 v20, v28, v20
	v_max_i32_e32 v28, v26, v27
	v_max_i32_e32 v30, v24, v29
	v_min_i32_e32 v26, v26, v27
	v_min_i32_e32 v24, v24, v29
	v_min_i32_e32 v41, v50, v39
	v_min_i32_e32 v40, v42, v38
	v_max_i32_e32 v27, v26, v24
	v_min_i32_e32 v24, v26, v24
	v_max_i32_e32 v26, v50, v39
	v_max_i32_e32 v29, v42, v38
	v_min_i32_e32 v45, v41, v40
	v_max_i32_e32 v43, v34, v25
	v_min_i32_e32 v25, v34, v25
	v_max_i32_e32 v31, v28, v30
	v_min_i32_e32 v28, v28, v30
	v_max_i32_e32 v30, v26, v29
	v_min_i32_e32 v26, v26, v29
	v_max_i32_e32 v29, v41, v40
	v_sub_u32_e32 v32, v43, v87
	v_sub_u32_e32 v25, v25, v87
	v_sub_u32_e32 v23, v23, v87
	v_sub_u32_e32 v22, v22, v87
	v_sub_u32_e32 v21, v21, v87
	v_sub_u32_e32 v20, v20, v87
	v_sub_u32_e32 v19, v19, v87
	v_sub_u32_e32 v18, v18, v87
	v_sub_u32_e32 v31, v31, v87
	v_sub_u32_e32 v28, v28, v87
	v_sub_u32_e32 v27, v27, v87
	v_sub_u32_e32 v24, v24, v87
	v_sub_u32_e32 v30, v30, v87
	v_sub_u32_e32 v26, v26, v87
	v_sub_u32_e32 v29, v29, v87
	v_sub_u32_e32 v33, v45, v87
	ds_bpermute_b32 v34, v123, v32
	ds_bpermute_b32 v35, v123, v25
	ds_bpermute_b32 v36, v123, v23
	ds_bpermute_b32 v37, v123, v22
	ds_bpermute_b32 v38, v123, v21
	ds_bpermute_b32 v39, v123, v20
	ds_bpermute_b32 v40, v123, v19
	ds_bpermute_b32 v41, v123, v18
	ds_bpermute_b32 v42, v123, v31
	ds_bpermute_b32 v43, v123, v28
	ds_bpermute_b32 v44, v123, v27
	ds_bpermute_b32 v45, v123, v33
	ds_bpermute_b32 v46, v123, v29
	ds_bpermute_b32 v47, v123, v26
	ds_bpermute_b32 v48, v123, v30
	ds_bpermute_b32 v49, v123, v24
	s_waitcnt lgkmcnt(4)
	v_max_i32_e32 v32, v32, v45
	s_waitcnt lgkmcnt(3)
	v_max_i32_e32 v25, v25, v46
	s_waitcnt lgkmcnt(2)
	v_max_i32_e32 v23, v23, v47
	s_waitcnt lgkmcnt(1)
	v_max_i32_e32 v22, v22, v48
	s_waitcnt lgkmcnt(0)
	v_max_i32_e32 v21, v21, v49
	v_max_i32_e32 v20, v20, v44
	v_max_i32_e32 v19, v19, v43
	v_max_i32_e32 v18, v18, v42
	v_max_i32_e32 v31, v31, v41
	v_max_i32_e32 v28, v28, v40
	v_max_i32_e32 v27, v27, v39
	v_max_i32_e32 v24, v24, v38
	v_max_i32_e32 v30, v30, v37
	v_max_i32_e32 v26, v26, v36
	v_max_i32_e32 v29, v29, v35
	v_max_i32_e32 v33, v33, v34
	v_max_i32_e32 v34, v32, v31
	v_min_i32_e32 v31, v32, v31
	v_max_i32_e32 v32, v25, v28
	v_min_i32_e32 v25, v25, v28
	v_max_i32_e32 v28, v23, v27
	v_min_i32_e32 v23, v23, v27
	v_max_i32_e32 v27, v22, v24
	v_min_i32_e32 v22, v22, v24
	v_max_i32_e32 v24, v21, v30
	v_min_i32_e32 v21, v21, v30
	v_max_i32_e32 v30, v20, v26
	v_min_i32_e32 v20, v20, v26
	v_max_i32_e32 v26, v19, v29
	v_min_i32_e32 v19, v19, v29
	v_max_i32_e32 v29, v18, v33
	v_min_i32_e32 v18, v18, v33
	v_max_i32_e32 v33, v34, v24
	v_min_i32_e32 v24, v34, v24
	v_max_i32_e32 v34, v32, v30
	v_min_i32_e32 v30, v32, v30
	v_max_i32_e32 v32, v28, v26
	v_min_i32_e32 v26, v28, v26
	v_max_i32_e32 v28, v27, v29
	v_min_i32_e32 v27, v27, v29
	v_max_i32_e32 v29, v31, v21
	v_min_i32_e32 v21, v31, v21
	v_max_i32_e32 v31, v25, v20
	v_min_i32_e32 v20, v25, v20
	v_max_i32_e32 v25, v23, v19
	v_min_i32_e32 v19, v23, v19
	v_max_i32_e32 v23, v22, v18
	v_min_i32_e32 v18, v22, v18
	v_max_i32_e32 v22, v33, v32
	v_min_i32_e32 v32, v33, v32
	v_max_i32_e32 v33, v34, v28
	v_min_i32_e32 v28, v34, v28
	v_max_i32_e32 v34, v24, v26
	v_min_i32_e32 v24, v24, v26
	v_max_i32_e32 v35, v30, v27
	v_min_i32_e32 v27, v30, v27
	v_max_i32_e32 v30, v29, v25
	v_min_i32_e32 v25, v29, v25
	v_max_i32_e32 v29, v31, v23
	v_min_i32_e32 v23, v31, v23
	v_max_i32_e32 v31, v21, v19
	v_min_i32_e32 v19, v21, v19
	v_max_i32_e32 v21, v20, v18
	v_min_i32_e32 v18, v20, v18
	v_max_i32_e32 v26, v22, v33
	v_min_i32_e32 v33, v22, v33
	v_lshlrev_b32_e32 v20, 8, v81
	v_lshlrev_b32_e32 v22, 16, v80
	v_max_i32_e32 v36, v32, v28
	v_max_i32_e32 v40, v19, v18
	v_min_i32_e32 v41, v19, v18
	v_and_b32_e32 v18, 0x7f, v79
	v_and_b32_e32 v20, 0x7f00, v20
	v_and_b32_e32 v22, 0x7f0000, v22
	v_max_i32_e32 v39, v31, v21
	v_min_i32_e32 v31, v31, v21
	v_lshlrev_b32_e32 v21, 8, v33
	v_or3_b32 v18, v20, v18, v22
	v_lshlrev_b32_e32 v20, 16, v36
	v_and_b32_e32 v19, 0x7f, v26
	v_and_b32_e32 v21, 0x7f00, v21
	v_and_b32_e32 v20, 0x7f0000, v20
	v_or3_b32 v20, v21, v19, v20
	v_lshlrev_b32_e32 v19, 24, v78
	v_min_i32_e32 v28, v32, v28
	v_and_b32_e32 v19, 0x7f000000, v19
	v_bitop3_b32 v19, v18, s68, v19 bitop3:0x36
	v_lshlrev_b32_e32 v18, 24, v28
	v_max_i32_e32 v32, v34, v35
	v_min_i32_e32 v34, v34, v35
	v_max_i32_e32 v35, v24, v27
	v_min_i32_e32 v27, v24, v27
	v_and_b32_e32 v18, 0x7f000000, v18
	v_lshlrev_b32_e32 v22, 8, v76
	v_lshlrev_b32_e32 v24, 16, v75
; __device__ __forceinline__ void route_task(int task, int tl0, const bf16* QP  , const LAS bf16* KHL, LAS unsigned short* EL, LAS float* GL, int lane) {
;     ...
;     for (int q = 0; q < 4; ++q) { P1[q] = 0u; P2[q] = 0u;
; #pragma unroll
;         for (int s = 0; s < 4; ++s) { P1[q] |= (127u - ((unsigned)top[0][4 * q + s] & 127u)) << (8 * s); P2[q] |= (127u - ((unsigned)top[1][4 * q + s] & 127u)) << (8 * s); } }
;     int bk[16];
;     {
;         int hi2 = hi; asm volatile("" : "+v"(hi2));
;         const bool h1 = hi2 != 0;
;         constexpr int A1[16] = {1, 1, 1, 1, 1, 1, 1, 1, 2, 2, 2, 2, 2, 3, 3, 3}, B1[16] = {0, 1, 2, 3, 4, 5, 6, 7, 0, 1, 2, 3, 4, 0, 1, 2};
; #pragma unroll
;         for (int i = 0; i < 16; ++i) { const float ta = __int_as_float(h1 ? top[0][A1[i]] : top[0][0]), tb = __int_as_float(h1 ? top[1][B1[i]] : top[1][i]); const unsigned code = h1 ? (unsigned)(A1[i] * 16 + B1[i]) : (unsigned)i;
;             bk[i] = (int)((__float_as_uint(ta + tb) | 255u) - code); }
;         sort16_desc(bk);
	v_bitop3_b32 v18, v20, s68, v18 bitop3:0x36
	v_and_b32_e32 v20, 0x7f, v77
	v_and_b32_e32 v22, 0x7f00, v22
	v_and_b32_e32 v24, 0x7f0000, v24
	v_max_i32_e32 v37, v30, v29
	v_min_i32_e32 v29, v30, v29
	v_max_i32_e32 v30, v25, v23
	v_min_i32_e32 v38, v25, v23
	v_lshlrev_b32_e32 v23, 8, v34
	v_or3_b32 v20, v22, v20, v24
	v_lshlrev_b32_e32 v22, 16, v35
	v_and_b32_e32 v21, 0x7f, v32
	v_and_b32_e32 v23, 0x7f00, v23
	v_and_b32_e32 v22, 0x7f0000, v22
	v_or3_b32 v22, v23, v21, v22
	v_lshlrev_b32_e32 v21, 24, v73
	v_and_b32_e32 v21, 0x7f000000, v21
	v_bitop3_b32 v21, v20, s68, v21 bitop3:0x36
	v_lshlrev_b32_e32 v20, 24, v27
	v_and_b32_e32 v20, 0x7f000000, v20
	v_lshlrev_b32_e32 v24, 8, v74
	v_lshlrev_b32_e32 v42, 16, v72
	v_bitop3_b32 v20, v22, s68, v20 bitop3:0x36
	v_and_b32_e32 v22, 0x7f, v71
	v_and_b32_e32 v24, 0x7f00, v24
	v_and_b32_e32 v42, 0x7f0000, v42
	v_lshlrev_b32_e32 v25, 8, v29
	v_or3_b32 v22, v24, v22, v42
	v_lshlrev_b32_e32 v24, 16, v30
	v_and_b32_e32 v23, 0x7f, v37
	v_and_b32_e32 v25, 0x7f00, v25
	v_and_b32_e32 v24, 0x7f0000, v24
	v_or3_b32 v24, v25, v23, v24
	v_lshlrev_b32_e32 v23, 24, v70
	v_and_b32_e32 v23, 0x7f000000, v23
	v_bitop3_b32 v23, v22, s68, v23 bitop3:0x36
	v_lshlrev_b32_e32 v22, 24, v38
	v_and_b32_e32 v22, 0x7f000000, v22
	v_lshlrev_b32_e32 v42, 8, v68
	v_lshlrev_b32_e32 v44, 16, v67
	v_bitop3_b32 v22, v24, s68, v22 bitop3:0x36
	v_and_b32_e32 v24, 0x7f, v69
	v_and_b32_e32 v42, 0x7f00, v42
	v_and_b32_e32 v44, 0x7f0000, v44
	v_lshlrev_b32_e32 v43, 8, v31
	v_or3_b32 v24, v42, v24, v44
	v_lshlrev_b32_e32 v42, 16, v40
	v_and_b32_e32 v25, 0x7f, v39
	v_and_b32_e32 v43, 0x7f00, v43
	v_and_b32_e32 v42, 0x7f0000, v42
	v_or3_b32 v42, v43, v25, v42
	v_lshlrev_b32_e32 v25, 24, v66
	v_and_b32_e32 v25, 0x7f000000, v25
	v_bitop3_b32 v25, v24, s68, v25 bitop3:0x36
	v_lshlrev_b32_e32 v24, 24, v41
	v_and_b32_e32 v24, 0x7f000000, v24
	v_bitop3_b32 v24, v42, s68, v24 bitop3:0x36
	v_mov_b32_e32 v42, v86
	v_add_f32_e32 v62, v74, v26
	v_cmp_eq_u32_e32 vcc, 0, v42
	v_add_f32_e32 v63, v72, v26
	v_add_f32_e32 v64, v70, v26
	v_cndmask_b32_e32 v42, v81, v79, vcc
	v_add_f32_e32 v44, v42, v26
	v_cndmask_b32_e64 v43, -16, 0, vcc
	v_or_b32_e32 v44, 0xff, v44
	v_add_f32_e32 v45, v42, v33
	v_add_u32_e32 v43, v44, v43
	v_cndmask_b32_e64 v44, v99, -1, vcc
	v_or_b32_e32 v45, 0xff, v45
	v_add_f32_e32 v46, v42, v36
	v_add_u32_e32 v44, v45, v44
	v_cndmask_b32_e64 v45, v100, -2, vcc
	v_or_b32_e32 v46, 0xff, v46
	v_add_f32_e32 v47, v42, v28
	v_add_u32_e32 v45, v46, v45
	v_cndmask_b32_e64 v46, v101, -3, vcc
	v_or_b32_e32 v47, 0xff, v47
	v_add_f32_e32 v48, v42, v32
	v_add_u32_e32 v46, v47, v46
	v_cndmask_b32_e64 v47, v102, -4, vcc
	v_or_b32_e32 v48, 0xff, v48
	v_add_f32_e32 v34, v42, v34
	v_add_f32_e32 v35, v42, v35
	v_add_f32_e32 v27, v42, v27
	v_cndmask_b32_e32 v42, v80, v79, vcc
	v_cndmask_b32_e32 v32, v32, v39, vcc
	v_add_u32_e32 v47, v48, v47
	v_cndmask_b32_e64 v48, v103, -5, vcc
	v_or_b32_e32 v34, 0xff, v34
	v_add_f32_e32 v32, v42, v32
	v_add_u32_e32 v34, v34, v48
	v_cndmask_b32_e64 v48, v104, -6, vcc
	v_or_b32_e32 v35, 0xff, v35
	v_cndmask_b32_e32 v37, v26, v37, vcc
	v_cndmask_b32_e64 v39, v116, -12, vcc
	v_or_b32_e32 v32, 0xff, v32
	v_add_u32_e32 v35, v35, v48
	v_cndmask_b32_e64 v48, v105, -7, vcc
	v_or_b32_e32 v27, 0xff, v27
	v_add_f32_e32 v37, v42, v37
	v_cndmask_b32_e32 v29, v33, v29, vcc
	v_add_u32_e32 v32, v32, v39
	v_cndmask_b32_e32 v39, v78, v79, vcc
	v_cndmask_b32_e32 v31, v26, v31, vcc
	v_add_u32_e32 v27, v27, v48
	v_cndmask_b32_e64 v48, v106, -8, vcc
	v_or_b32_e32 v37, 0xff, v37
	v_add_f32_e32 v29, v42, v29
	v_cndmask_b32_e32 v30, v36, v30, vcc
	v_cndmask_b32_e32 v38, v28, v38, vcc
	v_add_f32_e32 v31, v39, v31
	v_cndmask_b32_e32 v40, v33, v40, vcc
	v_add_u32_e32 v37, v37, v48
	v_cndmask_b32_e64 v48, v107, -9, vcc
	v_or_b32_e32 v29, 0xff, v29
	v_add_f32_e32 v30, v42, v30
	v_add_f32_e32 v38, v42, v38
	v_cndmask_b32_e64 v42, v117, -13, vcc
	v_or_b32_e32 v31, 0xff, v31
	v_add_f32_e32 v40, v39, v40
	v_cndmask_b32_e32 v41, v36, v41, vcc
	v_add_u32_e32 v29, v29, v48
	v_cndmask_b32_e64 v48, v114, -10, vcc
	v_or_b32_e32 v30, 0xff, v30
	v_add_u32_e32 v31, v31, v42
	v_cndmask_b32_e64 v42, v118, -14, vcc
	v_or_b32_e32 v40, 0xff, v40
	v_add_f32_e32 v39, v39, v41
	v_add_u32_e32 v30, v30, v48
	v_cndmask_b32_e64 v48, v115, -11, vcc
	v_or_b32_e32 v38, 0xff, v38
	v_add_u32_e32 v40, v40, v42
	v_cndmask_b32_e64 v42, v119, -15, vcc
	v_or_b32_e32 v39, 0xff, v39
	v_add_u32_e32 v38, v38, v48
	v_add_u32_e32 v39, v39, v42
	v_max_i32_e32 v41, v43, v31
	v_min_i32_e32 v31, v43, v31
	v_max_i32_e32 v42, v44, v32
	v_min_i32_e32 v32, v44, v32
	v_max_i32_e32 v43, v45, v39
	v_min_i32_e32 v39, v45, v39
	v_max_i32_e32 v44, v46, v40
	v_min_i32_e32 v40, v46, v40
	v_max_i32_e32 v45, v47, v37
	v_min_i32_e32 v37, v47, v37
	v_max_i32_e32 v46, v34, v35
	v_min_i32_e32 v34, v34, v35
	v_max_i32_e32 v35, v27, v38
	v_min_i32_e32 v27, v27, v38
	v_max_i32_e32 v38, v29, v30
	v_min_i32_e32 v29, v29, v30
	v_max_i32_e32 v30, v41, v46
	v_min_i32_e32 v41, v41, v46
	v_max_i32_e32 v46, v42, v35
	v_min_i32_e32 v35, v42, v35
	v_max_i32_e32 v42, v43, v38
	v_min_i32_e32 v38, v43, v38
	v_max_i32_e32 v43, v44, v45
	v_min_i32_e32 v44, v44, v45
	v_max_i32_e32 v45, v34, v31
	v_min_i32_e32 v31, v34, v31
	v_max_i32_e32 v34, v37, v40
	v_min_i32_e32 v37, v37, v40
	v_max_i32_e32 v40, v29, v39
	v_min_i32_e32 v29, v29, v39
	v_max_i32_e32 v39, v27, v32
	v_min_i32_e32 v27, v27, v32
	v_max_i32_e32 v32, v30, v46
	v_min_i32_e32 v30, v30, v46
	v_max_i32_e32 v46, v42, v43
	v_min_i32_e32 v42, v42, v43
	v_max_i32_e32 v43, v44, v41
	v_min_i32_e32 v41, v44, v41
	v_max_i32_e32 v44, v45, v34
	v_min_i32_e32 v34, v45, v34
; #define CAND(a, b) (int)((__float_as_uint(__int_as_float(top[0][a]) + __int_as_float(top[1][b])) | 255u) - (unsigned)((a) * 16 + (b)))
; __device__ __forceinline__ void route_task(int task, int tl0, const bf16* QP  , const LAS bf16* KHL, LAS unsigned short* EL, LAS float* GL, int lane) {
;     ...
;         sort16_desc(bk);
;         int oth[16];
; #pragma unroll
;         for (int i = 0; i < 16; ++i) oth[i] = __shfl_xor(bk[i], 32);
;         merge16_desc(bk, oth);
;     }
;     ...
;     {
;         int gk[16];
;         gk[0] = CAND(3, 3); gk[1] = CAND(4, 0); gk[2] = CAND(4, 1); gk[3] = CAND(4, 2); gk[4] = CAND(5, 0); gk[5] = CAND(5, 1); gk[6] = CAND(6, 0); gk[7] = CAND(6, 1);
;         gk[8] = CAND(7, 0); gk[9] = CAND(7, 1); gk[10] = CAND(8, 0); gk[11] = CAND(9, 0); gk[12] = CAND(10, 0); gk[13] = CAND(11, 0); gk[14] = CAND(12, 0); gk[15] = CAND(13, 0);
;         sort16_desc(gk);
	v_max_i32_e32 v45, v35, v38
	v_min_i32_e32 v35, v35, v38
	v_max_i32_e32 v38, v40, v39
	v_min_i32_e32 v39, v40, v39
	v_max_i32_e32 v40, v27, v31
	v_min_i32_e32 v27, v27, v31
	v_max_i32_e32 v31, v37, v29
	v_min_i32_e32 v29, v37, v29
	v_max_i32_e32 v37, v32, v46
	v_min_i32_e32 v32, v32, v46
	v_max_i32_e32 v46, v30, v42
	v_min_i32_e32 v30, v30, v42
	v_max_i32_e32 v42, v43, v38
	v_min_i32_e32 v38, v43, v38
	v_max_i32_e32 v43, v41, v39
	v_min_i32_e32 v39, v41, v39
	v_max_i32_e32 v41, v44, v45
	v_min_i32_e32 v44, v44, v45
	v_max_i32_e32 v45, v34, v35
	v_min_i32_e32 v34, v34, v35
	v_max_i32_e32 v35, v40, v31
	v_min_i32_e32 v31, v40, v31
	v_max_i32_e32 v40, v27, v29
	v_min_i32_e32 v27, v27, v29
	v_max_i32_e32 v29, v46, v32
	v_min_i32_e32 v32, v46, v32
	v_max_i32_e32 v46, v30, v35
	v_min_i32_e32 v30, v30, v35
	v_max_i32_e32 v35, v42, v41
	v_min_i32_e32 v41, v42, v41
	v_max_i32_e32 v42, v43, v44
	v_min_i32_e32 v43, v43, v44
	v_max_i32_e32 v44, v45, v38
	v_min_i32_e32 v38, v45, v38
	v_max_i32_e32 v45, v34, v39
	v_min_i32_e32 v34, v34, v39
	v_max_i32_e32 v39, v40, v31
	v_min_i32_e32 v31, v40, v31
	v_max_i32_e32 v40, v29, v35
	v_min_i32_e32 v29, v29, v35
	v_max_i32_e32 v35, v32, v41
	v_min_i32_e32 v32, v32, v41
	v_max_i32_e32 v41, v42, v44
	v_min_i32_e32 v42, v42, v44
	v_max_i32_e32 v44, v43, v38
	v_min_i32_e32 v38, v43, v38
	v_max_i32_e32 v43, v45, v39
	v_min_i32_e32 v39, v45, v39
	v_max_i32_e32 v45, v34, v31
	v_min_i32_e32 v31, v34, v31
	v_max_i32_e32 v34, v35, v29
	v_min_i32_e32 v29, v35, v29
	v_max_i32_e32 v35, v46, v32
	v_min_i32_e32 v32, v46, v32
	v_max_i32_e32 v46, v43, v30
	v_min_i32_e32 v30, v43, v30
	v_max_i32_e32 v43, v45, v39
	v_min_i32_e32 v39, v45, v39
	v_max_i32_e32 v45, v35, v41
	v_min_i32_e32 v35, v35, v41
	v_max_i32_e32 v41, v32, v42
	v_min_i32_e32 v32, v32, v42
	v_max_i32_e32 v42, v44, v46
	v_min_i32_e32 v44, v44, v46
	v_max_i32_e32 v46, v38, v30
	v_min_i32_e32 v30, v38, v30
	v_max_i32_e32 v38, v45, v29
	v_min_i32_e32 v29, v45, v29
	v_max_i32_e32 v45, v35, v41
	v_min_i32_e32 v35, v35, v41
	v_max_i32_e32 v41, v42, v32
	v_min_i32_e32 v32, v42, v32
	v_max_i32_e32 v42, v44, v46
	v_min_i32_e32 v44, v44, v46
	v_max_i32_e32 v46, v43, v30
	v_min_i32_e32 v30, v43, v30
	v_max_i32_e32 v43, v35, v41
	v_min_i32_e32 v35, v35, v41
	v_max_i32_e32 v41, v32, v42
	v_min_i32_e32 v32, v32, v42
	ds_bpermute_b32 v54, v123, v41
	ds_bpermute_b32 v55, v123, v32
	ds_bpermute_b32 v56, v123, v44
	ds_bpermute_b32 v57, v123, v27
	ds_bpermute_b32 v58, v123, v31
	ds_bpermute_b32 v59, v123, v39
	ds_bpermute_b32 v60, v123, v30
	ds_bpermute_b32 v61, v123, v46
	ds_bpermute_b32 v42, v123, v37
	ds_bpermute_b32 v47, v123, v40
	ds_bpermute_b32 v48, v123, v34
	ds_bpermute_b32 v49, v123, v38
	ds_bpermute_b32 v50, v123, v29
	ds_bpermute_b32 v51, v123, v45
	ds_bpermute_b32 v52, v123, v43
	ds_bpermute_b32 v53, v123, v35
	s_waitcnt lgkmcnt(12)
	v_max_i32_e32 v37, v37, v57
	s_waitcnt lgkmcnt(11)
	v_max_i32_e32 v40, v40, v58
	s_waitcnt lgkmcnt(10)
	v_max_i32_e32 v34, v34, v59
	s_waitcnt lgkmcnt(9)
	v_max_i32_e32 v38, v38, v60
	s_waitcnt lgkmcnt(8)
	v_max_i32_e32 v29, v29, v61
	v_max_i32_e32 v45, v45, v56
	v_max_i32_e32 v43, v43, v55
	v_max_i32_e32 v35, v35, v54
	v_add_f32_e32 v28, v78, v28
	v_add_f32_e32 v54, v77, v26
	v_add_f32_e32 v55, v77, v33
	v_add_f32_e32 v36, v77, v36
	v_add_f32_e32 v56, v76, v26
	v_add_f32_e32 v57, v76, v33
	v_add_f32_e32 v58, v75, v26
	v_add_f32_e32 v59, v75, v33
	v_add_f32_e32 v60, v73, v26
	v_add_f32_e32 v33, v73, v33
	v_add_f32_e32 v61, v71, v26
	v_add_f32_e32 v65, v69, v26
	v_add_f32_e32 v68, v68, v26
	v_or_b32_e32 v28, 0xff, v28
	v_or_b32_e32 v54, 0xff, v54
	v_or_b32_e32 v55, 0xff, v55
	v_or_b32_e32 v36, 0xff, v36
	v_or_b32_e32 v56, 0xff, v56
	v_or_b32_e32 v57, 0xff, v57
	v_or_b32_e32 v58, 0xff, v58
	v_or_b32_e32 v59, 0xff, v59
	v_or_b32_e32 v60, 0xff, v60
	v_or_b32_e32 v33, 0xff, v33
	v_or_b32_e32 v61, 0xff, v61
	v_or_b32_e32 v62, 0xff, v62
	v_or_b32_e32 v63, 0xff, v63
	v_or_b32_e32 v64, 0xff, v64
	v_or_b32_e32 v65, 0xff, v65
	v_or_b32_e32 v68, 0xff, v68
	v_subrev_u32_e32 v28, 51, v28
	v_subrev_u32_e32 v54, 64, v54
	v_add_u32_e32 v55, 0xffffffbf, v55
	v_add_u32_e32 v36, 0xffffffbe, v36
	v_add_u32_e32 v56, 0xffffffb0, v56
	v_add_u32_e32 v57, 0xffffffaf, v57
	v_add_u32_e32 v58, 0xffffffa0, v58
	v_add_u32_e32 v59, 0xffffff9f, v59
	v_add_u32_e32 v60, 0xffffff90, v60
	v_add_u32_e32 v33, 0xffffff8f, v33
	v_add_u32_e32 v61, 0xffffff80, v61
	v_add_u32_e32 v62, 0xffffff70, v62
	v_add_u32_e32 v63, 0xffffff60, v63
	v_add_u32_e32 v64, 0xffffff50, v64
	v_add_u32_e32 v65, 0xffffff40, v65
	v_add_u32_e32 v68, 0xffffff30, v68
	v_max_i32_e32 v69, v28, v64
	v_min_i32_e32 v28, v28, v64
	v_max_i32_e32 v64, v54, v63
	v_min_i32_e32 v54, v54, v63
	v_max_i32_e32 v63, v55, v68
	v_min_i32_e32 v55, v55, v68
	v_max_i32_e32 v68, v36, v65
	v_min_i32_e32 v36, v36, v65
	v_max_i32_e32 v65, v56, v60
	v_min_i32_e32 v56, v56, v60
	v_max_i32_e32 v60, v57, v58
	v_min_i32_e32 v57, v57, v58
	v_max_i32_e32 v58, v59, v62
	v_min_i32_e32 v59, v59, v62
	v_max_i32_e32 v62, v33, v61
	v_min_i32_e32 v33, v33, v61
	v_max_i32_e32 v61, v69, v60
	v_min_i32_e32 v60, v69, v60
	v_max_i32_e32 v69, v64, v58
	v_min_i32_e32 v58, v64, v58
	v_max_i32_e32 v64, v63, v62
	v_min_i32_e32 v62, v63, v62
	v_max_i32_e32 v63, v68, v65
	v_min_i32_e32 v65, v68, v65
	v_max_i32_e32 v68, v57, v28
	v_min_i32_e32 v28, v57, v28
	v_max_i32_e32 v57, v56, v36
	v_min_i32_e32 v36, v56, v36
	v_max_i32_e32 v56, v33, v55
	v_min_i32_e32 v33, v33, v55
	v_max_i32_e32 v55, v59, v54
	v_min_i32_e32 v54, v59, v54
	v_max_i32_e32 v59, v61, v69
	v_min_i32_e32 v61, v61, v69
	v_max_i32_e32 v69, v64, v63
	v_min_i32_e32 v63, v64, v63
	v_max_i32_e32 v64, v65, v60
	v_min_i32_e32 v60, v65, v60
	v_max_i32_e32 v65, v68, v57
	v_min_i32_e32 v57, v68, v57
	v_max_i32_e32 v68, v58, v62
	v_min_i32_e32 v58, v58, v62
	v_max_i32_e32 v62, v56, v55
	v_min_i32_e32 v55, v56, v55
	v_max_i32_e32 v56, v54, v28
	v_min_i32_e32 v28, v54, v28
	v_max_i32_e32 v54, v36, v33
	v_min_i32_e32 v33, v36, v33
	v_min_i32_e32 v36, v59, v69
	v_max_i32_e32 v70, v61, v63
	v_min_i32_e32 v61, v61, v63
	v_max_i32_e32 v63, v64, v62
	v_min_i32_e32 v62, v64, v62
	v_max_i32_e32 v64, v60, v55
	v_min_i32_e32 v55, v60, v55
	v_max_i32_e32 v60, v65, v68
	v_min_i32_e32 v65, v65, v68
	v_max_i32_e32 v68, v57, v58
	v_min_i32_e32 v57, v57, v58
	v_max_i32_e32 v58, v56, v54
	v_min_i32_e32 v54, v56, v54
	v_max_i32_e32 v56, v28, v33
	v_min_i32_e32 v28, v28, v33
	v_max_i32_e32 v33, v70, v36
	v_min_i32_e32 v36, v70, v36
	v_max_i32_e32 v70, v61, v58
	v_min_i32_e32 v58, v61, v58
	v_max_i32_e32 v61, v63, v60
	v_min_i32_e32 v60, v63, v60
	v_max_i32_e32 v63, v64, v65
	v_min_i32_e32 v64, v64, v65
	v_max_i32_e32 v65, v68, v62
	v_min_i32_e32 v62, v68, v62
	v_max_i32_e32 v68, v57, v55
	v_min_i32_e32 v55, v57, v55
	v_max_i32_e32 v57, v56, v54
	s_waitcnt lgkmcnt(0)
; #define CAND(a, b) (int)((__float_as_uint(__int_as_float(top[0][a]) + __int_as_float(top[1][b])) | 255u) - (unsigned)((a) * 16 + (b)))
; __device__ __forceinline__ void route_task(int task, int tl0, const bf16* QP  , const LAS bf16* KHL, LAS unsigned short* EL, LAS float* GL, int lane) {
;     ...
;         int oth[16];
; #pragma unroll
;         for (int i = 0; i < 16; ++i) oth[i] = __shfl_xor(bk[i], 32);
;         merge16_desc(bk, oth);
;     }
;     ...
;     {
;         int gk[16];
;         gk[0] = CAND(3, 3); gk[1] = CAND(4, 0); gk[2] = CAND(4, 1); gk[3] = CAND(4, 2); gk[4] = CAND(5, 0); gk[5] = CAND(5, 1); gk[6] = CAND(6, 0); gk[7] = CAND(6, 1);
;         gk[8] = CAND(7, 0); gk[9] = CAND(7, 1); gk[10] = CAND(8, 0); gk[11] = CAND(9, 0); gk[12] = CAND(10, 0); gk[13] = CAND(11, 0); gk[14] = CAND(12, 0); gk[15] = CAND(13, 0);
;         sort16_desc(gk);
;         merge16_desc(bk, gk);
;     }
;     {
;         const int c14 = CAND(14, 0), c15 = CAND(15, 0);
;         const int n14 = max(bk[14], c14), n15 = max(min(bk[14], c14), max(bk[15], c15));
;         bk[14] = n14; bk[15] = n15;
;     }
	v_max_i32_e32 v41, v41, v53
	v_max_i32_e32 v32, v32, v52
	v_max_i32_e32 v44, v44, v51
	v_max_i32_e32 v46, v46, v50
	v_max_i32_e32 v30, v30, v49
	v_max_i32_e32 v39, v39, v48
	v_max_i32_e32 v31, v31, v47
	v_max_i32_e32 v27, v27, v42
	v_min_i32_e32 v54, v56, v54
	v_max_i32_e32 v56, v33, v61
	v_min_i32_e32 v33, v33, v61
	v_max_i32_e32 v61, v36, v60
	v_min_i32_e32 v36, v36, v60
	v_max_i32_e32 v60, v63, v65
	v_min_i32_e32 v63, v63, v65
	v_max_i32_e32 v65, v64, v62
	v_min_i32_e32 v62, v64, v62
	v_max_i32_e32 v64, v68, v57
	v_max_i32_e32 v42, v37, v41
	v_min_i32_e32 v37, v37, v41
	v_max_i32_e32 v41, v40, v32
	v_min_i32_e32 v32, v40, v32
	v_max_i32_e32 v40, v34, v44
	v_min_i32_e32 v34, v34, v44
	v_max_i32_e32 v44, v38, v46
	v_min_i32_e32 v38, v38, v46
	v_max_i32_e32 v46, v29, v30
	v_min_i32_e32 v29, v29, v30
	v_max_i32_e32 v30, v45, v39
	v_min_i32_e32 v39, v45, v39
	v_max_i32_e32 v45, v43, v31
	v_min_i32_e32 v31, v43, v31
	v_max_i32_e32 v43, v35, v27
	v_min_i32_e32 v27, v35, v27
	v_min_i32_e32 v57, v68, v57
	v_max_i32_e32 v68, v55, v54
	v_max_i32_e32 v71, v70, v36
	v_min_i32_e32 v36, v70, v36
	v_max_i32_e32 v70, v64, v58
	v_min_i32_e32 v58, v64, v58
	v_max_i32_e32 v35, v42, v46
	v_min_i32_e32 v42, v42, v46
	v_max_i32_e32 v46, v41, v30
	v_min_i32_e32 v30, v41, v30
	v_max_i32_e32 v41, v40, v45
	v_min_i32_e32 v40, v40, v45
	v_max_i32_e32 v45, v44, v43
	v_min_i32_e32 v43, v44, v43
	v_max_i32_e32 v44, v37, v29
	v_min_i32_e32 v29, v37, v29
	v_max_i32_e32 v37, v32, v39
	v_min_i32_e32 v32, v32, v39
	v_max_i32_e32 v39, v34, v31
	v_min_i32_e32 v31, v34, v31
	v_max_i32_e32 v34, v38, v27
	v_min_i32_e32 v27, v38, v27
	v_min_i32_e32 v54, v55, v54
	v_min_i32_e32 v55, v61, v33
	v_max_i32_e32 v64, v68, v57
	v_min_i32_e32 v57, v68, v57
	v_max_i32_e32 v68, v71, v60
	v_min_i32_e32 v60, v71, v60
	v_max_i32_e32 v71, v36, v63
	v_min_i32_e32 v36, v36, v63
	v_max_i32_e32 v63, v65, v70
	v_min_i32_e32 v65, v65, v70
	v_max_i32_e32 v70, v62, v58
	v_max_i32_e32 v38, v35, v41
	v_min_i32_e32 v35, v35, v41
	v_max_i32_e32 v41, v46, v45
	v_min_i32_e32 v45, v46, v45
	v_max_i32_e32 v46, v42, v40
	v_min_i32_e32 v40, v42, v40
	v_max_i32_e32 v42, v30, v43
	v_min_i32_e32 v30, v30, v43
	v_max_i32_e32 v43, v44, v39
	v_min_i32_e32 v39, v44, v39
	v_max_i32_e32 v44, v37, v34
	v_min_i32_e32 v34, v37, v34
	v_max_i32_e32 v37, v29, v31
	v_min_i32_e32 v29, v29, v31
	v_max_i32_e32 v31, v32, v27
	v_min_i32_e32 v27, v32, v27
	v_min_i32_e32 v58, v62, v58
	v_max_i32_e32 v62, v68, v55
	v_min_i32_e32 v55, v68, v55
	v_max_i32_e32 v68, v60, v71
	v_min_i32_e32 v60, v60, v71
	v_max_i32_e32 v71, v63, v36
	v_min_i32_e32 v36, v63, v36
	v_max_i32_e32 v63, v65, v70
	v_min_i32_e32 v32, v38, v41
	v_min_i32_e32 v47, v35, v45
	v_min_i32_e32 v48, v46, v42
	v_min_i32_e32 v49, v40, v30
	v_min_i32_e32 v50, v43, v44
	v_min_i32_e32 v51, v39, v34
	v_min_i32_e32 v52, v37, v31
	v_min_i32_e32 v53, v29, v27
	v_min_i32_e32 v65, v65, v70
	v_max_i32_e32 v70, v64, v58
	v_min_i32_e32 v58, v64, v58
	v_min_i32_e32 v64, v60, v71
	v_min_i32_e32 v72, v36, v63
	v_max3_i32 v28, v38, v41, v28
	v_max_i32_e32 v32, v32, v54
	v_max3_i32 v35, v35, v45, v57
	v_max_i32_e32 v38, v47, v58
	v_max3_i32 v41, v46, v42, v70
	v_max_i32_e32 v42, v48, v65
	v_max3_i32 v30, v40, v30, v72
	v_max3_i32 v36, v49, v36, v63
	v_max3_i32 v40, v43, v44, v64
	v_max3_i32 v43, v50, v60, v71
	v_max3_i32 v34, v39, v34, v68
	v_max_i32_e32 v39, v51, v55
	v_max3_i32 v31, v37, v31, v62
	v_max3_i32 v33, v52, v61, v33
	v_max3_i32 v27, v29, v27, v56
	v_max3_i32 v29, v53, v59, v69
	v_max_i32_e32 v37, v28, v40
	v_min_i32_e32 v28, v28, v40
	v_max_i32_e32 v40, v32, v43
	v_min_i32_e32 v32, v32, v43
	v_max_i32_e32 v43, v35, v34
	v_min_i32_e32 v34, v35, v34
	v_max_i32_e32 v35, v38, v39
	v_min_i32_e32 v38, v38, v39
	v_max_i32_e32 v39, v41, v31
	v_min_i32_e32 v31, v41, v31
	v_max_i32_e32 v41, v42, v33
	v_min_i32_e32 v33, v42, v33
	v_max_i32_e32 v42, v30, v27
	v_min_i32_e32 v27, v30, v27
	v_max_i32_e32 v30, v36, v29
	v_min_i32_e32 v29, v36, v29
	v_max_i32_e32 v36, v37, v39
	v_min_i32_e32 v37, v37, v39
	v_max_i32_e32 v39, v40, v41
	v_min_i32_e32 v40, v40, v41
	v_max_i32_e32 v41, v43, v42
	v_min_i32_e32 v42, v43, v42
	v_max_i32_e32 v43, v35, v30
	v_min_i32_e32 v30, v35, v30
	v_max_i32_e32 v35, v28, v31
	v_min_i32_e32 v28, v28, v31
	v_max_i32_e32 v31, v32, v33
	v_min_i32_e32 v32, v32, v33
	v_max_i32_e32 v33, v34, v27
	v_min_i32_e32 v27, v34, v27
	v_max_i32_e32 v34, v38, v29
	v_min_i32_e32 v29, v38, v29
	v_max_i32_e32 v38, v36, v41
	v_min_i32_e32 v36, v36, v41
	v_max_i32_e32 v41, v39, v43
	v_min_i32_e32 v39, v39, v43
	v_max_i32_e32 v43, v37, v42
	v_min_i32_e32 v37, v37, v42
	v_max_i32_e32 v42, v40, v30
	v_min_i32_e32 v30, v40, v30
	v_max_i32_e32 v40, v35, v33
	v_min_i32_e32 v33, v35, v33
	v_max_i32_e32 v35, v31, v34
	v_min_i32_e32 v31, v31, v34
	v_max_i32_e32 v34, v28, v27
	v_min_i32_e32 v27, v28, v27
	v_max_i32_e32 v28, v32, v29
	v_min_i32_e32 v29, v32, v29
	v_max_i32_e32 v32, v38, v41
	v_min_i32_e32 v38, v38, v41
	v_max_i32_e32 v41, v36, v39
	v_min_i32_e32 v36, v36, v39
	v_max_i32_e32 v39, v43, v42
	v_min_i32_e32 v42, v43, v42
	v_max_i32_e32 v43, v37, v30
	v_min_i32_e32 v30, v37, v30
	v_max_i32_e32 v37, v40, v35
	v_min_i32_e32 v35, v40, v35
	v_max_i32_e32 v40, v33, v31
	v_min_i32_e32 v31, v33, v31
	v_max_i32_e32 v33, v34, v28
	v_min_i32_e32 v28, v34, v28
	v_max_i32_e32 v34, v27, v29
	v_min_i32_e32 v27, v27, v29
	v_add_f32_e32 v29, v67, v26
	v_or_b32_e32 v29, 0xff, v29
	v_add_f32_e32 v26, v66, v26
	v_add_u32_e32 v29, 0xffffff20, v29
	v_or_b32_e32 v26, 0xff, v26
	v_add_u32_e32 v26, 0xffffff10, v26
	v_max_i32_e32 v44, v34, v29
	v_min_i32_e32 v29, v34, v29
	v_max3_i32 v26, v29, v27, v26
; __device__ __forceinline__ void route_task(int task, int tl0, const bf16* QP  , const LAS bf16* KHL, LAS unsigned short* EL, LAS float* GL, int lane) {
;     ...
;     int my[8];
; #pragma unroll
;     for (int i = 0; i < 8; ++i) { int lo_ = bk[i], hi_ = bk[8 + i]; asm volatile("" : "+v"(lo_), "+v"(hi_)); my[i] = hi ? hi_ : lo_; }
;     int bv[8];
; #pragma unroll
;     for (int i = 0; i < 8; ++i) {
;         const unsigned cd = 255u - ((unsigned)my[i] & 255u), ca = cd >> 4, cb = cd & 15u;
;         const unsigned wa = (ca >> 2) == 0u ? P1[0] : (ca >> 2) == 1u ? P1[1] : (ca >> 2) == 2u ? P1[2] : P1[3];
;         const unsigned wb = (cb >> 2) == 0u ? P2[0] : (cb >> 2) == 1u ? P2[1] : (cb >> 2) == 2u ? P2[2] : P2[3];
;         bv[i] = (int)((((wa >> (8u * (ca & 3u))) & 255u) << 7) | ((wb >> (8u * (cb & 3u))) & 255u));
;     }
	v_mov_b32_e32 v27, v32
	s_nop 0
	v_cndmask_b32_e64 v27, v37, v27, s[6:7]
	v_not_b32_e32 v29, v27
	v_bfe_u32 v45, v29, 6, 2
	v_cmp_eq_u32_e32 vcc, 2, v45
	v_cndmask_b32_e64 v30, v26, v30, s[6:7]
	v_bitop3_b32 v26, v27, s3, v27 bitop3:0xc
	v_cndmask_b32_e32 v46, v25, v23, vcc
	v_cmp_eq_u32_e32 vcc, 1, v45
	v_cndmask_b32_e64 v34, v35, v38, s[6:7]
	v_not_b32_e32 v35, v34
	v_cndmask_b32_e32 v45, v46, v21, vcc
	v_cmp_gt_u32_e32 vcc, 64, v26
	v_cndmask_b32_e64 v37, v40, v41, s[6:7]
	v_cndmask_b32_e64 v41, v44, v43, s[6:7]
	v_cndmask_b32_e32 v26, v45, v19, vcc
	v_bfe_u32 v45, v29, 2, 2
	v_cmp_eq_u32_e32 vcc, 2, v45
	v_bitop3_b32 v44, v27, 15, v27 bitop3:0xc
	v_bfe_u32 v47, v35, 6, 2
	v_cndmask_b32_e32 v46, v24, v22, vcc
	v_cmp_eq_u32_e32 vcc, 1, v45
	v_not_b32_e32 v38, v37
	v_bfe_u32 v49, v38, 6, 2
	v_cndmask_b32_e32 v45, v46, v20, vcc
	v_cmp_gt_u32_e32 vcc, 4, v44
	v_bitop3_b32 v46, v34, 15, v34 bitop3:0xc
	v_cndmask_b32_e64 v31, v31, v36, s[6:7]
	v_cndmask_b32_e32 v44, v45, v18, vcc
	v_cmp_eq_u32_e32 vcc, 2, v47
	v_bitop3_b32 v45, v34, s3, v34 bitop3:0xc
	v_not_b32_e32 v36, v31
	v_cndmask_b32_e32 v48, v25, v23, vcc
	v_cmp_eq_u32_e32 vcc, 1, v47
	v_bfe_u32 v51, v36, 6, 2
	v_cndmask_b32_e64 v33, v33, v39, s[6:7]
	v_cndmask_b32_e32 v47, v48, v21, vcc
	v_cmp_gt_u32_e32 vcc, 64, v45
	v_not_b32_e32 v39, v33
	v_bfe_u32 v53, v39, 6, 2
	v_cndmask_b32_e32 v45, v47, v19, vcc
	v_bfe_u32 v47, v35, 2, 2
	v_cmp_eq_u32_e32 vcc, 2, v47
	v_cndmask_b32_e64 v28, v28, v42, s[6:7]
	v_not_b32_e32 v40, v28
	v_cndmask_b32_e32 v48, v24, v22, vcc
	v_cmp_eq_u32_e32 vcc, 1, v47
	v_bfe_u32 v55, v40, 6, 2
	v_not_b32_e32 v42, v41
	v_cndmask_b32_e32 v47, v48, v20, vcc
	v_cmp_gt_u32_e32 vcc, 4, v46
	v_bitop3_b32 v48, v37, 15, v37 bitop3:0xc
	v_bfe_u32 v57, v42, 6, 2
	v_cndmask_b32_e32 v46, v47, v18, vcc
	v_cmp_eq_u32_e32 vcc, 2, v49
	v_bitop3_b32 v47, v37, s3, v37 bitop3:0xc
	v_not_b32_e32 v43, v30
	v_cndmask_b32_e32 v50, v25, v23, vcc
	v_cmp_eq_u32_e32 vcc, 1, v49
	v_bfe_u32 v59, v43, 6, 2
	s_nop 0
	v_cndmask_b32_e32 v49, v50, v21, vcc
	v_cmp_gt_u32_e32 vcc, 64, v47
	s_nop 1
	v_cndmask_b32_e32 v47, v49, v19, vcc
	v_bfe_u32 v49, v38, 2, 2
	v_cmp_eq_u32_e32 vcc, 2, v49
	s_nop 1
	v_cndmask_b32_e32 v50, v24, v22, vcc
	v_cmp_eq_u32_e32 vcc, 1, v49
	s_nop 1
	v_cndmask_b32_e32 v49, v50, v20, vcc
	v_cmp_gt_u32_e32 vcc, 4, v48
	v_bitop3_b32 v50, v31, 15, v31 bitop3:0xc
	s_nop 0
	v_cndmask_b32_e32 v48, v49, v18, vcc
	v_cmp_eq_u32_e32 vcc, 2, v51
	v_bitop3_b32 v49, v31, s3, v31 bitop3:0xc
	s_nop 0
	v_cndmask_b32_e32 v52, v25, v23, vcc
	v_cmp_eq_u32_e32 vcc, 1, v51
	s_nop 1
	v_cndmask_b32_e32 v51, v52, v21, vcc
	v_cmp_gt_u32_e32 vcc, 64, v49
	s_nop 1
	v_cndmask_b32_e32 v49, v51, v19, vcc
	v_bfe_u32 v51, v36, 2, 2
	v_cmp_eq_u32_e32 vcc, 2, v51
	s_nop 1
	v_cndmask_b32_e32 v52, v24, v22, vcc
	v_cmp_eq_u32_e32 vcc, 1, v51
	s_nop 1
	v_cndmask_b32_e32 v51, v52, v20, vcc
	v_cmp_gt_u32_e32 vcc, 4, v50
	v_bitop3_b32 v52, v33, 15, v33 bitop3:0xc
	s_nop 0
	v_cndmask_b32_e32 v50, v51, v18, vcc
	v_cmp_eq_u32_e32 vcc, 2, v53
	v_bitop3_b32 v51, v33, s3, v33 bitop3:0xc
	s_nop 0
	v_cndmask_b32_e32 v54, v25, v23, vcc
	v_cmp_eq_u32_e32 vcc, 1, v53
	s_nop 1
	v_cndmask_b32_e32 v53, v54, v21, vcc
	v_cmp_gt_u32_e32 vcc, 64, v51
	s_nop 1
	v_cndmask_b32_e32 v51, v53, v19, vcc
	v_bfe_u32 v53, v39, 2, 2
	v_cmp_eq_u32_e32 vcc, 2, v53
	s_nop 1
	v_cndmask_b32_e32 v54, v24, v22, vcc
	v_cmp_eq_u32_e32 vcc, 1, v53
	s_nop 1
	v_cndmask_b32_e32 v53, v54, v20, vcc
	v_cmp_gt_u32_e32 vcc, 4, v52
	v_bitop3_b32 v54, v28, 15, v28 bitop3:0xc
	s_nop 0
	v_cndmask_b32_e32 v52, v53, v18, vcc
	v_cmp_eq_u32_e32 vcc, 2, v55
	v_bitop3_b32 v53, v28, s3, v28 bitop3:0xc
	s_nop 0
	v_cndmask_b32_e32 v56, v25, v23, vcc
	v_cmp_eq_u32_e32 vcc, 1, v55
	s_nop 1
	v_cndmask_b32_e32 v55, v56, v21, vcc
	v_cmp_gt_u32_e32 vcc, 64, v53
	s_nop 1
	v_cndmask_b32_e32 v53, v55, v19, vcc
	v_bfe_u32 v55, v40, 2, 2
	v_cmp_eq_u32_e32 vcc, 2, v55
	s_nop 1
	v_cndmask_b32_e32 v56, v24, v22, vcc
	v_cmp_eq_u32_e32 vcc, 1, v55
	s_nop 1
	v_cndmask_b32_e32 v55, v56, v20, vcc
	v_cmp_gt_u32_e32 vcc, 4, v54
	v_bitop3_b32 v56, v41, 15, v41 bitop3:0xc
	s_nop 0
	v_cndmask_b32_e32 v54, v55, v18, vcc
	v_cmp_eq_u32_e32 vcc, 2, v57
	v_bitop3_b32 v55, v41, s3, v41 bitop3:0xc
	s_nop 0
	v_cndmask_b32_e32 v58, v25, v23, vcc
	v_cmp_eq_u32_e32 vcc, 1, v57
	s_nop 1
	v_cndmask_b32_e32 v57, v58, v21, vcc
	v_cmp_gt_u32_e32 vcc, 64, v55
	s_nop 1
	v_cndmask_b32_e32 v55, v57, v19, vcc
	v_bfe_u32 v57, v42, 2, 2
	v_cmp_eq_u32_e32 vcc, 2, v57
	s_nop 1
	v_cndmask_b32_e32 v58, v24, v22, vcc
	v_cmp_eq_u32_e32 vcc, 1, v57
	s_nop 1
	v_cndmask_b32_e32 v57, v58, v20, vcc
	v_cmp_gt_u32_e32 vcc, 4, v56
	v_bitop3_b32 v58, v30, 15, v30 bitop3:0xc
	s_nop 0
	v_cndmask_b32_e32 v56, v57, v18, vcc
	v_cmp_eq_u32_e32 vcc, 2, v59
	v_bitop3_b32 v57, v30, s3, v30 bitop3:0xc
	s_nop 0
	v_cndmask_b32_e32 v23, v25, v23, vcc
	v_cmp_eq_u32_e32 vcc, 1, v59
	v_sub_f32_e32 v25, v31, v32
	v_mul_f32_e32 v25, 0x3fb8aa3b, v25
	v_cndmask_b32_e32 v21, v23, v21, vcc
	v_cmp_gt_u32_e32 vcc, 64, v57
	v_lshrrev_b32_e32 v23, 1, v39
	v_and_b32_e32 v23, 24, v23
	v_cndmask_b32_e32 v19, v21, v19, vcc
	v_bfe_u32 v21, v43, 2, 2
	v_cmp_eq_u32_e32 vcc, 2, v21
	v_lshrrev_b32_e32 v23, v23, v51
	v_lshlrev_b32_e32 v23, 7, v23
	v_cndmask_b32_e32 v22, v24, v22, vcc
	v_cmp_eq_u32_e32 vcc, 1, v21
	v_lshrrev_b32_e32 v21, 1, v42
	v_and_b32_e32 v21, 24, v21
	v_cndmask_b32_e32 v20, v22, v20, vcc
	v_cmp_gt_u32_e32 vcc, 4, v58
	v_lshrrev_b32_e32 v21, v21, v55
	v_lshrrev_b32_e32 v22, 1, v40
	v_cndmask_b32_e32 v18, v20, v18, vcc
	v_lshlrev_b32_e32 v20, 3, v42
	v_lshlrev_b32_e32 v21, 7, v21
	v_and_b32_e32 v22, 24, v22
	v_lshrrev_b32_e32 v20, v20, v56
; #define LAS __attribute__((address_space(3)))
; __device__ __forceinline__ void peer_u_item(int p, int j, const LAS unsigned short* EL  , const unsigned char* __restrict__ XQ, const unsigned char* __restrict__ U8, LAS int* ACC  , int lane, int wave) {
;     asm volatile("" : "+v"(lane));
;     const int gidx = lane >> 3; const unsigned coff = (unsigned)(p * 128 + (lane & 7) * 16), toff = (unsigned)(p * (16384 * 128) + (lane & 7) * 16);
; #pragma unroll 1
;     for (int it = 0; it < 8; ++it) {
;         const int t = j * 64 + it * 8 + wave;
;         unsigned E[8];
;         { const LAS v4u* ep = (const LAS v4u*)(EL + (it * 8 + wave) * 128 + 16 * gidx); const v4u e0 = ep[0], e1 = ep[1];
;           E[0] = e0.x; E[1] = e0.y; E[2] = e0.z; E[3] = e0.w; E[4] = e1.x; E[5] = e1.y; E[6] = e1.z; E[7] = e1.w; }
;         uint4 uu[16];
; #pragma unroll
;         for (int i = 0; i < 16; ++i) uu[i] = *(const uint4*)(U8 + (size_t)(PE_ID(E, i) * 128u + toff));
; __device__ __forceinline__ void route_task(int task, int tl0, const bf16* QP  , const LAS bf16* KHL, LAS unsigned short* EL, LAS float* GL, int lane) {
;     ...
;         const unsigned cd = 255u - ((unsigned)my[i] & 255u), ca = cd >> 4, cb = cd & 15u;
;         const unsigned wa = (ca >> 2) == 0u ? P1[0] : (ca >> 2) == 1u ? P1[1] : (ca >> 2) == 2u ? P1[2] : P1[3];
;         const unsigned wb = (cb >> 2) == 0u ? P2[0] : (cb >> 2) == 1u ? P2[1] : (cb >> 2) == 2u ? P2[2] : P2[3];
;         bv[i] = (int)((((wa >> (8u * (ca & 3u))) & 255u) << 7) | ((wb >> (8u * (cb & 3u))) & 255u));
;     }
;     float e[8], se = 0.f;
; #pragma unroll
;     for (int i = 0; i < 8; ++i) { e[i] = __expf(__int_as_float(my[i]) - __int_as_float(bk[0])); se += e[i]; }
;     se += __shfl_xor(se, 32);
;     const float inv = 1.f / se;
;     {
;         int l2 = lane; asm volatile("" : "+v"(l2));
;         const int o2 = (tl0 + ((l2 & 31) >> 3)) * 128 + (l2 & 7) * 16 + 8 * (l2 >> 5);
;         LAS v4u* ip = (LAS v4u*)(EL + o2); typedef float f4v __attribute__((ext_vector_type(4))); LAS f4v* gp = (LAS f4v*)(GL + o2);
;         ip[0] = (v4u){(unsigned)bv[0] | ((unsigned)bv[1] << 16), (unsigned)bv[2] | ((unsigned)bv[3] << 16), (unsigned)bv[4] | ((unsigned)bv[5] << 16), (unsigned)bv[6] | ((unsigned)bv[7] << 16)};
;         gp[0] = (f4v){e[0] * inv, e[1] * inv, e[2] * inv, e[3] * inv}; gp[1] = (f4v){e[4] * inv, e[5] * inv, e[6] * inv, e[7] * inv};
;     }
	v_and_b32_e32 v21, 0x7f80, v21
	v_lshrrev_b32_e32 v22, v22, v53
	v_and_or_b32 v21, v20, s3, v21
	v_lshlrev_b32_e32 v20, 3, v40
	v_lshlrev_b32_e32 v22, 7, v22
	v_lshrrev_b32_e32 v20, v20, v54
	v_and_b32_e32 v22, 0x7f80, v22
	v_and_or_b32 v20, v20, s3, v22
	v_lshlrev_b32_e32 v22, 3, v39
	v_lshrrev_b32_e32 v22, v22, v52
	v_and_b32_e32 v23, 0x7f80, v23
	v_and_or_b32 v39, v22, s3, v23
	v_lshrrev_b32_e32 v23, 1, v36
	v_and_b32_e32 v23, 24, v23
	v_lshrrev_b32_e32 v23, v23, v49
	v_lshlrev_b32_e32 v22, 3, v36
	v_lshlrev_b32_e32 v23, 7, v23
	v_lshrrev_b32_e32 v22, v22, v50
	v_and_b32_e32 v23, 0x7f80, v23
	v_and_or_b32 v36, v22, s3, v23
	v_lshrrev_b32_e32 v23, 1, v38
	v_and_b32_e32 v23, 24, v23
	v_lshrrev_b32_e32 v23, v23, v47
	v_lshlrev_b32_e32 v22, 3, v38
	v_lshlrev_b32_e32 v23, 7, v23
	v_lshrrev_b32_e32 v22, v22, v48
	v_and_b32_e32 v23, 0x7f80, v23
	v_and_or_b32 v38, v22, s3, v23
	v_lshrrev_b32_e32 v23, 1, v35
	v_and_b32_e32 v23, 24, v23
	v_lshrrev_b32_e32 v23, v23, v45
	v_lshlrev_b32_e32 v22, 3, v35
	v_lshlrev_b32_e32 v23, 7, v23
	v_lshrrev_b32_e32 v22, v22, v46
	v_and_b32_e32 v23, 0x7f80, v23
	v_and_or_b32 v35, v22, s3, v23
	v_lshrrev_b32_e32 v23, 1, v29
	v_and_b32_e32 v23, 24, v23
	v_lshrrev_b32_e32 v23, v23, v26
	v_lshlrev_b32_e32 v22, 3, v29
	v_lshlrev_b32_e32 v23, 7, v23
	v_lshrrev_b32_e32 v22, v22, v44
	v_and_b32_e32 v23, 0x7f80, v23
	v_and_or_b32 v40, v22, s3, v23
	v_sub_f32_e32 v22, v27, v32
	v_mul_f32_e32 v22, 0x3fb8aa3b, v22
	v_sub_f32_e32 v23, v34, v32
	v_exp_f32_e32 v22, v22
	v_mul_f32_e32 v23, 0x3fb8aa3b, v23
	v_sub_f32_e32 v24, v37, v32
	v_exp_f32_e32 v23, v23
	v_mul_f32_e32 v24, 0x3fb8aa3b, v24
	v_exp_f32_e32 v24, v24
	v_exp_f32_e32 v25, v25
	v_add_f32_e32 v26, 0, v22
	v_add_f32_e32 v26, v23, v26
	v_add_f32_e32 v26, v24, v26
	v_add_f32_e32 v31, v25, v26
	v_sub_f32_e32 v26, v33, v32
	v_mul_f32_e32 v26, 0x3fb8aa3b, v26
	v_sub_f32_e32 v27, v28, v32
	v_exp_f32_e32 v26, v26
	v_mul_f32_e32 v27, 0x3fb8aa3b, v27
	v_sub_f32_e32 v28, v41, v32
	v_exp_f32_e32 v27, v27
	v_mul_f32_e32 v28, 0x3fb8aa3b, v28
	v_sub_f32_e32 v29, v30, v32
	v_exp_f32_e32 v28, v28
	v_mul_f32_e32 v29, 0x3fb8aa3b, v29
	v_exp_f32_e32 v29, v29
	v_add_f32_e32 v30, v26, v31
	v_add_f32_e32 v30, v27, v30
	v_add_f32_e32 v30, v28, v30
	v_add_f32_e32 v30, v29, v30
	ds_bpermute_b32 v31, v123, v30
	v_lshrrev_b32_e32 v42, 1, v43
	v_and_b32_e32 v32, 24, v42
	v_lshrrev_b32_e32 v19, v32, v19
	v_lshlrev_b32_e32 v19, 7, v19
	s_waitcnt lgkmcnt(0)
	v_add_f32_e32 v30, v30, v31
	v_div_scale_f32 v31, s[12:13], v30, v30, 1.0
	v_rcp_f32_e32 v32, v31
	v_lshlrev_b32_e32 v33, 3, v43
	v_and_b32_e32 v19, 0x7f80, v19
	v_lshrrev_b32_e32 v18, v33, v18
	v_and_or_b32 v33, v18, s3, v19
	v_fma_f32 v18, -v31, v32, 1.0
	v_fmac_f32_e32 v32, v18, v32
	v_div_scale_f32 v18, vcc, 1.0, v30, 1.0
	v_mul_f32_e32 v19, v18, v32
	v_fma_f32 v34, -v31, v19, v18
	v_fmac_f32_e32 v19, v34, v32
	v_fma_f32 v18, -v31, v19, v18
	v_div_fmas_f32 v18, v18, v32, v19
	v_div_fixup_f32 v30, v18, v30, 1.0
	v_mov_b32_e32 v18, v1
	v_lshl_or_b32 v20, v20, 16, v39
	v_lshrrev_b32_e32 v19, 3, v18
	v_and_or_b32 v19, v19, 3, s57
	v_lshlrev_b32_e32 v31, 4, v18
	v_ashrrev_i32_e32 v18, 2, v18
	v_lshlrev_b32_e32 v19, 7, v19
	v_and_b32_e32 v31, 0x70, v31
	v_and_b32_e32 v18, -8, v18
	v_add3_u32 v18, v18, v31, v19
	v_lshl_add_u32 v31, v18, 1, s11
	v_lshl_add_u32 v32, v18, 2, s69
	v_lshl_or_b32 v18, v35, 16, v40
	v_lshl_or_b32 v19, v36, 16, v38
	v_lshl_or_b32 v21, v33, 16, v21
	ds_write_b128 v31, v[18:21]
	v_pk_mul_f32 v[20:21], v[24:25], v[30:31] op_sel_hi:[1,0]
	v_pk_mul_f32 v[18:19], v[22:23], v[30:31] op_sel_hi:[1,0]
	ds_write_b128 v32, v[18:21]
	v_pk_mul_f32 v[20:21], v[28:29], v[30:31] op_sel_hi:[1,0]
	v_pk_mul_f32 v[18:19], v[26:27], v[30:31] op_sel_hi:[1,0]
	ds_write_b128 v32, v[18:21] offset:16
	v_xor_b32_e32 v18, 4, v112
	v_cmp_lt_i32_e32 vcc, v18, v122
	s_waitcnt lgkmcnt(0)
	s_barrier
	v_cndmask_b32_e32 v18, v112, v18, vcc
	v_lshlrev_b32_e32 v30, 2, v18
	v_xor_b32_e32 v18, 2, v112
	v_cmp_lt_i32_e32 vcc, v18, v122
	s_nop 1
	v_cndmask_b32_e32 v18, v112, v18, vcc
	v_lshlrev_b32_e32 v31, 2, v18
	v_xor_b32_e32 v18, 1, v112
	v_cmp_lt_i32_e32 vcc, v18, v122
	s_nop 1
	v_cndmask_b32_e32 v18, v112, v18, vcc
	v_lshlrev_b32_e32 v32, 2, v18
	v_lshlrev_b32_e32 v56, 4, v1
	v_and_b32_e32 v56, 0x70, v56
	v_lshrrev_b32_e32 v59, 3, v1
	v_lshlrev_b32_e32 v59, 5, v59
	v_add_u32_e32 v59, s66, v59
	v_add_u32_e32 v59, -16, v59
	v_lshl_add_u32 v60, v1, 3, s64
	v_and_b32_e32 v38, 4, v1
	v_cmp_ne_u32_e64 s[10:11], 0, v38
	v_and_b32_e32 v38, 2, v1
	v_cmp_ne_u32_e64 s[12:13], 0, v38
	v_and_b32_e32 v38, 1, v1
	v_cmp_ne_u32_e64 s[14:15], 0, v38
	s_movk_i32 s94, 0x80
	s_mov_b32 s42, 0
	s_mov_b32 s43, 0
	s_mov_b32 s44, 1
	s_mov_b32 s45, 0
	s_lshl_b32 s32, s42, 11
	v_add_u32_e32 v39, s32, v59
	ds_read_b128 v[202:205], v39
	ds_read_b128 v[206:209], v39 offset:16
	s_lshl_b32 s46, s42, 3
	s_add_i32 s46, s46, s40
	s_lshl_b32 s46, s46, 9
	s_lshl_b32 s32, s43, 7
	s_add_i32 s46, s46, s32
	v_add_u32_e32 v57, s46, v56
	global_load_dwordx4 v[186:189], v57, s[34:35]
	global_load_dwordx4 v[190:193], v57, s[36:37]
	v_mov_b32_e32 v58, v56
	s_waitcnt lgkmcnt(0)
	v_and_b32_e32 v38, 0xffff, v202
	v_lshl_add_u32 v38, v38, 7, v58
	global_load_dwordx4 v[122:125], v38, s[96:97]
	v_lshrrev_b32_e32 v38, 16, v202
	v_lshl_add_u32 v38, v38, 7, v58
	global_load_dwordx4 v[126:129], v38, s[96:97]
	v_and_b32_e32 v38, 0xffff, v203
	v_lshl_add_u32 v38, v38, 7, v58
	global_load_dwordx4 v[130:133], v38, s[96:97]
	v_lshrrev_b32_e32 v38, 16, v203
	v_lshl_add_u32 v38, v38, 7, v58
	global_load_dwordx4 v[134:137], v38, s[96:97]
	v_and_b32_e32 v38, 0xffff, v204
	v_lshl_add_u32 v38, v38, 7, v58
	global_load_dwordx4 v[138:141], v38, s[96:97]
	v_lshrrev_b32_e32 v38, 16, v204
	v_lshl_add_u32 v38, v38, 7, v58
	global_load_dwordx4 v[142:145], v38, s[96:97]
	v_and_b32_e32 v38, 0xffff, v205
	v_lshl_add_u32 v38, v38, 7, v58
	global_load_dwordx4 v[146:149], v38, s[96:97]
	v_lshrrev_b32_e32 v38, 16, v205
	v_lshl_add_u32 v38, v38, 7, v58
	global_load_dwordx4 v[150:153], v38, s[96:97]
	v_and_b32_e32 v38, 0xffff, v206
	v_lshl_add_u32 v38, v38, 7, v58
	global_load_dwordx4 v[154:157], v38, s[96:97]
	v_lshrrev_b32_e32 v38, 16, v206
	v_lshl_add_u32 v38, v38, 7, v58
	global_load_dwordx4 v[158:161], v38, s[96:97]
	v_and_b32_e32 v38, 0xffff, v207
	v_lshl_add_u32 v38, v38, 7, v58
	global_load_dwordx4 v[162:165], v38, s[96:97]
	v_lshrrev_b32_e32 v38, 16, v207
	v_lshl_add_u32 v38, v38, 7, v58
	global_load_dwordx4 v[166:169], v38, s[96:97]
	v_and_b32_e32 v38, 0xffff, v208
	v_lshl_add_u32 v38, v38, 7, v58
	global_load_dwordx4 v[170:173], v38, s[96:97]
	v_lshrrev_b32_e32 v38, 16, v208
	v_lshl_add_u32 v38, v38, 7, v58
	global_load_dwordx4 v[174:177], v38, s[96:97]
	v_and_b32_e32 v38, 0xffff, v209
	v_lshl_add_u32 v38, v38, 7, v58
	global_load_dwordx4 v[178:181], v38, s[96:97]
	v_lshrrev_b32_e32 v38, 16, v209
	v_lshl_add_u32 v38, v38, 7, v58
	global_load_dwordx4 v[182:185], v38, s[96:97]
	s_mov_b32 s47, 16
